# hand-written conv prologue (all row loads in flight), hand-written lru_dir0 loop, exact logf peephole in GLA, gain vectors preloaded in GLA(c) epilogue
# speedup vs baseline: 1.0228x; 1.0228x over previous
; __device__ __forceinline__ float bf2f(bf16_t b) { return __uint_as_float(((unsigned)b) << 16); }
; __device__ __forceinline__ unsigned cvtpk(float lo, float hi) { const f32x2 v = (f32x2){lo, hi}; const bf16v2 b = __builtin_convertvector(v, bf16v2); return __builtin_bit_cast(unsigned, b); }
; __device__ __forceinline__ float siluf_(float x) { return x * sigmoidf_(x); }
; template <int MODE> __device__ void mixer_gla(const Params& p, int l, int n, LAS unsigned char* lds) {
;     ...
;         const float* gn = p.in[14] + (size_t)l * 128;
; #pragma unroll
;         for (int ti = 0; ti < 4; ++ti) { const int t = 16 * ti + c; const float rs = rsqrtf((SSQ[(h * 64 + t) * 2] + SSQ[(h * 64 + t) * 2 + 1]) * (1.0f / 128.0f) + EPS);
; #pragma unroll
;             for (int vf = 0; vf < 4; ++vf) { const int v = 64 * vh + 16 * vf + 4 * q; const f32x4 g4 = *(const f32x4*)(gn + v);
;                 float o[4];
; #pragma unroll
;                 for (int r = 0; r < 4; ++r) o[r] = acc[vf][ti][r] * rs * g4[r] * siluf_(bf2f((bf16_t)ggp[ti][vf][r]));
;                 *(u32x2*)(y + (size_t)(t0 + t) * D + 512 + 128 * h + v) = (u32x2){cvtpk(o[0], o[1]), cvtpk(o[2], o[3])}; } }
.LBB0_149:
	s_or_b64 exec, exec, s[0:1]
	v_or_b32_e32 v110, v250, v238
	v_readlane_b32 s6, v255, 24
	v_lshlrev_b32_e32 v96, 2, v110
	v_readlane_b32 s7, v255, 25
	s_waitcnt lgkmcnt(0)
	s_barrier
	v_readlane_b32 s0, v254, 24
	s_waitcnt vmcnt(15)
	v_lshlrev_b32_e32 v106, 16, v78
	global_load_dwordx4 v[120:123], v96, s[6:7]
	global_load_dwordx4 v[124:127], v96, s[6:7] offset:64
	global_load_dwordx4 v[128:131], v96, s[6:7] offset:128
	global_load_dwordx4 v[132:135], v96, s[6:7] offset:192
	v_lshl_add_u32 v97, v186, 2, s0
	v_and_b32_e32 v109, 0xffff0000, v79
	v_lshlrev_b32_e32 v108, 16, v79
	v_lshlrev_b64 v[104:105], 11, v[184:185]
	v_add_u32_e32 v111, v97, v98
	v_mul_f32_e32 v112, 0xbfb8aa3b, v106
	v_mul_f32_e32 v114, 0xbfb8aa3b, v108
	v_mul_f32_e32 v115, 0xbfb8aa3b, v109
	v_lshlrev_b32_e32 v176, 1, v110
	v_lshl_add_u32 v110, v236, 3, v97
	v_lshl_add_u64 v[98:99], s[60:61], 0, v[104:105]
	ds_read_b64 v[104:105], v111
	v_exp_f32_e32 v116, v112
	v_exp_f32_e32 v114, v114
	v_exp_f32_e32 v115, v115
	ds_read_b64 v[110:111], v110
	v_add_f32_e32 v116, 1.0, v116
	v_add_f32_e32 v117, 1.0, v114
	v_add_f32_e32 v118, 1.0, v115
	v_rcp_f32_e32 v114, v116
	v_rcp_f32_e32 v116, v117
	v_rcp_f32_e32 v117, v118
	s_waitcnt lgkmcnt(0)
	v_mov_b32_e32 v118, v110
	v_mov_b32_e32 v119, v104
	v_mov_b32_e32 v104, v111
	v_and_b32_e32 v107, 0xffff0000, v78
	v_mov_b64_e32 v[78:79], s[90:91]
	v_pk_add_f32 v[104:105], v[118:119], v[104:105]
	s_brev_b32 s2, 60
	v_mul_f32_e32 v113, 0xbfb8aa3b, v107
	v_pk_fma_f32 v[104:105], v[104:105], s[2:3], v[78:79] op_sel_hi:[1,0,0]
	v_exp_f32_e32 v113, v113
	v_mul_f32_e32 v110, 0x4b800000, v105
	v_cmp_gt_f32_e64 s[0:1], s25, v105
	v_lshl_add_u64 v[98:99], v[98:99], 0, v[182:183]
	v_add_f32_e32 v113, 1.0, v113
	v_cndmask_b32_e64 v105, v105, v110, s[0:1]
	v_rsq_f32_e32 v105, v105
	v_rcp_f32_e32 v115, v113
	v_lshl_add_u64 v[98:99], v[98:99], 0, v[176:177]
	v_pk_mul_f32 v[108:109], v[116:117], v[108:109]
	v_mul_f32_e32 v110, 0x45800000, v105
	v_cndmask_b32_e64 v110, v105, v110, s[0:1]
	v_pk_mul_f32 v[60:61], v[60:61], v[110:111] op_sel_hi:[1,0]
	v_pk_mul_f32 v[62:63], v[62:63], v[110:111] op_sel_hi:[1,0]
	v_pk_mul_f32 v[106:107], v[114:115], v[106:107]
	v_add_co_u32_e32 v112, vcc, s83, v98
	v_pk_mul_f32 v[56:57], v[56:57], v[110:111] op_sel_hi:[1,0]
	s_nop 0
	v_addc_co_u32_e32 v113, vcc, 0, v99, vcc
	v_pk_mul_f32 v[58:59], v[58:59], v[110:111] op_sel_hi:[1,0]
	s_mov_b64 s[4:5], 0x1858400
	v_lshl_add_u64 v[98:99], v[98:99], 0, s[4:5]
	v_pk_mul_f32 v[52:53], v[52:53], v[110:111] op_sel_hi:[1,0]
	v_pk_mul_f32 v[54:55], v[54:55], v[110:111] op_sel_hi:[1,0]
	v_pk_mul_f32 v[48:49], v[48:49], v[110:111] op_sel_hi:[1,0]
	v_pk_mul_f32 v[50:51], v[50:51], v[110:111] op_sel_hi:[1,0]
	v_cmp_gt_f32_e64 s[0:1], s25, v104
	v_readlane_b32 s8, v255, 26
	s_waitcnt vmcnt(0)
	v_pk_mul_f32 v[60:61], v[120:121], v[60:61]
	v_pk_mul_f32 v[62:63], v[122:123], v[62:63]
	v_pk_mul_f32 v[60:61], v[106:107], v[60:61]
	v_pk_mul_f32 v[62:63], v[108:109], v[62:63]
	v_cvt_pk_bf16_f32 v60, v60, v61
	v_cvt_pk_bf16_f32 v61, v62, v63
	global_store_dwordx2 v[112:113], v[60:61], off offset:1024
	v_and_b32_e32 v101, 0xffff0000, v94
	v_lshlrev_b32_e32 v100, 16, v94
	v_and_b32_e32 v103, 0xffff0000, v95
	v_lshlrev_b32_e32 v102, 16, v95
	v_mul_f32_e32 v94, 0xbfb8aa3b, v100
	v_mul_f32_e32 v95, 0xbfb8aa3b, v101
	v_mul_f32_e32 v105, 0xbfb8aa3b, v102
	v_mul_f32_e32 v106, 0xbfb8aa3b, v103
	v_exp_f32_e32 v94, v94
	v_exp_f32_e32 v95, v95
	v_exp_f32_e32 v105, v105
	v_exp_f32_e32 v106, v106
	v_add_f32_e32 v94, 1.0, v94
	v_add_f32_e32 v95, 1.0, v95
	v_add_f32_e32 v105, 1.0, v105
	v_add_f32_e32 v107, 1.0, v106
	v_rcp_f32_e32 v94, v94
	v_rcp_f32_e32 v95, v95
	v_rcp_f32_e32 v106, v105
	v_rcp_f32_e32 v107, v107
	v_pk_mul_f32 v[94:95], v[94:95], v[100:101]
	v_pk_mul_f32 v[100:101], v[106:107], v[102:103]
	v_pk_mul_f32 v[56:57], v[124:125], v[56:57]
	v_pk_mul_f32 v[58:59], v[126:127], v[58:59]
	v_pk_mul_f32 v[56:57], v[94:95], v[56:57]
	v_pk_mul_f32 v[58:59], v[100:101], v[58:59]
	v_cvt_pk_bf16_f32 v56, v56, v57
	v_cvt_pk_bf16_f32 v57, v58, v59
	global_store_dwordx2 v[98:99], v[56:57], off offset:32
	v_and_b32_e32 v61, 0xffff0000, v92
	v_lshlrev_b32_e32 v60, 16, v92
	v_and_b32_e32 v63, 0xffff0000, v93
	v_lshlrev_b32_e32 v62, 16, v93
	v_mul_f32_e32 v92, 0xbfb8aa3b, v60
	v_mul_f32_e32 v93, 0xbfb8aa3b, v61
	v_mul_f32_e32 v94, 0xbfb8aa3b, v62
	v_mul_f32_e32 v95, 0xbfb8aa3b, v63
	v_exp_f32_e32 v92, v92
	v_exp_f32_e32 v93, v93
	v_exp_f32_e32 v94, v94
	v_exp_f32_e32 v95, v95
	v_add_f32_e32 v92, 1.0, v92
	v_add_f32_e32 v93, 1.0, v93
	v_add_f32_e32 v94, 1.0, v94
	v_add_f32_e32 v95, 1.0, v95
	v_rcp_f32_e32 v92, v92
	v_rcp_f32_e32 v93, v93
	v_rcp_f32_e32 v94, v94
	v_rcp_f32_e32 v95, v95
	v_pk_mul_f32 v[60:61], v[92:93], v[60:61]
	v_pk_mul_f32 v[62:63], v[94:95], v[62:63]
	v_pk_mul_f32 v[52:53], v[128:129], v[52:53]
	v_pk_mul_f32 v[54:55], v[130:131], v[54:55]
	v_pk_mul_f32 v[52:53], v[60:61], v[52:53]
	v_pk_mul_f32 v[54:55], v[62:63], v[54:55]
	v_cvt_pk_bf16_f32 v52, v52, v53
	v_cvt_pk_bf16_f32 v53, v54, v55
	global_store_dwordx2 v[98:99], v[52:53], off offset:64
	v_and_b32_e32 v57, 0xffff0000, v90
	v_lshlrev_b32_e32 v56, 16, v90
	v_and_b32_e32 v59, 0xffff0000, v91
	v_lshlrev_b32_e32 v58, 16, v91
	v_mul_f32_e32 v60, 0xbfb8aa3b, v56
	v_mul_f32_e32 v61, 0xbfb8aa3b, v57
	v_mul_f32_e32 v62, 0xbfb8aa3b, v58
	v_mul_f32_e32 v63, 0xbfb8aa3b, v59
	v_exp_f32_e32 v60, v60
	v_exp_f32_e32 v61, v61
	v_exp_f32_e32 v62, v62
	v_exp_f32_e32 v63, v63
	v_add_f32_e32 v60, 1.0, v60
	v_add_f32_e32 v61, 1.0, v61
	v_add_f32_e32 v62, 1.0, v62
	v_add_f32_e32 v63, 1.0, v63
	v_rcp_f32_e32 v60, v60
	v_rcp_f32_e32 v61, v61
	v_rcp_f32_e32 v62, v62
; __device__ __forceinline__ float bf2f(bf16_t b) { return __uint_as_float(((unsigned)b) << 16); }
; __device__ __forceinline__ unsigned cvtpk(float lo, float hi) { const f32x2 v = (f32x2){lo, hi}; const bf16v2 b = __builtin_convertvector(v, bf16v2); return __builtin_bit_cast(unsigned, b); }
; __device__ __forceinline__ float siluf_(float x) { return x * sigmoidf_(x); }
; template <int MODE> __device__ void mixer_gla(const Params& p, int l, int n, LAS unsigned char* lds) {
;     ...
;         const float* gn = p.in[14] + (size_t)l * 128;
; #pragma unroll
;         for (int ti = 0; ti < 4; ++ti) { const int t = 16 * ti + c; const float rs = rsqrtf((SSQ[(h * 64 + t) * 2] + SSQ[(h * 64 + t) * 2 + 1]) * (1.0f / 128.0f) + EPS);
; #pragma unroll
;             for (int vf = 0; vf < 4; ++vf) { const int v = 64 * vh + 16 * vf + 4 * q; const f32x4 g4 = *(const f32x4*)(gn + v);
;                 float o[4];
; #pragma unroll
;                 for (int r = 0; r < 4; ++r) o[r] = acc[vf][ti][r] * rs * g4[r] * siluf_(bf2f((bf16_t)ggp[ti][vf][r]));
;                 *(u32x2*)(y + (size_t)(t0 + t) * D + 512 + 128 * h + v) = (u32x2){cvtpk(o[0], o[1]), cvtpk(o[2], o[3])}; } }
	v_rcp_f32_e32 v63, v63
	v_pk_mul_f32 v[56:57], v[60:61], v[56:57]
	v_pk_mul_f32 v[58:59], v[62:63], v[58:59]
	v_pk_mul_f32 v[48:49], v[132:133], v[48:49]
	v_pk_mul_f32 v[50:51], v[134:135], v[50:51]
	v_pk_mul_f32 v[48:49], v[56:57], v[48:49]
	v_pk_mul_f32 v[50:51], v[58:59], v[50:51]
	v_cvt_pk_bf16_f32 v48, v48, v49
	v_cvt_pk_bf16_f32 v49, v50, v51
	global_store_dwordx2 v[98:99], v[48:49], off offset:96
	v_and_b32_e32 v55, 0xffff0000, v88
	v_and_b32_e32 v57, 0xffff0000, v89
	v_mul_f32_e32 v59, 0xbfb8aa3b, v55
	v_lshlrev_b32_e32 v54, 16, v88
	v_lshlrev_b32_e32 v56, 16, v89
	v_mul_f32_e32 v61, 0xbfb8aa3b, v57
	v_exp_f32_e32 v59, v59
	v_mul_f32_e32 v58, 0xbfb8aa3b, v54
	v_mul_f32_e32 v60, 0xbfb8aa3b, v56
	v_exp_f32_e32 v61, v61
	v_exp_f32_e32 v58, v58
	v_exp_f32_e32 v60, v60
	v_add_f32_e32 v59, 1.0, v59
	v_add_f32_e32 v88, 1.0, v61
	v_rcp_f32_e32 v61, v59
	v_mul_f32_e32 v59, 0x4b800000, v104
	v_add_f32_e32 v62, 1.0, v58
	v_add_f32_e32 v63, 1.0, v60
	v_cndmask_b32_e64 v59, v104, v59, s[0:1]
	v_rcp_f32_e32 v60, v62
	v_rcp_f32_e32 v62, v63
	v_rcp_f32_e32 v63, v88
	v_rsq_f32_e32 v88, v59
	v_or_b32_e32 v52, s8, v236
	v_ashrrev_i32_e32 v53, 31, v52
	v_lshlrev_b64 v[52:53], 11, v[52:53]
	v_pk_mul_f32 v[54:55], v[60:61], v[54:55]
	v_mul_f32_e32 v60, 0x45800000, v88
	v_lshl_add_u64 v[52:53], s[60:61], 0, v[52:53]
	v_cndmask_b32_e64 v60, v88, v60, s[0:1]
	v_lshl_add_u64 v[52:53], v[52:53], 0, v[182:183]
	v_pk_mul_f32 v[44:45], v[44:45], v[60:61] op_sel_hi:[1,0]
	v_pk_mul_f32 v[46:47], v[46:47], v[60:61] op_sel_hi:[1,0]
	v_lshl_add_u64 v[52:53], v[52:53], 0, v[176:177]
	v_pk_mul_f32 v[56:57], v[62:63], v[56:57]
	v_add_co_u32_e32 v58, vcc, s83, v52
	v_pk_mul_f32 v[40:41], v[40:41], v[60:61] op_sel_hi:[1,0]
	s_nop 0
	v_addc_co_u32_e32 v59, vcc, 0, v53, vcc
	v_pk_mul_f32 v[42:43], v[42:43], v[60:61] op_sel_hi:[1,0]
	v_lshl_add_u64 v[52:53], v[52:53], 0, s[4:5]
	v_pk_mul_f32 v[36:37], v[36:37], v[60:61] op_sel_hi:[1,0]
	v_pk_mul_f32 v[38:39], v[38:39], v[60:61] op_sel_hi:[1,0]
	v_pk_mul_f32 v[32:33], v[32:33], v[60:61] op_sel_hi:[1,0]
	v_pk_mul_f32 v[34:35], v[34:35], v[60:61] op_sel_hi:[1,0]
	v_pk_mul_f32 v[44:45], v[120:121], v[44:45]
	v_pk_mul_f32 v[46:47], v[122:123], v[46:47]
	v_pk_mul_f32 v[44:45], v[54:55], v[44:45]
	v_pk_mul_f32 v[46:47], v[56:57], v[46:47]
	v_cvt_pk_bf16_f32 v44, v44, v45
	v_cvt_pk_bf16_f32 v45, v46, v47
	global_store_dwordx2 v[58:59], v[44:45], off offset:1024
	v_and_b32_e32 v49, 0xffff0000, v86
	v_lshlrev_b32_e32 v48, 16, v86
	v_and_b32_e32 v51, 0xffff0000, v87
	v_lshlrev_b32_e32 v50, 16, v87
	v_mul_f32_e32 v54, 0xbfb8aa3b, v48
	v_mul_f32_e32 v55, 0xbfb8aa3b, v49
	v_mul_f32_e32 v56, 0xbfb8aa3b, v50
	v_mul_f32_e32 v57, 0xbfb8aa3b, v51
	v_exp_f32_e32 v54, v54
	v_exp_f32_e32 v55, v55
	v_exp_f32_e32 v56, v56
	v_exp_f32_e32 v57, v57
	v_add_f32_e32 v54, 1.0, v54
	v_add_f32_e32 v55, 1.0, v55
	v_add_f32_e32 v56, 1.0, v56
	v_add_f32_e32 v57, 1.0, v57
	v_rcp_f32_e32 v54, v54
	v_rcp_f32_e32 v55, v55
	v_rcp_f32_e32 v56, v56
	v_rcp_f32_e32 v57, v57
	v_pk_mul_f32 v[48:49], v[54:55], v[48:49]
	v_pk_mul_f32 v[50:51], v[56:57], v[50:51]
	v_pk_mul_f32 v[40:41], v[124:125], v[40:41]
	v_pk_mul_f32 v[42:43], v[126:127], v[42:43]
	v_pk_mul_f32 v[40:41], v[48:49], v[40:41]
	v_pk_mul_f32 v[42:43], v[50:51], v[42:43]
	v_cvt_pk_bf16_f32 v40, v40, v41
	v_cvt_pk_bf16_f32 v41, v42, v43
	global_store_dwordx2 v[52:53], v[40:41], off offset:32
	v_and_b32_e32 v45, 0xffff0000, v84
	v_lshlrev_b32_e32 v44, 16, v84
	v_and_b32_e32 v47, 0xffff0000, v85
	v_lshlrev_b32_e32 v46, 16, v85
	v_mul_f32_e32 v48, 0xbfb8aa3b, v44
	v_mul_f32_e32 v49, 0xbfb8aa3b, v45
	v_mul_f32_e32 v50, 0xbfb8aa3b, v46
	v_mul_f32_e32 v51, 0xbfb8aa3b, v47
	v_exp_f32_e32 v48, v48
	v_exp_f32_e32 v49, v49
	v_exp_f32_e32 v50, v50
	v_exp_f32_e32 v51, v51
	v_add_f32_e32 v48, 1.0, v48
	v_add_f32_e32 v49, 1.0, v49
	v_add_f32_e32 v50, 1.0, v50
	v_add_f32_e32 v51, 1.0, v51
	v_rcp_f32_e32 v48, v48
	v_rcp_f32_e32 v49, v49
	v_rcp_f32_e32 v50, v50
	v_rcp_f32_e32 v51, v51
	v_pk_mul_f32 v[44:45], v[48:49], v[44:45]
	v_pk_mul_f32 v[46:47], v[50:51], v[46:47]
	v_pk_mul_f32 v[36:37], v[128:129], v[36:37]
	v_pk_mul_f32 v[38:39], v[130:131], v[38:39]
	v_pk_mul_f32 v[36:37], v[44:45], v[36:37]
	v_pk_mul_f32 v[38:39], v[46:47], v[38:39]
	v_cvt_pk_bf16_f32 v36, v36, v37
	v_cvt_pk_bf16_f32 v37, v38, v39
	global_store_dwordx2 v[52:53], v[36:37], off offset:64
	v_and_b32_e32 v41, 0xffff0000, v82
	v_lshlrev_b32_e32 v40, 16, v82
	v_and_b32_e32 v43, 0xffff0000, v83
	v_lshlrev_b32_e32 v42, 16, v83
	v_mul_f32_e32 v44, 0xbfb8aa3b, v40
	v_mul_f32_e32 v45, 0xbfb8aa3b, v41
	v_mul_f32_e32 v46, 0xbfb8aa3b, v42
	v_mul_f32_e32 v47, 0xbfb8aa3b, v43
	v_exp_f32_e32 v44, v44
	v_exp_f32_e32 v45, v45
	v_exp_f32_e32 v46, v46
	v_exp_f32_e32 v47, v47
	v_add_f32_e32 v44, 1.0, v44
	v_add_f32_e32 v45, 1.0, v45
	v_add_f32_e32 v46, 1.0, v46
	v_add_f32_e32 v47, 1.0, v47
	v_rcp_f32_e32 v44, v44
	v_rcp_f32_e32 v45, v45
	v_rcp_f32_e32 v46, v46
	v_rcp_f32_e32 v47, v47
	v_pk_mul_f32 v[40:41], v[44:45], v[40:41]
	v_lshl_add_u32 v44, v187, 3, v97
	v_pk_mul_f32 v[42:43], v[46:47], v[42:43]
	v_pk_mul_f32 v[32:33], v[132:133], v[32:33]
	v_pk_mul_f32 v[34:35], v[134:135], v[34:35]
	v_pk_mul_f32 v[32:33], v[40:41], v[32:33]
	v_pk_mul_f32 v[34:35], v[42:43], v[34:35]
	v_cvt_pk_bf16_f32 v32, v32, v33
	v_cvt_pk_bf16_f32 v33, v34, v35
	global_store_dwordx2 v[52:53], v[32:33], off offset:96
	v_lshlrev_b32_e32 v36, 16, v80
	v_and_b32_e32 v39, 0xffff0000, v81
	v_lshlrev_b32_e32 v38, 16, v81
	v_lshl_add_u32 v42, v235, 3, v97
	v_mul_f32_e32 v46, 0xbfb8aa3b, v36
	v_mul_f32_e32 v48, 0xbfb8aa3b, v38
	v_mul_f32_e32 v49, 0xbfb8aa3b, v39
	ds_read_b64 v[42:43], v42
	ds_read_b64 v[44:45], v44
	v_exp_f32_e32 v46, v46
	v_exp_f32_e32 v48, v48
	v_exp_f32_e32 v49, v49
	s_waitcnt lgkmcnt(1)
; __device__ __forceinline__ float bf2f(bf16_t b) { return __uint_as_float(((unsigned)b) << 16); }
; __device__ __forceinline__ unsigned cvtpk(float lo, float hi) { const f32x2 v = (f32x2){lo, hi}; const bf16v2 b = __builtin_convertvector(v, bf16v2); return __builtin_bit_cast(unsigned, b); }
; __device__ __forceinline__ float siluf_(float x) { return x * sigmoidf_(x); }
; template <int MODE> __device__ void mixer_gla(const Params& p, int l, int n, LAS unsigned char* lds) {
;     ...
;         const float* gn = p.in[14] + (size_t)l * 128;
; #pragma unroll
;         for (int ti = 0; ti < 4; ++ti) { const int t = 16 * ti + c; const float rs = rsqrtf((SSQ[(h * 64 + t) * 2] + SSQ[(h * 64 + t) * 2 + 1]) * (1.0f / 128.0f) + EPS);
; #pragma unroll
;             for (int vf = 0; vf < 4; ++vf) { const int v = 64 * vh + 16 * vf + 4 * q; const f32x4 g4 = *(const f32x4*)(gn + v);
;                 float o[4];
; #pragma unroll
;                 for (int r = 0; r < 4; ++r) o[r] = acc[vf][ti][r] * rs * g4[r] * siluf_(bf2f((bf16_t)ggp[ti][vf][r]));
;                 *(u32x2*)(y + (size_t)(t0 + t) * D + 512 + 128 * h + v) = (u32x2){cvtpk(o[0], o[1]), cvtpk(o[2], o[3])}; } }
	v_mov_b32_e32 v53, v42
	v_add_f32_e32 v50, 1.0, v46
	v_add_f32_e32 v51, 1.0, v48
	v_add_f32_e32 v52, 1.0, v49
	v_rcp_f32_e32 v48, v50
	v_rcp_f32_e32 v50, v51
	v_rcp_f32_e32 v51, v52
	s_waitcnt lgkmcnt(0)
	v_mov_b32_e32 v52, v44
	v_mov_b32_e32 v42, v45
	v_and_b32_e32 v37, 0xffff0000, v80
	v_pk_add_f32 v[42:43], v[52:53], v[42:43]
	v_mul_f32_e32 v47, 0xbfb8aa3b, v37
	v_pk_fma_f32 v[42:43], v[42:43], s[2:3], v[78:79] op_sel_hi:[1,0,0]
	v_exp_f32_e32 v47, v47
	v_mul_f32_e32 v44, 0x4b800000, v43
	v_cmp_gt_f32_e64 s[0:1], s25, v43
	v_or_b32_e32 v40, s8, v235
	v_add_f32_e32 v47, 1.0, v47
	v_cndmask_b32_e64 v43, v43, v44, s[0:1]
	v_rsq_f32_e32 v43, v43
	v_ashrrev_i32_e32 v41, 31, v40
	v_rcp_f32_e32 v49, v47
	v_lshlrev_b64 v[40:41], 11, v[40:41]
	v_mul_f32_e32 v44, 0x45800000, v43
	v_lshl_add_u64 v[40:41], s[60:61], 0, v[40:41]
	v_cndmask_b32_e64 v44, v43, v44, s[0:1]
	v_lshl_add_u64 v[40:41], v[40:41], 0, v[182:183]
	v_pk_mul_f32 v[28:29], v[28:29], v[44:45] op_sel_hi:[1,0]
	v_pk_mul_f32 v[30:31], v[30:31], v[44:45] op_sel_hi:[1,0]
	v_lshl_add_u64 v[40:41], v[40:41], 0, v[176:177]
	v_pk_mul_f32 v[36:37], v[48:49], v[36:37]
	v_pk_mul_f32 v[38:39], v[50:51], v[38:39]
	v_add_co_u32_e32 v46, vcc, s83, v40
	v_pk_mul_f32 v[24:25], v[24:25], v[44:45] op_sel_hi:[1,0]
	s_nop 0
	v_addc_co_u32_e32 v47, vcc, 0, v41, vcc
	v_pk_mul_f32 v[26:27], v[26:27], v[44:45] op_sel_hi:[1,0]
	v_lshl_add_u64 v[40:41], v[40:41], 0, s[4:5]
	v_pk_mul_f32 v[20:21], v[20:21], v[44:45] op_sel_hi:[1,0]
	v_pk_mul_f32 v[22:23], v[22:23], v[44:45] op_sel_hi:[1,0]
	v_pk_mul_f32 v[16:17], v[16:17], v[44:45] op_sel_hi:[1,0]
	v_pk_mul_f32 v[18:19], v[18:19], v[44:45] op_sel_hi:[1,0]
	v_cmp_gt_f32_e64 s[0:1], s25, v42
	v_pk_mul_f32 v[28:29], v[120:121], v[28:29]
	v_pk_mul_f32 v[30:31], v[122:123], v[30:31]
	v_pk_mul_f32 v[28:29], v[36:37], v[28:29]
	v_pk_mul_f32 v[30:31], v[38:39], v[30:31]
	v_cvt_pk_bf16_f32 v28, v28, v29
	v_cvt_pk_bf16_f32 v29, v30, v31
	global_store_dwordx2 v[46:47], v[28:29], off offset:1024
	v_and_b32_e32 v33, 0xffff0000, v76
	v_lshlrev_b32_e32 v32, 16, v76
	v_and_b32_e32 v35, 0xffff0000, v77
	v_lshlrev_b32_e32 v34, 16, v77
	v_mul_f32_e32 v36, 0xbfb8aa3b, v32
	v_mul_f32_e32 v37, 0xbfb8aa3b, v33
	v_mul_f32_e32 v38, 0xbfb8aa3b, v34
	v_mul_f32_e32 v39, 0xbfb8aa3b, v35
	v_exp_f32_e32 v36, v36
	v_exp_f32_e32 v37, v37
	v_exp_f32_e32 v38, v38
	v_exp_f32_e32 v39, v39
	v_add_f32_e32 v36, 1.0, v36
	v_add_f32_e32 v37, 1.0, v37
	v_add_f32_e32 v38, 1.0, v38
	v_add_f32_e32 v39, 1.0, v39
	v_rcp_f32_e32 v36, v36
	v_rcp_f32_e32 v37, v37
	v_rcp_f32_e32 v38, v38
	v_rcp_f32_e32 v39, v39
	v_pk_mul_f32 v[32:33], v[36:37], v[32:33]
	v_pk_mul_f32 v[34:35], v[38:39], v[34:35]
	v_pk_mul_f32 v[24:25], v[124:125], v[24:25]
	v_pk_mul_f32 v[26:27], v[126:127], v[26:27]
	v_pk_mul_f32 v[24:25], v[32:33], v[24:25]
	v_pk_mul_f32 v[26:27], v[34:35], v[26:27]
	v_cvt_pk_bf16_f32 v24, v24, v25
	v_cvt_pk_bf16_f32 v25, v26, v27
	global_store_dwordx2 v[40:41], v[24:25], off offset:32
	v_and_b32_e32 v29, 0xffff0000, v74
	v_lshlrev_b32_e32 v28, 16, v74
	v_and_b32_e32 v31, 0xffff0000, v75
	v_lshlrev_b32_e32 v30, 16, v75
	v_mul_f32_e32 v32, 0xbfb8aa3b, v28
	v_mul_f32_e32 v33, 0xbfb8aa3b, v29
	v_mul_f32_e32 v34, 0xbfb8aa3b, v30
	v_mul_f32_e32 v35, 0xbfb8aa3b, v31
	v_exp_f32_e32 v32, v32
	v_exp_f32_e32 v33, v33
	v_exp_f32_e32 v34, v34
	v_exp_f32_e32 v35, v35
	v_add_f32_e32 v32, 1.0, v32
	v_add_f32_e32 v33, 1.0, v33
	v_add_f32_e32 v34, 1.0, v34
	v_add_f32_e32 v35, 1.0, v35
	v_rcp_f32_e32 v32, v32
	v_rcp_f32_e32 v33, v33
	v_rcp_f32_e32 v34, v34
	v_rcp_f32_e32 v35, v35
	v_pk_mul_f32 v[28:29], v[32:33], v[28:29]
	v_pk_mul_f32 v[30:31], v[34:35], v[30:31]
	v_pk_mul_f32 v[20:21], v[128:129], v[20:21]
	v_pk_mul_f32 v[22:23], v[130:131], v[22:23]
	v_pk_mul_f32 v[20:21], v[28:29], v[20:21]
	v_pk_mul_f32 v[22:23], v[30:31], v[22:23]
	v_cvt_pk_bf16_f32 v20, v20, v21
	v_cvt_pk_bf16_f32 v21, v22, v23
	global_store_dwordx2 v[40:41], v[20:21], off offset:64
	v_and_b32_e32 v25, 0xffff0000, v72
	v_lshlrev_b32_e32 v24, 16, v72
	v_and_b32_e32 v27, 0xffff0000, v73
	v_lshlrev_b32_e32 v26, 16, v73
	v_mul_f32_e32 v28, 0xbfb8aa3b, v24
	v_mul_f32_e32 v29, 0xbfb8aa3b, v25
	v_mul_f32_e32 v30, 0xbfb8aa3b, v26
	v_mul_f32_e32 v31, 0xbfb8aa3b, v27
	v_exp_f32_e32 v28, v28
	v_exp_f32_e32 v29, v29
	v_exp_f32_e32 v30, v30
	v_exp_f32_e32 v31, v31
	v_add_f32_e32 v28, 1.0, v28
	v_add_f32_e32 v29, 1.0, v29
	v_add_f32_e32 v30, 1.0, v30
	v_add_f32_e32 v31, 1.0, v31
	v_rcp_f32_e32 v28, v28
	v_rcp_f32_e32 v29, v29
	v_rcp_f32_e32 v30, v30
	v_rcp_f32_e32 v31, v31
	v_pk_mul_f32 v[24:25], v[28:29], v[24:25]
	v_pk_mul_f32 v[26:27], v[30:31], v[26:27]
	v_pk_mul_f32 v[16:17], v[132:133], v[16:17]
	v_pk_mul_f32 v[18:19], v[134:135], v[18:19]
	v_pk_mul_f32 v[16:17], v[24:25], v[16:17]
	v_pk_mul_f32 v[18:19], v[26:27], v[18:19]
	v_cvt_pk_bf16_f32 v16, v16, v17
	v_cvt_pk_bf16_f32 v17, v18, v19
	global_store_dwordx2 v[40:41], v[16:17], off offset:96
	v_and_b32_e32 v23, 0xffff0000, v70
; __device__ __forceinline__ float bf2f(bf16_t b) { return __uint_as_float(((unsigned)b) << 16); }
; __device__ __forceinline__ unsigned cvtpk(float lo, float hi) { const f32x2 v = (f32x2){lo, hi}; const bf16v2 b = __builtin_convertvector(v, bf16v2); return __builtin_bit_cast(unsigned, b); }
; __device__ __forceinline__ float siluf_(float x) { return x * sigmoidf_(x); }
; template <int MODE> __device__ void mixer_gla(const Params& p, int l, int n, LAS unsigned char* lds) {
;     ...
;         const float* gn = p.in[14] + (size_t)l * 128;
; #pragma unroll
;         for (int ti = 0; ti < 4; ++ti) { const int t = 16 * ti + c; const float rs = rsqrtf((SSQ[(h * 64 + t) * 2] + SSQ[(h * 64 + t) * 2 + 1]) * (1.0f / 128.0f) + EPS);
; #pragma unroll
;             for (int vf = 0; vf < 4; ++vf) { const int v = 64 * vh + 16 * vf + 4 * q; const f32x4 g4 = *(const f32x4*)(gn + v);
;                 float o[4];
; #pragma unroll
;                 for (int r = 0; r < 4; ++r) o[r] = acc[vf][ti][r] * rs * g4[r] * siluf_(bf2f((bf16_t)ggp[ti][vf][r]));
;                 *(u32x2*)(y + (size_t)(t0 + t) * D + 512 + 128 * h + v) = (u32x2){cvtpk(o[0], o[1]), cvtpk(o[2], o[3])}; } }
;     ...
;     __syncthreads();
	v_and_b32_e32 v25, 0xffff0000, v71
	v_mul_f32_e32 v27, 0xbfb8aa3b, v23
	v_lshlrev_b32_e32 v22, 16, v70
	v_lshlrev_b32_e32 v24, 16, v71
	v_mul_f32_e32 v29, 0xbfb8aa3b, v25
	v_exp_f32_e32 v27, v27
	v_mul_f32_e32 v26, 0xbfb8aa3b, v22
	v_mul_f32_e32 v28, 0xbfb8aa3b, v24
	v_exp_f32_e32 v29, v29
	v_exp_f32_e32 v26, v26
	v_exp_f32_e32 v28, v28
	v_add_f32_e32 v27, 1.0, v27
	v_add_f32_e32 v32, 1.0, v29
	v_rcp_f32_e32 v29, v27
	v_mul_f32_e32 v27, 0x4b800000, v42
	v_add_f32_e32 v30, 1.0, v26
	v_add_f32_e32 v31, 1.0, v28
	v_cndmask_b32_e64 v27, v42, v27, s[0:1]
	v_rcp_f32_e32 v28, v30
	v_rcp_f32_e32 v30, v31
	v_rcp_f32_e32 v31, v32
	v_rsq_f32_e32 v32, v27
	v_or_b32_e32 v20, s8, v187
	v_ashrrev_i32_e32 v21, 31, v20
	v_lshlrev_b64 v[20:21], 11, v[20:21]
	v_pk_mul_f32 v[22:23], v[28:29], v[22:23]
	v_mul_f32_e32 v28, 0x45800000, v32
	v_lshl_add_u64 v[20:21], s[60:61], 0, v[20:21]
	v_cndmask_b32_e64 v28, v32, v28, s[0:1]
	v_lshl_add_u64 v[20:21], v[20:21], 0, v[182:183]
	v_pk_mul_f32 v[12:13], v[12:13], v[28:29] op_sel_hi:[1,0]
	v_pk_mul_f32 v[14:15], v[14:15], v[28:29] op_sel_hi:[1,0]
	v_lshl_add_u64 v[20:21], v[20:21], 0, v[176:177]
	v_pk_mul_f32 v[24:25], v[30:31], v[24:25]
	v_add_co_u32_e32 v26, vcc, s83, v20
	v_pk_mul_f32 v[8:9], v[8:9], v[28:29] op_sel_hi:[1,0]
	s_nop 0
	v_addc_co_u32_e32 v27, vcc, 0, v21, vcc
	v_pk_mul_f32 v[10:11], v[10:11], v[28:29] op_sel_hi:[1,0]
	v_lshl_add_u64 v[20:21], v[20:21], 0, s[4:5]
	v_pk_mul_f32 v[4:5], v[4:5], v[28:29] op_sel_hi:[1,0]
	v_pk_mul_f32 v[6:7], v[6:7], v[28:29] op_sel_hi:[1,0]
	v_pk_mul_f32 v[0:1], v[0:1], v[28:29] op_sel_hi:[1,0]
	v_pk_mul_f32 v[2:3], v[2:3], v[28:29] op_sel_hi:[1,0]
	v_pk_mul_f32 v[12:13], v[120:121], v[12:13]
	v_pk_mul_f32 v[14:15], v[122:123], v[14:15]
	v_pk_mul_f32 v[12:13], v[22:23], v[12:13]
	v_pk_mul_f32 v[14:15], v[24:25], v[14:15]
	v_cvt_pk_bf16_f32 v12, v12, v13
	v_cvt_pk_bf16_f32 v13, v14, v15
	global_store_dwordx2 v[26:27], v[12:13], off offset:1024
	v_and_b32_e32 v17, 0xffff0000, v68
	v_lshlrev_b32_e32 v16, 16, v68
	v_and_b32_e32 v19, 0xffff0000, v69
	v_lshlrev_b32_e32 v18, 16, v69
	v_mul_f32_e32 v22, 0xbfb8aa3b, v16
	v_mul_f32_e32 v23, 0xbfb8aa3b, v17
	v_mul_f32_e32 v24, 0xbfb8aa3b, v18
	v_mul_f32_e32 v25, 0xbfb8aa3b, v19
	v_exp_f32_e32 v22, v22
	v_exp_f32_e32 v23, v23
	v_exp_f32_e32 v24, v24
	v_exp_f32_e32 v25, v25
	v_add_f32_e32 v22, 1.0, v22
	v_add_f32_e32 v23, 1.0, v23
	v_add_f32_e32 v24, 1.0, v24
	v_add_f32_e32 v25, 1.0, v25
	v_rcp_f32_e32 v22, v22
	v_rcp_f32_e32 v23, v23
	v_rcp_f32_e32 v24, v24
	v_rcp_f32_e32 v25, v25
	v_pk_mul_f32 v[16:17], v[22:23], v[16:17]
	v_pk_mul_f32 v[18:19], v[24:25], v[18:19]
	v_pk_mul_f32 v[8:9], v[124:125], v[8:9]
	v_pk_mul_f32 v[10:11], v[126:127], v[10:11]
	v_pk_mul_f32 v[8:9], v[16:17], v[8:9]
	v_pk_mul_f32 v[10:11], v[18:19], v[10:11]
	v_cvt_pk_bf16_f32 v8, v8, v9
	v_cvt_pk_bf16_f32 v9, v10, v11
	global_store_dwordx2 v[20:21], v[8:9], off offset:32
	v_and_b32_e32 v13, 0xffff0000, v66
	v_lshlrev_b32_e32 v12, 16, v66
	v_and_b32_e32 v15, 0xffff0000, v67
	v_lshlrev_b32_e32 v14, 16, v67
	v_mul_f32_e32 v16, 0xbfb8aa3b, v12
	v_mul_f32_e32 v17, 0xbfb8aa3b, v13
	v_mul_f32_e32 v18, 0xbfb8aa3b, v14
	v_mul_f32_e32 v19, 0xbfb8aa3b, v15
	v_exp_f32_e32 v16, v16
	v_exp_f32_e32 v17, v17
	v_exp_f32_e32 v18, v18
	v_exp_f32_e32 v19, v19
	v_add_f32_e32 v16, 1.0, v16
	v_add_f32_e32 v17, 1.0, v17
	v_add_f32_e32 v18, 1.0, v18
	v_add_f32_e32 v19, 1.0, v19
	v_rcp_f32_e32 v16, v16
	v_rcp_f32_e32 v17, v17
	v_rcp_f32_e32 v18, v18
	v_rcp_f32_e32 v19, v19
	v_pk_mul_f32 v[12:13], v[16:17], v[12:13]
	v_pk_mul_f32 v[14:15], v[18:19], v[14:15]
	v_pk_mul_f32 v[4:5], v[128:129], v[4:5]
	v_pk_mul_f32 v[6:7], v[130:131], v[6:7]
	v_pk_mul_f32 v[4:5], v[12:13], v[4:5]
	v_pk_mul_f32 v[6:7], v[14:15], v[6:7]
	v_cvt_pk_bf16_f32 v4, v4, v5
	v_cvt_pk_bf16_f32 v5, v6, v7
	global_store_dwordx2 v[20:21], v[4:5], off offset:64
	v_and_b32_e32 v9, 0xffff0000, v64
	v_lshlrev_b32_e32 v8, 16, v64
	v_and_b32_e32 v11, 0xffff0000, v65
	v_lshlrev_b32_e32 v10, 16, v65
	v_mul_f32_e32 v12, 0xbfb8aa3b, v8
	v_mul_f32_e32 v13, 0xbfb8aa3b, v9
	v_mul_f32_e32 v14, 0xbfb8aa3b, v10
	v_mul_f32_e32 v15, 0xbfb8aa3b, v11
	v_exp_f32_e32 v12, v12
	v_exp_f32_e32 v13, v13
	v_exp_f32_e32 v14, v14
	v_exp_f32_e32 v15, v15
	v_add_f32_e32 v12, 1.0, v12
	v_add_f32_e32 v13, 1.0, v13
	v_add_f32_e32 v14, 1.0, v14
	v_add_f32_e32 v15, 1.0, v15
	v_rcp_f32_e32 v12, v12
	v_rcp_f32_e32 v13, v13
	v_rcp_f32_e32 v14, v14
	v_rcp_f32_e32 v15, v15
	v_pk_mul_f32 v[8:9], v[12:13], v[8:9]
	v_pk_mul_f32 v[10:11], v[14:15], v[10:11]
	v_pk_mul_f32 v[0:1], v[132:133], v[0:1]
	v_pk_mul_f32 v[2:3], v[134:135], v[2:3]
	v_pk_mul_f32 v[0:1], v[8:9], v[0:1]
	v_pk_mul_f32 v[2:3], v[10:11], v[2:3]
	v_cvt_pk_bf16_f32 v0, v0, v1
	v_cvt_pk_bf16_f32 v1, v2, v3
	global_store_dwordx2 v[20:21], v[0:1], off offset:96
	s_barrier
	s_load_dword s0, s[52:53], 0x0
	s_waitcnt lgkmcnt(0)
	s_add_i32 s43, s0, s43
	s_cmpk_gt_i32 s43, 0xff
	s_cbranch_scc1 .LBB0_170

; __device__ __forceinline__ f32x4 mfma16(bf16x8 a, bf16x8 b, f32x4 c) { return __builtin_amdgcn_mfma_f32_16x16x32_bf16(a, b, c, 0, 0, 0); }
; template <int MODE> __device__ void mixer_gla(const Params& p, int l, int n, LAS unsigned char* lds) {
;     ...
;             bf16x8 lrf[4], gwf[4]; float bgv[4];
; #pragma unroll
;             for (int tt = 0; tt < 4; ++tt) { lrf[tt] = (bf16x8){0, 0, 0, 0, 0, 0, 0, 0}; if (q < 2) lrf[tt] = *(const bf16x8*)(proj + (size_t)(t0 + 16 * tt + c) * DINP + 2560 + dir * 16 + 8 * q); }
; #pragma unroll
;             for (int ef = 0; ef < 4; ++ef) { gwf[ef] = *(const bf16x8*)(GW + (size_t)(dir * 256 + 64 * h + SIGC(ef, c)) * 32 + 8 * q); bgv[ef] = p.in[13][(size_t)(l * 2 + dir) * 256 + 64 * h + SIGC(ef, c)]; }
; #pragma unroll
;             for (int ef = 0; ef < 4; ++ef) { tot[ef] = 0.f;
; #pragma unroll
;                 for (int ks = 0; ks < 2; ++ks) { f32x4 la2[2];
; #pragma unroll
;                     for (int t2 = 0; t2 < 2; ++t2) { const f32x4 z = mfma16(lrf[2 * ks + t2], gwf[ef], zero4);
; #pragma unroll
;                         for (int r = 0; r < 4; ++r) { const float zz = z[r] + bgv[ef]; const float la = (fminf(zz, 0.f) - __logf(1.0f + __expf(-fabsf(zz)))) * (1.0f / 16.0f); la2[t2][r] = la; tot[ef] += la; } }
;                     laop[ef][ks] = pack8(la2[0], la2[1]); __builtin_amdgcn_sched_barrier(0); } }
.LBB0_151:
	s_or_b64 exec, exec, s[0:1]
	s_lshl_b32 s34, s4, 8
	v_add_u32_e32 v70, s34, v200
	v_or_b32_e32 v68, v70, v241
	v_ashrrev_i32_e32 v69, 31, v68
	v_lshlrev_b64 v[68:69], 6, v[68:69]
	v_readlane_b32 s0, v255, 21
	v_lshl_add_u64 v[68:69], v[202:203], 0, v[68:69]
	s_or_b32 s0, s4, s0
	global_load_dwordx4 v[84:87], v[68:69], off
	s_ashr_i32 s1, s0, 31
	s_lshl_b64 s[0:1], s[0:1], 10
	v_lshl_add_u64 v[76:77], v[222:223], 0, s[0:1]
	global_load_dword v104, v[76:77], off
	v_or_b32_e32 v68, 4, v241
	v_or_b32_e32 v68, v70, v68
	v_ashrrev_i32_e32 v69, 31, v68
	v_lshlrev_b64 v[68:69], 6, v[68:69]
	v_lshl_add_u64 v[68:69], v[202:203], 0, v[68:69]
	global_load_dwordx4 v[100:103], v[68:69], off
	global_load_dword v108, v[76:77], off offset:16
	v_or_b32_e32 v68, 32, v241
	v_or_b32_e32 v68, v70, v68
	v_ashrrev_i32_e32 v69, 31, v68
	v_lshlrev_b64 v[68:69], 6, v[68:69]
	v_lshl_add_u64 v[68:69], v[202:203], 0, v[68:69]
	global_load_dwordx4 v[92:95], v[68:69], off
	global_load_dword v113, v[76:77], off offset:128
	v_or_b32_e32 v68, 36, v241
	v_or_b32_e32 v68, v70, v68
	v_ashrrev_i32_e32 v69, 31, v68
	v_lshlrev_b64 v[68:69], 6, v[68:69]
	v_lshl_add_u64 v[68:69], v[202:203], 0, v[68:69]
	global_load_dwordx4 v[68:71], v[68:69], off
	s_nop 0
	global_load_dword v112, v[76:77], off offset:144
	s_xor_b64 s[30:31], s[26:27], -1
	s_waitcnt vmcnt(7)
	v_mfma_f32_16x16x32_bf16 v[76:79], v[88:91], v[84:87], 0
	s_waitcnt vmcnt(6)
	s_nop 6
	v_add_f32_e32 v96, v104, v76
	v_min_f32_e32 v76, 0, v96
	v_mul_f32_e64 v96, |v96|, s33
	v_exp_f32_e32 v96, v96
	v_add_f32_e32 v79, v104, v79
	v_add_f32_e32 v96, 1.0, v96
	v_log_f32_e32 v96, v96
	s_nop 0
	v_mul_f32_e32 v97, 0x3f317217, v96
	v_fma_f32 v97, v96, s36, -v97
	v_fmac_f32_e32 v97, 0x3377d1cf, v96
	v_fmac_f32_e32 v97, 0x3f317217, v96
	v_mov_b32_e32 v96, v97
	v_add_f32_e32 v97, v104, v77
	v_min_f32_e32 v77, 0, v97
	v_mul_f32_e64 v97, |v97|, s33
	v_exp_f32_e32 v97, v97
	s_nop 0
	v_add_f32_e32 v97, 1.0, v97
	v_log_f32_e32 v97, v97
	s_nop 0
	v_mul_f32_e32 v98, 0x3f317217, v97
	v_fma_f32 v98, v97, s36, -v98
	v_fmac_f32_e32 v98, 0x3377d1cf, v97
	v_fmac_f32_e32 v98, 0x3f317217, v97
	v_mov_b32_e32 v97, v98
	v_pk_add_f32 v[76:77], v[76:77], v[96:97] neg_lo:[0,1] neg_hi:[0,1]
	s_nop 0
	v_pk_mul_f32 v[96:97], v[76:77], s[50:51] op_sel_hi:[1,0]
	v_add_f32_e32 v77, v104, v78
	v_min_f32_e32 v76, 0, v77
	v_mul_f32_e64 v77, |v77|, s33
	v_exp_f32_e32 v77, v77
	s_nop 0
	v_add_f32_e32 v77, 1.0, v77
	v_log_f32_e32 v77, v77
	s_nop 0
	v_mul_f32_e32 v78, 0x3f317217, v77
	v_fma_f32 v78, v77, s36, -v78
	v_fmac_f32_e32 v78, 0x3377d1cf, v77
	v_fmac_f32_e32 v78, 0x3f317217, v77
	v_min_f32_e32 v77, 0, v79
	v_mul_f32_e64 v79, |v79|, s33
	v_exp_f32_e32 v79, v79
	s_nop 0
	v_add_f32_e32 v79, 1.0, v79
	v_log_f32_e32 v79, v79
	s_nop 0
	v_mul_f32_e32 v98, 0x3f317217, v79
	v_fma_f32 v98, v79, s36, -v98
	v_fmac_f32_e32 v98, 0x3377d1cf, v79
	v_fmac_f32_e32 v98, 0x3f317217, v79
	v_mov_b32_e32 v79, v98
	v_pk_add_f32 v[76:77], v[76:77], v[78:79] neg_lo:[0,1] neg_hi:[0,1]
	s_nop 0
	v_pk_mul_f32 v[98:99], v[76:77], s[50:51] op_sel_hi:[1,0]
	v_mfma_f32_16x16x32_bf16 v[76:79], v[80:83], v[84:87], 0
	s_nop 7
	v_add_f32_e32 v105, v104, v76
	v_min_f32_e32 v76, 0, v105
	v_mul_f32_e64 v105, |v105|, s33
	v_exp_f32_e32 v105, v105
	v_add_f32_e32 v79, v104, v79
	v_add_f32_e32 v105, 1.0, v105
	v_log_f32_e32 v105, v105
	s_nop 0
	v_mul_f32_e32 v106, 0x3f317217, v105
	v_fma_f32 v106, v105, s36, -v106
	v_fmac_f32_e32 v106, 0x3377d1cf, v105
	v_fmac_f32_e32 v106, 0x3f317217, v105
	v_add_f32_e32 v105, v104, v77
	v_min_f32_e32 v77, 0, v105
	v_mul_f32_e64 v105, |v105|, s33
	v_exp_f32_e32 v105, v105
	s_nop 0
	v_add_f32_e32 v105, 1.0, v105
	v_log_f32_e32 v105, v105
	s_nop 0
	v_mul_f32_e32 v107, 0x3f317217, v105
	v_fma_f32 v107, v105, s36, -v107
	v_fmac_f32_e32 v107, 0x3377d1cf, v105
	v_fmac_f32_e32 v107, 0x3f317217, v105
	v_pk_add_f32 v[76:77], v[76:77], v[106:107] neg_lo:[0,1] neg_hi:[0,1]
	s_nop 0
	v_pk_mul_f32 v[106:107], v[76:77], s[50:51] op_sel_hi:[1,0]
	v_add_f32_e32 v77, v104, v78
	v_min_f32_e32 v76, 0, v77
	v_mul_f32_e64 v77, |v77|, s33
	v_exp_f32_e32 v77, v77
	s_nop 0
	v_add_f32_e32 v77, 1.0, v77
	v_log_f32_e32 v77, v77
	s_nop 0
	v_mul_f32_e32 v78, 0x3f317217, v77
	v_fma_f32 v78, v77, s36, -v78
	v_fmac_f32_e32 v78, 0x3377d1cf, v77
	v_fmac_f32_e32 v78, 0x3f317217, v77
	v_min_f32_e32 v77, 0, v79
	v_mul_f32_e64 v79, |v79|, s33
	v_exp_f32_e32 v79, v79
	s_nop 0
	v_add_f32_e32 v79, 1.0, v79
	v_log_f32_e32 v79, v79
	s_nop 0
	v_mul_f32_e32 v105, 0x3f317217, v79
	v_fma_f32 v105, v79, s36, -v105
	v_fmac_f32_e32 v105, 0x3377d1cf, v79
	v_fmac_f32_e32 v105, 0x3f317217, v79
	v_mov_b32_e32 v79, v105
	v_pk_add_f32 v[76:77], v[76:77], v[78:79] neg_lo:[0,1] neg_hi:[0,1]
	v_cvt_pk_bf16_f32 v78, v106, v107
	v_pk_mul_f32 v[110:111], v[76:77], s[50:51] op_sel_hi:[1,0]
	v_cvt_pk_bf16_f32 v76, v96, v97
	v_cvt_pk_bf16_f32 v77, v98, v99
	v_cvt_pk_bf16_f32 v79, v110, v111
	v_mfma_f32_16x16x32_bf16 v[96:99], v[72:75], v[84:87], 0
	v_mfma_f32_16x16x32_bf16 v[84:87], v[64:67], v[84:87], 0
	s_nop 6
	v_add_f32_e32 v105, v104, v96
	v_min_f32_e32 v96, 0, v105
	v_mul_f32_e64 v105, |v105|, s33
	v_exp_f32_e32 v105, v105
	v_add_f32_e32 v87, v104, v87
	v_add_f32_e32 v105, 1.0, v105
	v_log_f32_e32 v105, v105
	s_nop 0
	v_mul_f32_e32 v106, 0x3f317217, v105
	v_fma_f32 v106, v105, s36, -v106
	v_fmac_f32_e32 v106, 0x3377d1cf, v105
	v_fmac_f32_e32 v106, 0x3f317217, v105
	v_add_f32_e32 v105, v104, v97
	v_min_f32_e32 v97, 0, v105
	v_mul_f32_e64 v105, |v105|, s33
	v_exp_f32_e32 v105, v105
	s_nop 0
	v_add_f32_e32 v105, 1.0, v105
	v_log_f32_e32 v105, v105
	s_nop 0
	v_mul_f32_e32 v107, 0x3f317217, v105
	v_fma_f32 v107, v105, s36, -v107
; __device__ __forceinline__ f32x4 mfma16(bf16x8 a, bf16x8 b, f32x4 c) { return __builtin_amdgcn_mfma_f32_16x16x32_bf16(a, b, c, 0, 0, 0); }
; template <int MODE> __device__ void mixer_gla(const Params& p, int l, int n, LAS unsigned char* lds) {
;     ...
;             bf16x8 lrf[4], gwf[4]; float bgv[4];
; #pragma unroll
;             for (int tt = 0; tt < 4; ++tt) { lrf[tt] = (bf16x8){0, 0, 0, 0, 0, 0, 0, 0}; if (q < 2) lrf[tt] = *(const bf16x8*)(proj + (size_t)(t0 + 16 * tt + c) * DINP + 2560 + dir * 16 + 8 * q); }
; #pragma unroll
;             for (int ef = 0; ef < 4; ++ef) { gwf[ef] = *(const bf16x8*)(GW + (size_t)(dir * 256 + 64 * h + SIGC(ef, c)) * 32 + 8 * q); bgv[ef] = p.in[13][(size_t)(l * 2 + dir) * 256 + 64 * h + SIGC(ef, c)]; }
; #pragma unroll
;             for (int ef = 0; ef < 4; ++ef) { tot[ef] = 0.f;
; #pragma unroll
;                 for (int ks = 0; ks < 2; ++ks) { f32x4 la2[2];
; #pragma unroll
;                     for (int t2 = 0; t2 < 2; ++t2) { const f32x4 z = mfma16(lrf[2 * ks + t2], gwf[ef], zero4);
; #pragma unroll
;                         for (int r = 0; r < 4; ++r) { const float zz = z[r] + bgv[ef]; const float la = (fminf(zz, 0.f) - __logf(1.0f + __expf(-fabsf(zz)))) * (1.0f / 16.0f); la2[t2][r] = la; tot[ef] += la; } }
;                     laop[ef][ks] = pack8(la2[0], la2[1]); __builtin_amdgcn_sched_barrier(0); } }
	v_fmac_f32_e32 v107, 0x3377d1cf, v105
	v_fmac_f32_e32 v107, 0x3f317217, v105
	v_add_f32_e32 v105, v104, v98
	v_min_f32_e32 v98, 0, v105
	v_mul_f32_e64 v105, |v105|, s33
	v_exp_f32_e32 v105, v105
	v_pk_add_f32 v[96:97], v[96:97], v[106:107] neg_lo:[0,1] neg_hi:[0,1]
	v_add_f32_e32 v105, 1.0, v105
	v_pk_mul_f32 v[96:97], v[96:97], s[50:51] op_sel_hi:[1,0]
	s_nop 0
	v_log_f32_e32 v105, v105
	s_nop 0
	v_mul_f32_e32 v106, 0x3f317217, v105
	v_fma_f32 v106, v105, s36, -v106
	v_fmac_f32_e32 v106, 0x3377d1cf, v105
	v_fmac_f32_e32 v106, 0x3f317217, v105
	v_add_f32_e32 v105, v104, v99
	v_min_f32_e32 v99, 0, v105
	v_mul_f32_e64 v105, |v105|, s33
	v_exp_f32_e32 v105, v105
	s_nop 0
	v_add_f32_e32 v105, 1.0, v105
	v_log_f32_e32 v105, v105
	s_nop 0
	v_mul_f32_e32 v107, 0x3f317217, v105
	v_fma_f32 v107, v105, s36, -v107
	v_fmac_f32_e32 v107, 0x3377d1cf, v105
	v_fmac_f32_e32 v107, 0x3f317217, v105
	v_add_f32_e32 v105, v104, v84
	v_min_f32_e32 v84, 0, v105
	v_mul_f32_e64 v105, |v105|, s33
	v_exp_f32_e32 v105, v105
	v_pk_add_f32 v[98:99], v[98:99], v[106:107] neg_lo:[0,1] neg_hi:[0,1]
	v_add_f32_e32 v105, 1.0, v105
	v_pk_mul_f32 v[98:99], v[98:99], s[50:51] op_sel_hi:[1,0]
	s_nop 0
	v_log_f32_e32 v105, v105
	s_nop 0
	v_mul_f32_e32 v106, 0x3f317217, v105
	v_fma_f32 v106, v105, s36, -v106
	v_fmac_f32_e32 v106, 0x3377d1cf, v105
	v_fmac_f32_e32 v106, 0x3f317217, v105
	v_add_f32_e32 v105, v104, v85
	v_min_f32_e32 v85, 0, v105
	v_mul_f32_e64 v105, |v105|, s33
	v_exp_f32_e32 v105, v105
	s_nop 0
	v_add_f32_e32 v105, 1.0, v105
	v_log_f32_e32 v105, v105
	s_nop 0
	v_mul_f32_e32 v107, 0x3f317217, v105
	v_fma_f32 v107, v105, s36, -v107
	v_fmac_f32_e32 v107, 0x3377d1cf, v105
	v_fmac_f32_e32 v107, 0x3f317217, v105
	v_pk_add_f32 v[84:85], v[84:85], v[106:107] neg_lo:[0,1] neg_hi:[0,1]
	s_nop 0
	v_pk_mul_f32 v[106:107], v[84:85], s[50:51] op_sel_hi:[1,0]
	v_add_f32_e32 v85, v104, v86
	v_min_f32_e32 v84, 0, v85
	v_mul_f32_e64 v85, |v85|, s33
	v_exp_f32_e32 v85, v85
	s_nop 0
	v_add_f32_e32 v85, 1.0, v85
	v_log_f32_e32 v85, v85
	s_nop 0
	v_mul_f32_e32 v86, 0x3f317217, v85
	v_fma_f32 v86, v85, s36, -v86
	v_fmac_f32_e32 v86, 0x3377d1cf, v85
	v_fmac_f32_e32 v86, 0x3f317217, v85
	v_min_f32_e32 v85, 0, v87
	v_mul_f32_e64 v87, |v87|, s33
	v_exp_f32_e32 v87, v87
	s_nop 0
	v_add_f32_e32 v87, 1.0, v87
	v_log_f32_e32 v87, v87
	s_nop 0
	v_mul_f32_e32 v104, 0x3f317217, v87
	v_fma_f32 v104, v87, s36, -v104
	v_fmac_f32_e32 v104, 0x3377d1cf, v87
	v_fmac_f32_e32 v104, 0x3f317217, v87
	v_mov_b32_e32 v87, v104
	v_pk_add_f32 v[84:85], v[84:85], v[86:87] neg_lo:[0,1] neg_hi:[0,1]
	v_cvt_pk_bf16_f32 v86, v106, v107
	v_pk_mul_f32 v[104:105], v[84:85], s[50:51] op_sel_hi:[1,0]
	v_cvt_pk_bf16_f32 v84, v96, v97
	v_cvt_pk_bf16_f32 v85, v98, v99
	v_cvt_pk_bf16_f32 v87, v104, v105
	s_waitcnt vmcnt(5)
	v_mfma_f32_16x16x32_bf16 v[96:99], v[88:91], v[100:103], 0
	s_waitcnt vmcnt(4)
	s_nop 6
	v_add_f32_e32 v104, v108, v96
	v_min_f32_e32 v96, 0, v104
	v_mul_f32_e64 v104, |v104|, s33
	v_exp_f32_e32 v104, v104
	s_nop 0
	v_add_f32_e32 v104, 1.0, v104
	v_log_f32_e32 v104, v104
	s_nop 0
	v_mul_f32_e32 v105, 0x3f317217, v104
	v_fma_f32 v105, v104, s36, -v105
	v_fmac_f32_e32 v105, 0x3377d1cf, v104
	v_fmac_f32_e32 v105, 0x3f317217, v104
	v_mov_b32_e32 v104, v105
	v_add_f32_e32 v105, v108, v97
	v_min_f32_e32 v97, 0, v105
	v_mul_f32_e64 v105, |v105|, s33
	v_exp_f32_e32 v105, v105
	s_nop 0
	v_add_f32_e32 v105, 1.0, v105
	v_log_f32_e32 v105, v105
	s_nop 0
	v_mul_f32_e32 v106, 0x3f317217, v105
	v_fma_f32 v106, v105, s36, -v106
	v_fmac_f32_e32 v106, 0x3377d1cf, v105
	v_fmac_f32_e32 v106, 0x3f317217, v105
	v_mov_b32_e32 v105, v106
	v_pk_add_f32 v[96:97], v[96:97], v[104:105] neg_lo:[0,1] neg_hi:[0,1]
	v_add_f32_e32 v104, v108, v98
	v_min_f32_e32 v98, 0, v104
	v_mul_f32_e64 v104, |v104|, s33
	v_exp_f32_e32 v104, v104
	v_pk_mul_f32 v[96:97], v[96:97], s[50:51] op_sel_hi:[1,0]
	v_add_f32_e32 v104, 1.0, v104
	v_cvt_pk_bf16_f32 v96, v96, v97
	s_nop 0
	v_log_f32_e32 v104, v104
	s_nop 0
	v_mul_f32_e32 v105, 0x3f317217, v104
	v_fma_f32 v105, v104, s36, -v105
	v_fmac_f32_e32 v105, 0x3377d1cf, v104
	v_fmac_f32_e32 v105, 0x3f317217, v104
	v_mov_b32_e32 v104, v105
	v_add_f32_e32 v105, v108, v99
	v_min_f32_e32 v99, 0, v105
	v_mul_f32_e64 v105, |v105|, s33
	v_exp_f32_e32 v105, v105
	s_nop 0
	v_add_f32_e32 v105, 1.0, v105
	v_log_f32_e32 v105, v105
	s_nop 0
	v_mul_f32_e32 v106, 0x3f317217, v105
	v_fma_f32 v106, v105, s36, -v106
	v_fmac_f32_e32 v106, 0x3377d1cf, v105
	v_fmac_f32_e32 v106, 0x3f317217, v105
	v_mov_b32_e32 v105, v106
	v_pk_add_f32 v[98:99], v[98:99], v[104:105] neg_lo:[0,1] neg_hi:[0,1]
	v_mfma_f32_16x16x32_bf16 v[104:107], v[80:83], v[100:103], 0
	v_mul_f32_e64 v98, v98, s50
	v_mul_f32_e64 v99, v99, s50
	v_cvt_pk_bf16_f32 v97, v98, v99
	s_nop 4
	v_add_f32_e32 v109, v108, v104
	v_min_f32_e32 v104, 0, v109
	v_mul_f32_e64 v109, |v109|, s33
	v_exp_f32_e32 v109, v109
	s_nop 0
	v_add_f32_e32 v109, 1.0, v109
	v_log_f32_e32 v109, v109
	s_nop 0
	v_mul_f32_e32 v110, 0x3f317217, v109
	v_fma_f32 v110, v109, s36, -v110
	v_fmac_f32_e32 v110, 0x3377d1cf, v109
	v_fmac_f32_e32 v110, 0x3f317217, v109
	v_add_f32_e32 v109, v108, v105
	v_min_f32_e32 v105, 0, v109
	v_mul_f32_e64 v109, |v109|, s33
	v_exp_f32_e32 v109, v109
	s_nop 0
	v_add_f32_e32 v109, 1.0, v109
	v_log_f32_e32 v109, v109
	s_nop 0
	v_mul_f32_e32 v111, 0x3f317217, v109
	v_fma_f32 v111, v109, s36, -v111
	v_fmac_f32_e32 v111, 0x3377d1cf, v109
	v_fmac_f32_e32 v111, 0x3f317217, v109
	v_add_f32_e32 v109, v108, v106
	v_min_f32_e32 v106, 0, v109
	v_mul_f32_e64 v109, |v109|, s33
	v_exp_f32_e32 v109, v109
	v_pk_add_f32 v[104:105], v[104:105], v[110:111] neg_lo:[0,1] neg_hi:[0,1]
; __device__ __forceinline__ f32x4 mfma16(bf16x8 a, bf16x8 b, f32x4 c) { return __builtin_amdgcn_mfma_f32_16x16x32_bf16(a, b, c, 0, 0, 0); }
; template <int MODE> __device__ void mixer_gla(const Params& p, int l, int n, LAS unsigned char* lds) {
;     ...
;             bf16x8 lrf[4], gwf[4]; float bgv[4];
; #pragma unroll
;             for (int tt = 0; tt < 4; ++tt) { lrf[tt] = (bf16x8){0, 0, 0, 0, 0, 0, 0, 0}; if (q < 2) lrf[tt] = *(const bf16x8*)(proj + (size_t)(t0 + 16 * tt + c) * DINP + 2560 + dir * 16 + 8 * q); }
; #pragma unroll
;             for (int ef = 0; ef < 4; ++ef) { gwf[ef] = *(const bf16x8*)(GW + (size_t)(dir * 256 + 64 * h + SIGC(ef, c)) * 32 + 8 * q); bgv[ef] = p.in[13][(size_t)(l * 2 + dir) * 256 + 64 * h + SIGC(ef, c)]; }
; #pragma unroll
;             for (int ef = 0; ef < 4; ++ef) { tot[ef] = 0.f;
; #pragma unroll
;                 for (int ks = 0; ks < 2; ++ks) { f32x4 la2[2];
; #pragma unroll
;                     for (int t2 = 0; t2 < 2; ++t2) { const f32x4 z = mfma16(lrf[2 * ks + t2], gwf[ef], zero4);
; #pragma unroll
;                         for (int r = 0; r < 4; ++r) { const float zz = z[r] + bgv[ef]; const float la = (fminf(zz, 0.f) - __logf(1.0f + __expf(-fabsf(zz)))) * (1.0f / 16.0f); la2[t2][r] = la; tot[ef] += la; } }
;                     laop[ef][ks] = pack8(la2[0], la2[1]); __builtin_amdgcn_sched_barrier(0); } }
	v_add_f32_e32 v109, 1.0, v109
	v_pk_mul_f32 v[104:105], v[104:105], s[50:51] op_sel_hi:[1,0]
	s_nop 0
	v_log_f32_e32 v109, v109
	v_cvt_pk_bf16_f32 v98, v104, v105
	v_mul_f32_e32 v110, 0x3f317217, v109
	v_fma_f32 v110, v109, s36, -v110
	v_fmac_f32_e32 v110, 0x3377d1cf, v109
	v_fmac_f32_e32 v110, 0x3f317217, v109
	v_add_f32_e32 v109, v108, v107
	v_min_f32_e32 v107, 0, v109
	v_mul_f32_e64 v109, |v109|, s33
	v_exp_f32_e32 v109, v109
	s_nop 0
	v_add_f32_e32 v109, 1.0, v109
	v_log_f32_e32 v109, v109
	s_nop 0
	v_mul_f32_e32 v111, 0x3f317217, v109
	v_fma_f32 v111, v109, s36, -v111
	v_fmac_f32_e32 v111, 0x3377d1cf, v109
	v_fmac_f32_e32 v111, 0x3f317217, v109
	v_pk_add_f32 v[106:107], v[106:107], v[110:111] neg_lo:[0,1] neg_hi:[0,1]
	s_nop 0
	v_pk_mul_f32 v[106:107], v[106:107], s[50:51] op_sel_hi:[1,0]
	s_nop 0
	v_cvt_pk_bf16_f32 v99, v106, v107
	v_mfma_f32_16x16x32_bf16 v[104:107], v[72:75], v[100:103], 0
	v_mfma_f32_16x16x32_bf16 v[100:103], v[64:67], v[100:103], 0
	s_nop 6
	v_add_f32_e32 v109, v108, v104
	v_min_f32_e32 v104, 0, v109
	v_mul_f32_e64 v109, |v109|, s33
	v_exp_f32_e32 v109, v109
	v_add_f32_e32 v103, v108, v103
	v_add_f32_e32 v109, 1.0, v109
	v_log_f32_e32 v109, v109
	s_nop 0
	v_mul_f32_e32 v110, 0x3f317217, v109
	v_fma_f32 v110, v109, s36, -v110
	v_fmac_f32_e32 v110, 0x3377d1cf, v109
	v_fmac_f32_e32 v110, 0x3f317217, v109
	v_add_f32_e32 v109, v108, v105
	v_min_f32_e32 v105, 0, v109
	v_mul_f32_e64 v109, |v109|, s33
	v_exp_f32_e32 v109, v109
	s_nop 0
	v_add_f32_e32 v109, 1.0, v109
	v_log_f32_e32 v109, v109
	s_nop 0
	v_mul_f32_e32 v111, 0x3f317217, v109
	v_fma_f32 v111, v109, s36, -v111
	v_fmac_f32_e32 v111, 0x3377d1cf, v109
	v_fmac_f32_e32 v111, 0x3f317217, v109
	v_add_f32_e32 v109, v108, v106
	v_min_f32_e32 v106, 0, v109
	v_mul_f32_e64 v109, |v109|, s33
	v_exp_f32_e32 v109, v109
	v_pk_add_f32 v[104:105], v[104:105], v[110:111] neg_lo:[0,1] neg_hi:[0,1]
	v_add_f32_e32 v109, 1.0, v109
	v_pk_mul_f32 v[104:105], v[104:105], s[50:51] op_sel_hi:[1,0]
	s_nop 0
	v_log_f32_e32 v109, v109
	s_nop 0
	v_mul_f32_e32 v110, 0x3f317217, v109
	v_fma_f32 v110, v109, s36, -v110
	v_fmac_f32_e32 v110, 0x3377d1cf, v109
	v_fmac_f32_e32 v110, 0x3f317217, v109
	v_add_f32_e32 v109, v108, v107
	v_min_f32_e32 v107, 0, v109
	v_mul_f32_e64 v109, |v109|, s33
	v_exp_f32_e32 v109, v109
	s_nop 0
	v_add_f32_e32 v109, 1.0, v109
	v_log_f32_e32 v109, v109
	s_nop 0
	v_mul_f32_e32 v111, 0x3f317217, v109
	v_fma_f32 v111, v109, s36, -v111
	v_fmac_f32_e32 v111, 0x3377d1cf, v109
	v_fmac_f32_e32 v111, 0x3f317217, v109
	v_add_f32_e32 v109, v108, v100
	v_min_f32_e32 v100, 0, v109
	v_mul_f32_e64 v109, |v109|, s33
	v_exp_f32_e32 v109, v109
	v_pk_add_f32 v[106:107], v[106:107], v[110:111] neg_lo:[0,1] neg_hi:[0,1]
	v_add_f32_e32 v109, 1.0, v109
	v_pk_mul_f32 v[106:107], v[106:107], s[50:51] op_sel_hi:[1,0]
	s_nop 0
	v_log_f32_e32 v109, v109
	s_nop 0
	v_mul_f32_e32 v110, 0x3f317217, v109
	v_fma_f32 v110, v109, s36, -v110
	v_fmac_f32_e32 v110, 0x3377d1cf, v109
	v_fmac_f32_e32 v110, 0x3f317217, v109
	v_add_f32_e32 v109, v108, v101
	v_min_f32_e32 v101, 0, v109
	v_mul_f32_e64 v109, |v109|, s33
	v_exp_f32_e32 v109, v109
	s_nop 0
	v_add_f32_e32 v109, 1.0, v109
	v_log_f32_e32 v109, v109
	s_nop 0
	v_mul_f32_e32 v111, 0x3f317217, v109
	v_fma_f32 v111, v109, s36, -v111
	v_fmac_f32_e32 v111, 0x3377d1cf, v109
	v_fmac_f32_e32 v111, 0x3f317217, v109
	v_pk_add_f32 v[100:101], v[100:101], v[110:111] neg_lo:[0,1] neg_hi:[0,1]
	s_nop 0
	v_pk_mul_f32 v[110:111], v[100:101], s[50:51] op_sel_hi:[1,0]
	v_add_f32_e32 v101, v108, v102
	v_min_f32_e32 v100, 0, v101
	v_mul_f32_e64 v101, |v101|, s33
	v_exp_f32_e32 v101, v101
	s_nop 0
	v_add_f32_e32 v101, 1.0, v101
	v_log_f32_e32 v101, v101
	s_nop 0
	v_mul_f32_e32 v102, 0x3f317217, v101
	v_fma_f32 v102, v101, s36, -v102
	v_fmac_f32_e32 v102, 0x3377d1cf, v101
	v_fmac_f32_e32 v102, 0x3f317217, v101
	v_min_f32_e32 v101, 0, v103
	v_mul_f32_e64 v103, |v103|, s33
	v_exp_f32_e32 v103, v103
	s_nop 0
	v_add_f32_e32 v103, 1.0, v103
	v_log_f32_e32 v103, v103
	s_nop 0
	v_mul_f32_e32 v108, 0x3f317217, v103
	v_fma_f32 v108, v103, s36, -v108
	v_fmac_f32_e32 v108, 0x3377d1cf, v103
	v_fmac_f32_e32 v108, 0x3f317217, v103
	v_mov_b32_e32 v103, v108
	v_pk_add_f32 v[100:101], v[100:101], v[102:103] neg_lo:[0,1] neg_hi:[0,1]
	v_cvt_pk_bf16_f32 v102, v110, v111
	v_pk_mul_f32 v[108:109], v[100:101], s[50:51] op_sel_hi:[1,0]
	v_cvt_pk_bf16_f32 v100, v104, v105
	v_cvt_pk_bf16_f32 v101, v106, v107
	v_cvt_pk_bf16_f32 v103, v108, v109
	s_waitcnt vmcnt(3)
	v_mfma_f32_16x16x32_bf16 v[104:107], v[88:91], v[92:95], 0
	s_waitcnt vmcnt(2)
; __device__ __forceinline__ f32x4 mfma16(bf16x8 a, bf16x8 b, f32x4 c) { return __builtin_amdgcn_mfma_f32_16x16x32_bf16(a, b, c, 0, 0, 0); }
; template <int MODE> __device__ void mixer_gla(const Params& p, int l, int n, LAS unsigned char* lds) {
;     ...
;             bf16x8 lrf[4], gwf[4]; float bgv[4];
; #pragma unroll
;             for (int tt = 0; tt < 4; ++tt) { lrf[tt] = (bf16x8){0, 0, 0, 0, 0, 0, 0, 0}; if (q < 2) lrf[tt] = *(const bf16x8*)(proj + (size_t)(t0 + 16 * tt + c) * DINP + 2560 + dir * 16 + 8 * q); }
; #pragma unroll
;             for (int ef = 0; ef < 4; ++ef) { gwf[ef] = *(const bf16x8*)(GW + (size_t)(dir * 256 + 64 * h + SIGC(ef, c)) * 32 + 8 * q); bgv[ef] = p.in[13][(size_t)(l * 2 + dir) * 256 + 64 * h + SIGC(ef, c)]; }
; #pragma unroll
;             for (int ef = 0; ef < 4; ++ef) { tot[ef] = 0.f;
; #pragma unroll
;                 for (int ks = 0; ks < 2; ++ks) { f32x4 la2[2];
; #pragma unroll
;                     for (int t2 = 0; t2 < 2; ++t2) { const f32x4 z = mfma16(lrf[2 * ks + t2], gwf[ef], zero4);
; #pragma unroll
;                         for (int r = 0; r < 4; ++r) { const float zz = z[r] + bgv[ef]; const float la = (fminf(zz, 0.f) - __logf(1.0f + __expf(-fabsf(zz)))) * (1.0f / 16.0f); la2[t2][r] = la; tot[ef] += la; } }
;                     laop[ef][ks] = pack8(la2[0], la2[1]); __builtin_amdgcn_sched_barrier(0); } }
	s_nop 6
	v_add_f32_e32 v108, v113, v104
	v_min_f32_e32 v104, 0, v108
	v_mul_f32_e64 v108, |v108|, s33
	v_exp_f32_e32 v108, v108
	s_nop 0
	v_add_f32_e32 v108, 1.0, v108
	v_log_f32_e32 v108, v108
	s_nop 0
	v_mul_f32_e32 v109, 0x3f317217, v108
	v_fma_f32 v109, v108, s36, -v109
	v_fmac_f32_e32 v109, 0x3377d1cf, v108
	v_fmac_f32_e32 v109, 0x3f317217, v108
	v_mov_b32_e32 v108, v109
	v_add_f32_e32 v109, v113, v105
	v_min_f32_e32 v105, 0, v109
	v_mul_f32_e64 v109, |v109|, s33
	v_exp_f32_e32 v109, v109
	s_nop 0
	v_add_f32_e32 v109, 1.0, v109
	v_log_f32_e32 v109, v109
	s_nop 0
	v_mul_f32_e32 v110, 0x3f317217, v109
	v_fma_f32 v110, v109, s36, -v110
	v_fmac_f32_e32 v110, 0x3377d1cf, v109
	v_fmac_f32_e32 v110, 0x3f317217, v109
	v_mov_b32_e32 v109, v110
	v_pk_add_f32 v[104:105], v[104:105], v[108:109] neg_lo:[0,1] neg_hi:[0,1]
	v_add_f32_e32 v108, v113, v106
	v_min_f32_e32 v106, 0, v108
	v_mul_f32_e64 v108, |v108|, s33
	v_exp_f32_e32 v108, v108
	v_pk_mul_f32 v[104:105], v[104:105], s[50:51] op_sel_hi:[1,0]
	v_add_f32_e32 v108, 1.0, v108
	v_cvt_pk_bf16_f32 v104, v104, v105
	s_nop 0
	v_log_f32_e32 v108, v108
	s_nop 0
	v_mul_f32_e32 v109, 0x3f317217, v108
	v_fma_f32 v109, v108, s36, -v109
	v_fmac_f32_e32 v109, 0x3377d1cf, v108
	v_fmac_f32_e32 v109, 0x3f317217, v108
	v_mov_b32_e32 v108, v109
	v_add_f32_e32 v109, v113, v107
	v_min_f32_e32 v107, 0, v109
	v_mul_f32_e64 v109, |v109|, s33
	v_exp_f32_e32 v109, v109
	s_nop 0
	v_add_f32_e32 v109, 1.0, v109
	v_log_f32_e32 v109, v109
	s_nop 0
	v_mul_f32_e32 v110, 0x3f317217, v109
	v_fma_f32 v110, v109, s36, -v110
	v_fmac_f32_e32 v110, 0x3377d1cf, v109
	v_fmac_f32_e32 v110, 0x3f317217, v109
	v_mov_b32_e32 v109, v110
	v_pk_add_f32 v[106:107], v[106:107], v[108:109] neg_lo:[0,1] neg_hi:[0,1]
	v_mfma_f32_16x16x32_bf16 v[108:111], v[80:83], v[92:95], 0
	v_mul_f32_e64 v106, v106, s50
	v_mul_f32_e64 v107, v107, s50
	v_cvt_pk_bf16_f32 v105, v106, v107
	s_nop 4
	v_add_f32_e32 v114, v113, v108
	v_min_f32_e32 v108, 0, v114
	v_mul_f32_e64 v114, |v114|, s33
	v_exp_f32_e32 v114, v114
	s_nop 0
	v_add_f32_e32 v114, 1.0, v114
	v_log_f32_e32 v114, v114
	s_nop 0
	v_mul_f32_e32 v115, 0x3f317217, v114
	v_fma_f32 v115, v114, s36, -v115
	v_fmac_f32_e32 v115, 0x3377d1cf, v114
	v_fmac_f32_e32 v115, 0x3f317217, v114
	v_mov_b32_e32 v114, v115
	v_add_f32_e32 v115, v113, v109
	v_min_f32_e32 v109, 0, v115
	v_mul_f32_e64 v115, |v115|, s33
	v_exp_f32_e32 v115, v115
	s_nop 0
	v_add_f32_e32 v115, 1.0, v115
	v_log_f32_e32 v115, v115
	s_nop 0
	v_mul_f32_e32 v116, 0x3f317217, v115
	v_fma_f32 v116, v115, s36, -v116
	v_fmac_f32_e32 v116, 0x3377d1cf, v115
	v_fmac_f32_e32 v116, 0x3f317217, v115
	v_mov_b32_e32 v115, v116
	v_pk_add_f32 v[108:109], v[108:109], v[114:115] neg_lo:[0,1] neg_hi:[0,1]
	v_add_f32_e32 v114, v113, v110
	v_min_f32_e32 v110, 0, v114
	v_mul_f32_e64 v114, |v114|, s33
	v_exp_f32_e32 v114, v114
	v_pk_mul_f32 v[108:109], v[108:109], s[50:51] op_sel_hi:[1,0]
	v_add_f32_e32 v114, 1.0, v114
	v_cvt_pk_bf16_f32 v106, v108, v109
	s_nop 0
	v_log_f32_e32 v114, v114
	s_nop 0
	v_mul_f32_e32 v115, 0x3f317217, v114
	v_fma_f32 v115, v114, s36, -v115
	v_fmac_f32_e32 v115, 0x3377d1cf, v114
	v_fmac_f32_e32 v115, 0x3f317217, v114
	v_mov_b32_e32 v114, v115
	v_add_f32_e32 v115, v113, v111
	v_min_f32_e32 v111, 0, v115
	v_mul_f32_e64 v115, |v115|, s33
	v_exp_f32_e32 v115, v115
	s_nop 0
	v_add_f32_e32 v115, 1.0, v115
	v_log_f32_e32 v115, v115
	s_nop 0
	v_mul_f32_e32 v116, 0x3f317217, v115
	v_fma_f32 v116, v115, s36, -v116
	v_fmac_f32_e32 v116, 0x3377d1cf, v115
	v_fmac_f32_e32 v116, 0x3f317217, v115
	v_mov_b32_e32 v115, v116
	v_pk_add_f32 v[110:111], v[110:111], v[114:115] neg_lo:[0,1] neg_hi:[0,1]
	s_nop 0
	v_pk_mul_f32 v[110:111], v[110:111], s[50:51] op_sel_hi:[1,0]
	s_nop 0
	v_cvt_pk_bf16_f32 v107, v110, v111
	v_mfma_f32_16x16x32_bf16 v[108:111], v[72:75], v[92:95], 0
	v_mfma_f32_16x16x32_bf16 v[92:95], v[64:67], v[92:95], 0
	s_nop 6
	v_add_f32_e32 v114, v113, v108
	v_min_f32_e32 v108, 0, v114
	v_mul_f32_e64 v114, |v114|, s33
	v_exp_f32_e32 v114, v114
	v_add_f32_e32 v95, v113, v95
	v_add_f32_e32 v114, 1.0, v114
	v_log_f32_e32 v114, v114
	s_nop 0
	v_mul_f32_e32 v115, 0x3f317217, v114
	v_fma_f32 v115, v114, s36, -v115
	v_fmac_f32_e32 v115, 0x3377d1cf, v114
	v_fmac_f32_e32 v115, 0x3f317217, v114
	v_mov_b32_e32 v114, v115
	v_add_f32_e32 v115, v113, v109
	v_min_f32_e32 v109, 0, v115
	v_mul_f32_e64 v115, |v115|, s33
	v_exp_f32_e32 v115, v115
	s_nop 0
	v_add_f32_e32 v115, 1.0, v115
	v_log_f32_e32 v115, v115
	s_nop 0
	v_mul_f32_e32 v116, 0x3f317217, v115
	v_fma_f32 v116, v115, s36, -v116
	v_fmac_f32_e32 v116, 0x3377d1cf, v115
	v_fmac_f32_e32 v116, 0x3f317217, v115
	v_mov_b32_e32 v115, v116
	v_pk_add_f32 v[108:109], v[108:109], v[114:115] neg_lo:[0,1] neg_hi:[0,1]
	v_add_f32_e32 v114, v113, v110
	v_min_f32_e32 v110, 0, v114
	v_mul_f32_e64 v114, |v114|, s33
	v_exp_f32_e32 v114, v114
	v_pk_mul_f32 v[108:109], v[108:109], s[50:51] op_sel_hi:[1,0]
	v_add_f32_e32 v114, 1.0, v114
	v_log_f32_e32 v114, v114
	s_nop 0
	v_mul_f32_e32 v115, 0x3f317217, v114
	v_fma_f32 v115, v114, s36, -v115
	v_fmac_f32_e32 v115, 0x3377d1cf, v114
	v_fmac_f32_e32 v115, 0x3f317217, v114
	v_mov_b32_e32 v114, v115
	v_add_f32_e32 v115, v113, v111
	v_min_f32_e32 v111, 0, v115
	v_mul_f32_e64 v115, |v115|, s33
	v_exp_f32_e32 v115, v115
	s_nop 0
	v_add_f32_e32 v115, 1.0, v115
	v_log_f32_e32 v115, v115
	s_nop 0
	v_mul_f32_e32 v116, 0x3f317217, v115
	v_fma_f32 v116, v115, s36, -v116
	v_fmac_f32_e32 v116, 0x3377d1cf, v115
	v_fmac_f32_e32 v116, 0x3f317217, v115
	v_mov_b32_e32 v115, v116
	v_pk_add_f32 v[110:111], v[110:111], v[114:115] neg_lo:[0,1] neg_hi:[0,1]
	v_add_f32_e32 v114, v113, v92
; __device__ __forceinline__ f32x4 mfma16(bf16x8 a, bf16x8 b, f32x4 c) { return __builtin_amdgcn_mfma_f32_16x16x32_bf16(a, b, c, 0, 0, 0); }
; template <int MODE> __device__ void mixer_gla(const Params& p, int l, int n, LAS unsigned char* lds) {
;     ...
;             bf16x8 lrf[4], gwf[4]; float bgv[4];
; #pragma unroll
;             for (int tt = 0; tt < 4; ++tt) { lrf[tt] = (bf16x8){0, 0, 0, 0, 0, 0, 0, 0}; if (q < 2) lrf[tt] = *(const bf16x8*)(proj + (size_t)(t0 + 16 * tt + c) * DINP + 2560 + dir * 16 + 8 * q); }
; #pragma unroll
;             for (int ef = 0; ef < 4; ++ef) { gwf[ef] = *(const bf16x8*)(GW + (size_t)(dir * 256 + 64 * h + SIGC(ef, c)) * 32 + 8 * q); bgv[ef] = p.in[13][(size_t)(l * 2 + dir) * 256 + 64 * h + SIGC(ef, c)]; }
; #pragma unroll
;             for (int ef = 0; ef < 4; ++ef) { tot[ef] = 0.f;
; #pragma unroll
;                 for (int ks = 0; ks < 2; ++ks) { f32x4 la2[2];
; #pragma unroll
;                     for (int t2 = 0; t2 < 2; ++t2) { const f32x4 z = mfma16(lrf[2 * ks + t2], gwf[ef], zero4);
; #pragma unroll
;                         for (int r = 0; r < 4; ++r) { const float zz = z[r] + bgv[ef]; const float la = (fminf(zz, 0.f) - __logf(1.0f + __expf(-fabsf(zz)))) * (1.0f / 16.0f); la2[t2][r] = la; tot[ef] += la; } }
;                     laop[ef][ks] = pack8(la2[0], la2[1]); __builtin_amdgcn_sched_barrier(0); } }
	v_min_f32_e32 v92, 0, v114
	v_mul_f32_e64 v114, |v114|, s33
	v_exp_f32_e32 v114, v114
	v_pk_mul_f32 v[110:111], v[110:111], s[50:51] op_sel_hi:[1,0]
	v_add_f32_e32 v114, 1.0, v114
	v_log_f32_e32 v114, v114
	s_nop 0
	v_mul_f32_e32 v115, 0x3f317217, v114
	v_fma_f32 v115, v114, s36, -v115
	v_fmac_f32_e32 v115, 0x3377d1cf, v114
	v_fmac_f32_e32 v115, 0x3f317217, v114
	v_mov_b32_e32 v114, v115
	v_add_f32_e32 v115, v113, v93
	v_min_f32_e32 v93, 0, v115
	v_mul_f32_e64 v115, |v115|, s33
	v_exp_f32_e32 v115, v115
	s_nop 0
	v_add_f32_e32 v115, 1.0, v115
	v_log_f32_e32 v115, v115
	s_nop 0
	v_mul_f32_e32 v116, 0x3f317217, v115
	v_fma_f32 v116, v115, s36, -v116
	v_fmac_f32_e32 v116, 0x3377d1cf, v115
	v_fmac_f32_e32 v116, 0x3f317217, v115
	v_mov_b32_e32 v115, v116
	v_pk_add_f32 v[92:93], v[92:93], v[114:115] neg_lo:[0,1] neg_hi:[0,1]
	s_nop 0
	v_pk_mul_f32 v[114:115], v[92:93], s[50:51] op_sel_hi:[1,0]
	v_add_f32_e32 v93, v113, v94
	v_min_f32_e32 v92, 0, v93
	v_mul_f32_e64 v93, |v93|, s33
	v_exp_f32_e32 v93, v93
	s_nop 0
	v_add_f32_e32 v93, 1.0, v93
	v_log_f32_e32 v93, v93
	s_nop 0
	v_mul_f32_e32 v94, 0x3f317217, v93
	v_fma_f32 v94, v93, s36, -v94
	v_fmac_f32_e32 v94, 0x3377d1cf, v93
	v_fmac_f32_e32 v94, 0x3f317217, v93
	v_min_f32_e32 v93, 0, v95
	v_mul_f32_e64 v95, |v95|, s33
	v_exp_f32_e32 v95, v95
	s_nop 0
	v_add_f32_e32 v95, 1.0, v95
	v_log_f32_e32 v95, v95
	s_nop 0
	v_mul_f32_e32 v113, 0x3f317217, v95
	v_fma_f32 v113, v95, s36, -v113
	v_fmac_f32_e32 v113, 0x3377d1cf, v95
	v_fmac_f32_e32 v113, 0x3f317217, v95
	v_mov_b32_e32 v95, v113
	v_pk_add_f32 v[92:93], v[92:93], v[94:95] neg_lo:[0,1] neg_hi:[0,1]
	v_cvt_pk_bf16_f32 v94, v114, v115
	v_pk_mul_f32 v[116:117], v[92:93], s[50:51] op_sel_hi:[1,0]
	v_cvt_pk_bf16_f32 v92, v108, v109
	v_cvt_pk_bf16_f32 v93, v110, v111
	v_cvt_pk_bf16_f32 v95, v116, v117
	s_waitcnt vmcnt(1)
	v_mfma_f32_16x16x32_bf16 v[88:91], v[88:91], v[68:71], 0
	v_mfma_f32_16x16x32_bf16 v[80:83], v[80:83], v[68:71], 0
	s_waitcnt vmcnt(0)
	s_nop 5
	v_add_f32_e32 v108, v112, v88
	v_min_f32_e32 v88, 0, v108
	v_mul_f32_e64 v108, |v108|, s33
	v_exp_f32_e32 v108, v108
	v_add_f32_e32 v83, v112, v83
	v_add_f32_e32 v108, 1.0, v108
	v_log_f32_e32 v108, v108
	s_nop 0
	v_mul_f32_e32 v109, 0x3f317217, v108
	v_fma_f32 v109, v108, s36, -v109
	v_fmac_f32_e32 v109, 0x3377d1cf, v108
	v_fmac_f32_e32 v109, 0x3f317217, v108
	v_mov_b32_e32 v108, v109
	v_add_f32_e32 v109, v112, v89
	v_min_f32_e32 v89, 0, v109
	v_mul_f32_e64 v109, |v109|, s33
	v_exp_f32_e32 v109, v109
	s_nop 0
	v_add_f32_e32 v109, 1.0, v109
	v_log_f32_e32 v109, v109
	s_nop 0
	v_mul_f32_e32 v110, 0x3f317217, v109
	v_fma_f32 v110, v109, s36, -v110
	v_fmac_f32_e32 v110, 0x3377d1cf, v109
	v_fmac_f32_e32 v110, 0x3f317217, v109
	v_mov_b32_e32 v109, v110
	v_pk_add_f32 v[88:89], v[88:89], v[108:109] neg_lo:[0,1] neg_hi:[0,1]
	v_add_f32_e32 v108, v112, v90
	v_min_f32_e32 v90, 0, v108
	v_mul_f32_e64 v108, |v108|, s33
	v_exp_f32_e32 v108, v108
	v_pk_mul_f32 v[88:89], v[88:89], s[50:51] op_sel_hi:[1,0]
	v_add_f32_e32 v108, 1.0, v108
	v_log_f32_e32 v108, v108
	s_nop 0
	v_mul_f32_e32 v109, 0x3f317217, v108
	v_fma_f32 v109, v108, s36, -v109
	v_fmac_f32_e32 v109, 0x3377d1cf, v108
	v_fmac_f32_e32 v109, 0x3f317217, v108
	v_mov_b32_e32 v108, v109
	v_add_f32_e32 v109, v112, v91
	v_min_f32_e32 v91, 0, v109
	v_mul_f32_e64 v109, |v109|, s33
	v_exp_f32_e32 v109, v109
	s_nop 0
	v_add_f32_e32 v109, 1.0, v109
	v_log_f32_e32 v109, v109
	s_nop 0
	v_mul_f32_e32 v110, 0x3f317217, v109
	v_fma_f32 v110, v109, s36, -v110
	v_fmac_f32_e32 v110, 0x3377d1cf, v109
	v_fmac_f32_e32 v110, 0x3f317217, v109
	v_mov_b32_e32 v109, v110
	v_pk_add_f32 v[90:91], v[90:91], v[108:109] neg_lo:[0,1] neg_hi:[0,1]
	v_add_f32_e32 v108, v112, v80
	v_min_f32_e32 v80, 0, v108
	v_mul_f32_e64 v108, |v108|, s33
	v_exp_f32_e32 v108, v108
	v_pk_mul_f32 v[90:91], v[90:91], s[50:51] op_sel_hi:[1,0]
	v_add_f32_e32 v108, 1.0, v108
	v_log_f32_e32 v108, v108
	s_nop 0
	v_mul_f32_e32 v109, 0x3f317217, v108
	v_fma_f32 v109, v108, s36, -v109
	v_fmac_f32_e32 v109, 0x3377d1cf, v108
	v_fmac_f32_e32 v109, 0x3f317217, v108
	v_mov_b32_e32 v108, v109
	v_add_f32_e32 v109, v112, v81
	v_min_f32_e32 v81, 0, v109
	v_mul_f32_e64 v109, |v109|, s33
	v_exp_f32_e32 v109, v109
	s_nop 0
	v_add_f32_e32 v109, 1.0, v109
	v_log_f32_e32 v109, v109
	s_nop 0
	v_mul_f32_e32 v110, 0x3f317217, v109
	v_fma_f32 v110, v109, s36, -v110
	v_fmac_f32_e32 v110, 0x3377d1cf, v109
	v_fmac_f32_e32 v110, 0x3f317217, v109
	v_mov_b32_e32 v109, v110
	v_pk_add_f32 v[80:81], v[80:81], v[108:109] neg_lo:[0,1] neg_hi:[0,1]
	s_nop 0
	v_pk_mul_f32 v[108:109], v[80:81], s[50:51] op_sel_hi:[1,0]
	v_add_f32_e32 v81, v112, v82
	v_min_f32_e32 v80, 0, v81
	v_mul_f32_e64 v81, |v81|, s33
	v_exp_f32_e32 v81, v81
	s_nop 0
	v_add_f32_e32 v81, 1.0, v81
	v_log_f32_e32 v81, v81
	s_nop 0
	v_mul_f32_e32 v82, 0x3f317217, v81
	v_fma_f32 v82, v81, s36, -v82
	v_fmac_f32_e32 v82, 0x3377d1cf, v81
	v_fmac_f32_e32 v82, 0x3f317217, v81
	v_min_f32_e32 v81, 0, v83
	v_mul_f32_e64 v83, |v83|, s33
	v_exp_f32_e32 v83, v83
	s_nop 0
	v_add_f32_e32 v83, 1.0, v83
	v_log_f32_e32 v83, v83
	s_nop 0
	v_mul_f32_e32 v110, 0x3f317217, v83
	v_fma_f32 v110, v83, s36, -v110
	v_fmac_f32_e32 v110, 0x3377d1cf, v83
	v_fmac_f32_e32 v110, 0x3f317217, v83
	v_mov_b32_e32 v83, v110
	v_pk_add_f32 v[80:81], v[80:81], v[82:83] neg_lo:[0,1] neg_hi:[0,1]
	v_cvt_pk_bf16_f32 v82, v108, v109
	v_pk_mul_f32 v[110:111], v[80:81], s[50:51] op_sel_hi:[1,0]
	v_cvt_pk_bf16_f32 v80, v88, v89
	v_cvt_pk_bf16_f32 v81, v90, v91
	v_cvt_pk_bf16_f32 v83, v110, v111
	v_mfma_f32_16x16x32_bf16 v[72:75], v[72:75], v[68:71], 0
	v_mfma_f32_16x16x32_bf16 v[64:67], v[64:67], v[68:71], 0
	s_nop 6
; __device__ __forceinline__ f32x4 mfma16(bf16x8 a, bf16x8 b, f32x4 c) { return __builtin_amdgcn_mfma_f32_16x16x32_bf16(a, b, c, 0, 0, 0); }
; template <int MODE> __device__ void mixer_gla(const Params& p, int l, int n, LAS unsigned char* lds) {
;     ...
;                     for (int t2 = 0; t2 < 2; ++t2) { const f32x4 z = mfma16(lrf[2 * ks + t2], gwf[ef], zero4);
; #pragma unroll
;                         for (int r = 0; r < 4; ++r) { const float zz = z[r] + bgv[ef]; const float la = (fminf(zz, 0.f) - __logf(1.0f + __expf(-fabsf(zz)))) * (1.0f / 16.0f); la2[t2][r] = la; tot[ef] += la; } }
;                     laop[ef][ks] = pack8(la2[0], la2[1]); __builtin_amdgcn_sched_barrier(0); } }
;     ...
;             for (int tj = 0; tj < 4; ++tj)
; #pragma unroll
;                 for (int ks = 0; ks < 2; ++ks) { const bf16_t* rp = proj + (size_t)(t0 + 16 * tj + c) * DINP + 64 * h + 32 * ks + 8 * q; qn[tj][ks] = *(const bf16x8*)(rp + 1024); kn1[tj][ks] = *(const bf16x8*)(rp + 1280); }
;             __builtin_amdgcn_sched_barrier(0);
; #pragma unroll
;             for (int tj = 0; tj < 4; ++tj) {
;                 const int t = 16 * tj + c;
;                 bf16x8 mk[2];
; #pragma unroll
;                 for (int ks = 0; ks < 2; ++ks)
; #pragma unroll
;                     for (int jj = 0; jj < 8; ++jj) { const int sidx = SLOT(ks, q, jj); const bool on = dir == 0 ? sidx <= t : sidx >= t; mk[ks][jj] = on ? (short)0x3F80 : (short)0; }
	v_add_f32_e32 v88, v112, v72
	v_min_f32_e32 v72, 0, v88
	v_mul_f32_e64 v88, |v88|, s33
	v_exp_f32_e32 v88, v88
	v_add_f32_e32 v68, v112, v64
	v_min_f32_e32 v64, 0, v68
	v_mul_f32_e64 v68, |v68|, s33
	v_add_f32_e32 v88, 1.0, v88
	v_exp_f32_e32 v68, v68
	s_nop 0
	v_log_f32_e32 v88, v88
	v_add_f32_e32 v68, 1.0, v68
	v_mul_f32_e32 v89, 0x3f317217, v88
	v_fma_f32 v89, v88, s36, -v89
	v_fmac_f32_e32 v89, 0x3377d1cf, v88
	v_fmac_f32_e32 v89, 0x3f317217, v88
	v_mov_b32_e32 v88, v89
	v_add_f32_e32 v89, v112, v73
	v_min_f32_e32 v73, 0, v89
	v_mul_f32_e64 v89, |v89|, s33
	v_exp_f32_e32 v89, v89
	s_nop 0
	v_add_f32_e32 v89, 1.0, v89
	v_log_f32_e32 v89, v89
	s_nop 0
	v_mul_f32_e32 v90, 0x3f317217, v89
	v_fma_f32 v90, v89, s36, -v90
	v_fmac_f32_e32 v90, 0x3377d1cf, v89
	v_fmac_f32_e32 v90, 0x3f317217, v89
	v_mov_b32_e32 v89, v90
	v_pk_add_f32 v[72:73], v[72:73], v[88:89] neg_lo:[0,1] neg_hi:[0,1]
	v_add_f32_e32 v88, v112, v74
	v_min_f32_e32 v74, 0, v88
	v_mul_f32_e64 v88, |v88|, s33
	v_exp_f32_e32 v88, v88
	v_pk_mul_f32 v[72:73], v[72:73], s[50:51] op_sel_hi:[1,0]
	v_add_f32_e32 v88, 1.0, v88
	v_log_f32_e32 v88, v88
	s_nop 0
	v_mul_f32_e32 v89, 0x3f317217, v88
	v_fma_f32 v89, v88, s36, -v89
	v_fmac_f32_e32 v89, 0x3377d1cf, v88
	v_fmac_f32_e32 v89, 0x3f317217, v88
	v_mov_b32_e32 v88, v89
	v_add_f32_e32 v89, v112, v75
	v_min_f32_e32 v75, 0, v89
	v_mul_f32_e64 v89, |v89|, s33
	v_exp_f32_e32 v89, v89
	s_nop 0
	v_add_f32_e32 v89, 1.0, v89
	v_log_f32_e32 v89, v89
	s_nop 0
	v_mul_f32_e32 v90, 0x3f317217, v89
	v_fma_f32 v90, v89, s36, -v90
	v_fmac_f32_e32 v90, 0x3377d1cf, v89
	v_fmac_f32_e32 v90, 0x3f317217, v89
	v_mov_b32_e32 v89, v90
	v_pk_add_f32 v[74:75], v[74:75], v[88:89] neg_lo:[0,1] neg_hi:[0,1]
	v_log_f32_e32 v68, v68
	v_pk_mul_f32 v[74:75], v[74:75], s[50:51] op_sel_hi:[1,0]
	v_mul_f32_e32 v69, 0x3f317217, v68
	v_fma_f32 v69, v68, s36, -v69
	v_fmac_f32_e32 v69, 0x3377d1cf, v68
	v_fmac_f32_e32 v69, 0x3f317217, v68
	v_cvt_pk_bf16_f32 v113, v74, v75
	s_nop 0
	v_mov_b32_e32 v68, v69
	v_add_f32_e32 v69, v112, v65
	v_min_f32_e32 v65, 0, v69
	v_mul_f32_e64 v69, |v69|, s33
	v_exp_f32_e32 v69, v69
	s_nop 0
	v_add_f32_e32 v69, 1.0, v69
	v_log_f32_e32 v69, v69
	s_nop 0
	v_mul_f32_e32 v70, 0x3f317217, v69
	v_fma_f32 v70, v69, s36, -v70
	v_fmac_f32_e32 v70, 0x3377d1cf, v69
	v_fmac_f32_e32 v70, 0x3f317217, v69
	v_mov_b32_e32 v69, v70
	v_pk_add_f32 v[64:65], v[64:65], v[68:69] neg_lo:[0,1] neg_hi:[0,1]
	v_add_f32_e32 v68, v112, v66
	v_min_f32_e32 v66, 0, v68
	v_mul_f32_e64 v68, |v68|, s33
	v_exp_f32_e32 v68, v68
	v_pk_mul_f32 v[64:65], v[64:65], s[50:51] op_sel_hi:[1,0]
	v_add_f32_e32 v68, 1.0, v68
	v_cvt_pk_bf16_f32 v114, v64, v65
	s_nop 0
	v_log_f32_e32 v68, v68
	s_nop 0
	v_mul_f32_e32 v69, 0x3f317217, v68
	v_fma_f32 v69, v68, s36, -v69
	v_fmac_f32_e32 v69, 0x3377d1cf, v68
	v_fmac_f32_e32 v69, 0x3f317217, v68
	v_mov_b32_e32 v68, v69
	v_add_f32_e32 v69, v112, v67
	v_min_f32_e32 v67, 0, v69
	v_mul_f32_e64 v69, |v69|, s33
	v_exp_f32_e32 v69, v69
	v_cvt_pk_bf16_f32 v112, v72, v73
	v_add_f32_e32 v69, 1.0, v69
	v_log_f32_e32 v69, v69
	s_nop 0
	v_mul_f32_e32 v70, 0x3f317217, v69
	v_fma_f32 v70, v69, s36, -v70
	v_fmac_f32_e32 v70, 0x3377d1cf, v69
	v_fmac_f32_e32 v70, 0x3f317217, v69
	v_mov_b32_e32 v69, v70
	v_pk_add_f32 v[66:67], v[66:67], v[68:69] neg_lo:[0,1] neg_hi:[0,1]
	s_nop 0
	v_pk_mul_f32 v[66:67], v[66:67], s[50:51] op_sel_hi:[1,0]
	s_nop 0
	v_cvt_pk_bf16_f32 v115, v66, v67
	global_load_dwordx4 v[64:67], v[212:213], off offset:2048
	global_load_dwordx4 v[120:123], v[212:213], off offset:2112
	global_load_dwordx4 v[72:75], v[212:213], off offset:2560
	global_load_dwordx4 v[68:71], v[212:213], off offset:2624
	global_load_dwordx4 v[136:139], v[214:215], off offset:2048
	global_load_dwordx4 v[156:159], v[214:215], off offset:2112
	global_load_dwordx4 v[116:119], v[214:215], off offset:2560
	global_load_dwordx4 v[132:135], v[214:215], off offset:2624
	global_load_dwordx4 v[164:167], v[216:217], off offset:2048
	global_load_dwordx4 v[144:147], v[216:217], off offset:2112
	global_load_dwordx4 v[160:163], v[216:217], off offset:2560
	global_load_dwordx4 v[140:143], v[216:217], off offset:2624
	global_load_dwordx4 v[128:131], v[218:219], off offset:2048
	global_load_dwordx4 v[108:111], v[218:219], off offset:2112
	global_load_dwordx4 v[124:127], v[218:219], off offset:2560
	global_load_dwordx4 v[88:91], v[218:219], off offset:2624
	v_readlane_b32 s0, v255, 22
	v_readlane_b32 s1, v255, 23
	v_cndmask_b32_e64 v149, 0, 1, s[28:29]
	v_cndmask_b32_e64 v150, 0, 1, s[40:41]
	v_cndmask_b32_e64 v148, 0, 1, s[0:1]
	v_cndmask_b32_e64 v148, v149, v148, s[26:27]
	v_and_b32_e32 v148, 1, v148
	v_cmp_eq_u32_e64 s[16:17], 1, v148
	v_cndmask_b32_e64 v148, 0, 1, s[44:45]
	v_cndmask_b32_e64 v149, 0, 1, s[46:47]
	v_cndmask_b32_e64 v148, v149, v148, s[26:27]
	v_cndmask_b32_e64 v149, 0, 1, s[48:49]
	v_cndmask_b32_e64 v149, v150, v149, s[26:27]
	v_cndmask_b32_e64 v150, 0, 1, s[52:53]
	v_cndmask_b32_e64 v151, 0, 1, s[54:55]
	v_cndmask_b32_e64 v150, v151, v150, s[26:27]
	v_and_b32_e32 v148, 1, v148
	v_and_b32_e32 v149, 1, v149
	v_and_b32_e32 v150, 1, v150
	s_and_b64 s[0:1], s[26:27], exec
	v_cmp_eq_u32_e64 s[92:93], 1, v148
	v_cmp_eq_u32_e64 s[94:95], 1, v149
	v_cmp_eq_u32_e64 s[96:97], 1, v150
	s_cselect_b32 s0, 0, 0x3f80
	v_cndmask_b32_e64 v176, 0, v229, s[16:17]
	v_cndmask_b32_e64 v148, 0, v229, s[92:93]
	v_cndmask_b32_e64 v149, 0, v229, s[94:95]
	v_cndmask_b32_e64 v150, 0, v229, s[96:97]
	s_pack_ll_b32_b16 s4, s0, s0
	v_perm_b32 v148, v148, v176, s3
	v_perm_b32 v149, v150, v149, s3
	v_mov_b32_e32 v150, s4
	v_mov_b32_e32 v151, s4
	s_mov_b32 s6, s4
	s_mov_b32 s7, s4
	v_mfma_f32_16x16x32_bf16 v[152:155], v[76:79], v[148:151], 0
	s_mov_b32 s5, s4
	v_mov_b64_e32 v[170:171], s[6:7]
	v_mov_b64_e32 v[168:169], s[4:5]
	s_waitcnt vmcnt(15)
; __device__ __forceinline__ float bf2f(bf16_t b) { return __uint_as_float(((unsigned)b) << 16); }
; __device__ __forceinline__ f32x4 mfma16(bf16x8 a, bf16x8 b, f32x4 c) { return __builtin_amdgcn_mfma_f32_16x16x32_bf16(a, b, c, 0, 0, 0); }
; template <int MODE> __device__ void mixer_gla(const Params& p, int l, int n, LAS unsigned char* lds) {
;     ...
;             for (int tj = 0; tj < 4; ++tj) {
;                 const int t = 16 * tj + c;
;                 bf16x8 mk[2];
; #pragma unroll
;                 for (int ks = 0; ks < 2; ++ks)
; #pragma unroll
;                     for (int jj = 0; jj < 8; ++jj) { const int sidx = SLOT(ks, q, jj); const bool on = dir == 0 ? sidx <= t : sidx >= t; mk[ks][jj] = on ? (short)0x3F80 : (short)0; }
; #pragma unroll
;                 for (int ks2 = 0; ks2 < 2; ++ks2) { f32x4 qe2[2], ke2[2];
; #pragma unroll
;                     for (int e2 = 0; e2 < 2; ++e2) { const int ef = 2 * ks2 + e2;
;                         f32x4 b = mfma16(laop[ef][0], mk[0], zero4); b = mfma16(laop[ef][1], mk[1], b);
; #pragma unroll
;                         for (int r = 0; r < 4; ++r) { qe2[e2][r] = bf2f((bf16_t)qn[tj][ks2][4 * e2 + r]) * 0.125f * __expf(b[r]); ke2[e2][r] = bf2f((bf16_t)kn1[tj][ks2][4 * e2 + r]) * __expf(-b[r]); } }
;                     QEop[tj][ks2] = pack8(qe2[0], qe2[1]); KEop[tj][ks2] = pack8(ke2[0], ke2[1]); }
	v_and_b32_e32 v175, 0xffff0000, v64
	v_lshlrev_b32_e32 v174, 16, v64
	v_mfma_f32_16x16x32_bf16 v[152:155], v[84:87], v[168:171], v[152:155]
	v_mul_f32_e64 v174, v174, s24
	v_mul_f32_e64 v175, v175, s24
	v_and_b32_e32 v179, 0xffff0000, v65
	v_lshlrev_b32_e32 v178, 16, v65
	v_pk_mul_f32 v[178:179], v[178:179], s[24:25] op_sel_hi:[1,0]
	s_waitcnt vmcnt(13)
	v_and_b32_e32 v181, 0xffff0000, v73
	s_nop 0
	v_mul_f32_e32 v172, 0x3fb8aa3b, v152
	v_mul_f32_e32 v173, 0x3fb8aa3b, v153
	v_exp_f32_e32 v172, v172
	v_mul_f32_e32 v152, 0xbfb8aa3b, v152
	v_exp_f32_e32 v173, v173
	v_mul_f32_e32 v64, 0xbfb8aa3b, v153
	v_exp_f32_e32 v152, v152
	v_exp_f32_e32 v153, v64
	v_pk_mul_f32 v[172:173], v[174:175], v[172:173]
	v_and_b32_e32 v175, 0xffff0000, v72
	v_lshlrev_b32_e32 v174, 16, v72
	v_mul_f32_e32 v64, 0x3fb8aa3b, v154
	v_mul_f32_e32 v72, 0x3fb8aa3b, v155
	v_pk_mul_f32 v[174:175], v[152:153], v[174:175]
	v_exp_f32_e32 v152, v64
	v_exp_f32_e32 v153, v72
	v_mul_f32_e32 v64, 0xbfb8aa3b, v154
	v_mul_f32_e32 v65, 0xbfb8aa3b, v155
	v_exp_f32_e32 v64, v64
	v_pk_mul_f32 v[178:179], v[178:179], v[152:153]
	v_mfma_f32_16x16x32_bf16 v[152:155], v[96:99], v[148:151], 0
	v_exp_f32_e32 v65, v65
	v_lshlrev_b32_e32 v180, 16, v73
	v_and_b32_e32 v189, 0xffff0000, v66
	v_mfma_f32_16x16x32_bf16 v[152:155], v[100:103], v[168:171], v[152:155]
	v_mul_f32_e64 v180, v64, v180
	v_mul_f32_e64 v181, v65, v181
	v_lshlrev_b32_e32 v188, 16, v66
	v_pk_mul_f32 v[188:189], v[188:189], s[24:25] op_sel_hi:[1,0]
	s_nop 3
	v_mul_f32_e32 v65, 0xbfb8aa3b, v152
	v_mul_f32_e32 v64, 0x3fb8aa3b, v152
	v_exp_f32_e32 v72, v65
	v_mul_f32_e32 v65, 0x3fb8aa3b, v153
	v_exp_f32_e32 v64, v64
	v_exp_f32_e32 v65, v65
	v_mul_f32_e32 v66, 0xbfb8aa3b, v153
	v_exp_f32_e32 v73, v66
	v_pk_mul_f32 v[152:153], v[188:189], v[64:65]
	v_and_b32_e32 v65, 0xffff0000, v74
	v_lshlrev_b32_e32 v64, 16, v74
	v_pk_mul_f32 v[188:189], v[72:73], v[64:65]
	v_mul_f32_e32 v65, 0xbfb8aa3b, v154
	v_mul_f32_e32 v64, 0x3fb8aa3b, v154
	v_exp_f32_e32 v66, v65
	v_mul_f32_e32 v65, 0x3fb8aa3b, v155
	v_exp_f32_e32 v64, v64
	v_exp_f32_e32 v65, v65
	v_and_b32_e32 v73, 0xffff0000, v67
	v_lshlrev_b32_e32 v72, 16, v67
	v_mul_f32_e32 v67, 0xbfb8aa3b, v155
	v_exp_f32_e32 v67, v67
	v_pk_mul_f32 v[72:73], v[72:73], s[24:25] op_sel_hi:[1,0]
	v_cvt_pk_bf16_f32 v74, v188, v189
	v_pk_mul_f32 v[72:73], v[72:73], v[64:65]
	v_and_b32_e32 v65, 0xffff0000, v75
	v_lshlrev_b32_e32 v64, 16, v75
	v_pk_mul_f32 v[190:191], v[66:67], v[64:65]
	v_cvt_pk_bf16_f32 v66, v152, v153
	v_mfma_f32_16x16x32_bf16 v[152:155], v[104:107], v[148:151], 0
	v_cvt_pk_bf16_f32 v64, v172, v173
	v_cvt_pk_bf16_f32 v67, v72, v73
	v_cvt_pk_bf16_f32 v72, v174, v175
	v_mfma_f32_16x16x32_bf16 v[152:155], v[92:95], v[168:171], v[152:155]
	v_and_b32_e32 v175, 0xffff0000, v120
	v_lshlrev_b32_e32 v174, 16, v120
	v_pk_mul_f32 v[174:175], v[174:175], s[24:25] op_sel_hi:[1,0]
	v_cvt_pk_bf16_f32 v65, v178, v179
	v_and_b32_e32 v179, 0xffff0000, v121
	s_nop 2
	v_mul_f32_e32 v172, 0x3fb8aa3b, v152
	v_mul_f32_e32 v173, 0x3fb8aa3b, v153
	v_exp_f32_e32 v172, v172
	v_mul_f32_e32 v152, 0xbfb8aa3b, v152
	v_exp_f32_e32 v173, v173
	v_mul_f32_e32 v120, 0xbfb8aa3b, v153
	v_exp_f32_e32 v152, v152
	v_exp_f32_e32 v153, v120
	v_pk_mul_f32 v[172:173], v[174:175], v[172:173]
	s_waitcnt vmcnt(12)
	v_and_b32_e32 v175, 0xffff0000, v68
	v_lshlrev_b32_e32 v174, 16, v68
	v_mul_f32_e32 v68, 0x3fb8aa3b, v154
	v_pk_mul_f32 v[174:175], v[152:153], v[174:175]
	v_exp_f32_e32 v152, v68
	v_mul_f32_e32 v68, 0xbfb8aa3b, v154
	v_exp_f32_e32 v120, v68
	v_mul_f32_e32 v68, 0x3fb8aa3b, v155
	v_exp_f32_e32 v153, v68
	v_lshlrev_b32_e32 v178, 16, v121
	v_pk_mul_f32 v[178:179], v[178:179], s[24:25] op_sel_hi:[1,0]
	v_mul_f32_e32 v68, 0xbfb8aa3b, v155
	v_pk_mul_f32 v[178:179], v[178:179], v[152:153]
	v_mfma_f32_16x16x32_bf16 v[152:155], v[80:83], v[148:151], 0
	v_exp_f32_e32 v121, v68
	v_and_b32_e32 v149, 0xffff0000, v69
	v_lshlrev_b32_e32 v148, 16, v69
	v_mfma_f32_16x16x32_bf16 v[152:155], v[112:115], v[168:171], v[152:155]
	v_mul_f32_e64 v148, v120, v148
	v_mul_f32_e64 v149, v121, v149
	v_cvt_pk_bf16_f32 v73, v180, v181
	v_and_b32_e32 v181, 0xffff0000, v122
	v_lshlrev_b32_e32 v180, 16, v122
	v_pk_mul_f32 v[180:181], v[180:181], s[24:25] op_sel_hi:[1,0]
	s_nop 1
	v_mul_f32_e32 v69, 0xbfb8aa3b, v152
	v_mul_f32_e32 v68, 0x3fb8aa3b, v152
	v_exp_f32_e32 v120, v69
	v_mul_f32_e32 v69, 0x3fb8aa3b, v153
	v_exp_f32_e32 v68, v68
	v_exp_f32_e32 v69, v69
	v_mul_f32_e32 v121, 0xbfb8aa3b, v153
	v_exp_f32_e32 v121, v121
	v_and_b32_e32 v189, 0xffff0000, v123
	v_pk_mul_f32 v[152:153], v[180:181], v[68:69]
	v_and_b32_e32 v69, 0xffff0000, v70
	v_lshlrev_b32_e32 v68, 16, v70
	v_pk_mul_f32 v[180:181], v[120:121], v[68:69]
	v_mul_f32_e32 v69, 0xbfb8aa3b, v154
	v_mul_f32_e32 v68, 0x3fb8aa3b, v154
	v_exp_f32_e32 v120, v69
	v_mul_f32_e32 v69, 0x3fb8aa3b, v155
	v_exp_f32_e32 v68, v68
	v_exp_f32_e32 v69, v69
	v_mul_f32_e32 v70, 0xbfb8aa3b, v155
	v_exp_f32_e32 v121, v70
	v_lshlrev_b32_e32 v188, 16, v123
	v_pk_mul_f32 v[122:123], v[188:189], s[24:25] op_sel_hi:[1,0]
	v_cvt_pk_bf16_f32 v75, v190, v191
	v_pk_mul_f32 v[122:123], v[122:123], v[68:69]
	v_and_b32_e32 v69, 0xffff0000, v71
	v_lshlrev_b32_e32 v68, 16, v71
	v_pk_mul_f32 v[154:155], v[120:121], v[68:69]
	v_cvt_pk_bf16_f32 v68, v172, v173
	v_cvt_pk_bf16_f32 v69, v178, v179
	v_cvt_pk_bf16_f32 v70, v152, v153
	v_cvt_pk_bf16_f32 v71, v122, v123
	v_cvt_pk_bf16_f32 v120, v174, v175
	v_cvt_pk_bf16_f32 v121, v148, v149
	v_cvt_pk_bf16_f32 v122, v180, v181
	v_cvt_pk_bf16_f32 v123, v154, v155
	v_cndmask_b32_e64 v148, 0, 1, s[56:57]
	v_cndmask_b32_e64 v149, 0, 1, s[58:59]
	v_cndmask_b32_e64 v148, v149, v148, s[26:27]
	v_and_b32_e32 v148, 1, v148
	v_cmp_eq_u32_e64 s[20:21], 1, v148
	v_cndmask_b32_e64 v149, 0, 1, s[62:63]
	v_cndmask_b32_e64 v151, 0, 1, s[66:67]
	v_cndmask_b32_e64 v148, 0, v229, s[20:21]
	v_perm_b32 v154, v148, v176, s3
	v_cndmask_b32_e64 v148, 0, 1, s[60:61]
	v_cndmask_b32_e64 v148, v149, v148, s[26:27]
	v_cndmask_b32_e64 v149, 0, 1, s[64:65]
	v_cndmask_b32_e64 v149, v151, v149, s[26:27]
	v_and_b32_e32 v148, 1, v148
	v_and_b32_e32 v149, 1, v149
	s_cselect_b32 s0, 0x3f80, 0
	v_cmp_eq_u32_e64 s[4:5], 1, v148
	v_cmp_eq_u32_e64 s[6:7], 1, v149
	s_pack_ll_b32_b16 s12, s0, s0
	v_cndmask_b32_e64 v148, 0, v229, s[4:5]
	v_cndmask_b32_e64 v149, 0, v229, s[6:7]
	v_perm_b32 v155, v149, v148, s3
	v_mov_b32_e32 v152, s12
	v_mov_b32_e32 v153, s12
	s_waitcnt vmcnt(11)
; __device__ __forceinline__ float bf2f(bf16_t b) { return __uint_as_float(((unsigned)b) << 16); }
; __device__ __forceinline__ f32x4 mfma16(bf16x8 a, bf16x8 b, f32x4 c) { return __builtin_amdgcn_mfma_f32_16x16x32_bf16(a, b, c, 0, 0, 0); }
; template <int MODE> __device__ void mixer_gla(const Params& p, int l, int n, LAS unsigned char* lds) {
;     ...
;             for (int tj = 0; tj < 4; ++tj) {
;                 const int t = 16 * tj + c;
;                 bf16x8 mk[2];
; #pragma unroll
;                 for (int ks = 0; ks < 2; ++ks)
; #pragma unroll
;                     for (int jj = 0; jj < 8; ++jj) { const int sidx = SLOT(ks, q, jj); const bool on = dir == 0 ? sidx <= t : sidx >= t; mk[ks][jj] = on ? (short)0x3F80 : (short)0; }
; #pragma unroll
;                 for (int ks2 = 0; ks2 < 2; ++ks2) { f32x4 qe2[2], ke2[2];
; #pragma unroll
;                     for (int e2 = 0; e2 < 2; ++e2) { const int ef = 2 * ks2 + e2;
;                         f32x4 b = mfma16(laop[ef][0], mk[0], zero4); b = mfma16(laop[ef][1], mk[1], b);
; #pragma unroll
;                         for (int r = 0; r < 4; ++r) { qe2[e2][r] = bf2f((bf16_t)qn[tj][ks2][4 * e2 + r]) * 0.125f * __expf(b[r]); ke2[e2][r] = bf2f((bf16_t)kn1[tj][ks2][4 * e2 + r]) * __expf(-b[r]); } }
;                     QEop[tj][ks2] = pack8(qe2[0], qe2[1]); KEop[tj][ks2] = pack8(ke2[0], ke2[1]); }
	v_and_b32_e32 v179, 0xffff0000, v136
	v_lshlrev_b32_e32 v178, 16, v136
	v_mfma_f32_16x16x32_bf16 v[172:175], v[76:79], v[152:155], 0
	v_mul_f32_e64 v178, v178, s24
	v_mul_f32_e64 v179, v179, s24
	v_and_b32_e32 v181, 0xffff0000, v137
	v_lshlrev_b32_e32 v180, 16, v137
	v_mfma_f32_16x16x32_bf16 v[172:175], v[84:87], v[168:171], v[172:175]
	v_mul_f32_e64 v180, v180, s24
	v_mul_f32_e64 v181, v181, s24
	s_waitcnt vmcnt(9)
	v_and_b32_e32 v189, 0xffff0000, v117
	v_lshlrev_b32_e32 v188, 16, v117
	v_and_b32_e32 v191, 0xffff0000, v138
	v_lshlrev_b32_e32 v190, 16, v138
	s_nop 0
	v_mul_f32_e32 v149, 0xbfb8aa3b, v172
	v_mul_f32_e32 v148, 0x3fb8aa3b, v172
	v_exp_f32_e32 v172, v149
	v_mul_f32_e32 v149, 0x3fb8aa3b, v173
	v_exp_f32_e32 v148, v148
	v_exp_f32_e32 v149, v149
	v_mul_f32_e32 v136, 0xbfb8aa3b, v173
	v_exp_f32_e32 v173, v136
	v_pk_mul_f32 v[190:191], v[190:191], s[24:25] op_sel_hi:[1,0]
	v_pk_mul_f32 v[148:149], v[178:179], v[148:149]
	v_and_b32_e32 v179, 0xffff0000, v116
	v_lshlrev_b32_e32 v178, 16, v116
	v_mul_f32_e32 v116, 0x3fb8aa3b, v174
	v_pk_mul_f32 v[178:179], v[172:173], v[178:179]
	v_exp_f32_e32 v172, v116
	v_mul_f32_e32 v116, 0xbfb8aa3b, v174
	v_exp_f32_e32 v136, v116
	v_mul_f32_e32 v116, 0x3fb8aa3b, v175
	v_exp_f32_e32 v173, v116
	v_mul_f32_e32 v116, 0xbfb8aa3b, v175
	v_exp_f32_e32 v137, v116
	v_and_b32_e32 v247, 0xffff0000, v139
	v_pk_mul_f32 v[180:181], v[180:181], v[172:173]
	v_mfma_f32_16x16x32_bf16 v[172:175], v[96:99], v[152:155], 0
	v_mul_f32_e64 v188, v136, v188
	v_mul_f32_e64 v189, v137, v189
	v_lshlrev_b32_e32 v246, 16, v139
	v_pk_mul_f32 v[138:139], v[246:247], s[24:25] op_sel_hi:[1,0]
	v_mfma_f32_16x16x32_bf16 v[172:175], v[100:103], v[168:171], v[172:175]
	s_nop 7
	v_mul_f32_e32 v117, 0xbfb8aa3b, v172
	v_mul_f32_e32 v116, 0x3fb8aa3b, v172
	v_exp_f32_e32 v136, v117
	v_mul_f32_e32 v117, 0x3fb8aa3b, v173
	v_exp_f32_e32 v116, v116
	v_exp_f32_e32 v117, v117
	v_mul_f32_e32 v137, 0xbfb8aa3b, v173
	v_exp_f32_e32 v137, v137
	v_pk_mul_f32 v[172:173], v[190:191], v[116:117]
	v_and_b32_e32 v117, 0xffff0000, v118
	v_lshlrev_b32_e32 v116, 16, v118
	v_pk_mul_f32 v[190:191], v[136:137], v[116:117]
	v_mul_f32_e32 v117, 0xbfb8aa3b, v174
	v_mul_f32_e32 v118, 0xbfb8aa3b, v175
	v_mul_f32_e32 v116, 0x3fb8aa3b, v174
	v_exp_f32_e32 v136, v117
	v_mul_f32_e32 v117, 0x3fb8aa3b, v175
	v_exp_f32_e32 v137, v118
	v_cvt_pk_bf16_f32 v118, v172, v173
	v_mfma_f32_16x16x32_bf16 v[172:175], v[104:107], v[152:155], 0
	v_exp_f32_e32 v116, v116
	v_exp_f32_e32 v117, v117
	v_mfma_f32_16x16x32_bf16 v[172:175], v[92:95], v[168:171], v[172:175]
	v_mul_f32_e64 v138, v138, v116
	v_mul_f32_e64 v139, v139, v117
	v_and_b32_e32 v117, 0xffff0000, v119
	v_lshlrev_b32_e32 v116, 16, v119
	v_pk_mul_f32 v[246:247], v[136:137], v[116:117]
	v_cvt_pk_bf16_f32 v116, v148, v149
	s_nop 1
	v_mul_f32_e32 v149, 0xbfb8aa3b, v172
	v_mul_f32_e32 v148, 0x3fb8aa3b, v172
	v_exp_f32_e32 v172, v149
	v_mul_f32_e32 v149, 0x3fb8aa3b, v173
	v_exp_f32_e32 v148, v148
	v_exp_f32_e32 v149, v149
	v_mul_f32_e32 v151, 0xbfb8aa3b, v173
	v_exp_f32_e32 v173, v151
	v_cvt_pk_bf16_f32 v136, v178, v179
	v_and_b32_e32 v179, 0xffff0000, v156
	v_lshlrev_b32_e32 v178, 16, v156
	v_pk_mul_f32 v[178:179], v[178:179], s[24:25] op_sel_hi:[1,0]
	v_cvt_pk_bf16_f32 v117, v180, v181
	v_pk_mul_f32 v[148:149], v[178:179], v[148:149]
	s_waitcnt vmcnt(8)
	v_and_b32_e32 v179, 0xffff0000, v132
	v_lshlrev_b32_e32 v178, 16, v132
	v_mul_f32_e32 v132, 0x3fb8aa3b, v174
	v_pk_mul_f32 v[172:173], v[172:173], v[178:179]
	v_exp_f32_e32 v178, v132
	v_mul_f32_e32 v132, 0xbfb8aa3b, v174
	v_exp_f32_e32 v174, v132
	v_mul_f32_e32 v132, 0x3fb8aa3b, v175
	v_exp_f32_e32 v179, v132
	v_and_b32_e32 v181, 0xffff0000, v157
	v_lshlrev_b32_e32 v180, 16, v157
	v_pk_mul_f32 v[156:157], v[180:181], s[24:25] op_sel_hi:[1,0]
	v_mul_f32_e32 v132, 0xbfb8aa3b, v175
	v_pk_mul_f32 v[178:179], v[156:157], v[178:179]
	v_mfma_f32_16x16x32_bf16 v[154:157], v[80:83], v[152:155], 0
	v_and_b32_e32 v181, 0xffff0000, v133
	v_lshlrev_b32_e32 v180, 16, v133
	v_exp_f32_e32 v175, v132
	v_mfma_f32_16x16x32_bf16 v[154:157], v[112:115], v[168:171], v[154:157]
	v_and_b32_e32 v169, 0xffff0000, v158
	v_lshlrev_b32_e32 v168, 16, v158
	v_pk_mul_f32 v[168:169], v[168:169], s[24:25] op_sel_hi:[1,0]
	v_and_b32_e32 v171, 0xffff0000, v159
	v_lshlrev_b32_e32 v170, 16, v159
	s_nop 2
	v_mul_f32_e32 v133, 0xbfb8aa3b, v154
	v_mul_f32_e32 v132, 0x3fb8aa3b, v154
	v_exp_f32_e32 v154, v133
	v_mul_f32_e32 v133, 0x3fb8aa3b, v155
	v_exp_f32_e32 v132, v132
	v_exp_f32_e32 v133, v133
	v_mul_f32_e32 v151, 0xbfb8aa3b, v155
	v_exp_f32_e32 v155, v151
	v_pk_mul_f32 v[158:159], v[170:171], s[24:25] op_sel_hi:[1,0]
	v_pk_mul_f32 v[168:169], v[168:169], v[132:133]
	v_and_b32_e32 v133, 0xffff0000, v134
	v_lshlrev_b32_e32 v132, 16, v134
	v_pk_mul_f32 v[154:155], v[154:155], v[132:133]
	v_mul_f32_e32 v133, 0xbfb8aa3b, v156
	v_mul_f32_e32 v132, 0x3fb8aa3b, v156
	v_exp_f32_e32 v156, v133
	v_mul_f32_e32 v133, 0x3fb8aa3b, v157
	v_exp_f32_e32 v132, v132
	v_exp_f32_e32 v133, v133
	v_mul_f32_e32 v134, 0xbfb8aa3b, v157
	v_exp_f32_e32 v157, v134
	v_pk_mul_f32 v[174:175], v[174:175], v[180:181]
	v_pk_mul_f32 v[158:159], v[158:159], v[132:133]
	v_and_b32_e32 v133, 0xffff0000, v135
	v_lshlrev_b32_e32 v132, 16, v135
	v_pk_mul_f32 v[170:171], v[156:157], v[132:133]
	v_cvt_pk_bf16_f32 v119, v138, v139
	v_cvt_pk_bf16_f32 v137, v188, v189
	v_cvt_pk_bf16_f32 v138, v190, v191
	v_cvt_pk_bf16_f32 v139, v246, v247
	v_cvt_pk_bf16_f32 v132, v148, v149
	v_cvt_pk_bf16_f32 v133, v178, v179
	v_cvt_pk_bf16_f32 v134, v168, v169
	v_cvt_pk_bf16_f32 v135, v158, v159
	v_cvt_pk_bf16_f32 v156, v172, v173
	v_cvt_pk_bf16_f32 v157, v174, v175
	v_cvt_pk_bf16_f32 v158, v154, v155
	v_cvt_pk_bf16_f32 v159, v170, v171
	v_cndmask_b32_e64 v148, 0, 1, s[68:69]
	v_cndmask_b32_e64 v149, 0, 1, s[70:71]
	v_cndmask_b32_e64 v148, v149, v148, s[26:27]
	v_cndmask_b32_e64 v149, 0, 1, s[72:73]
	v_cndmask_b32_e64 v151, 0, 1, s[74:75]
	s_mov_b32 s14, s12
	s_mov_b32 s15, s12
	v_cndmask_b32_e64 v149, v151, v149, s[26:27]
	v_cndmask_b32_e64 v151, 0, 1, s[76:77]
	v_cndmask_b32_e64 v153, 0, 1, s[78:79]
	s_mov_b32 s13, s12
	v_mov_b64_e32 v[248:249], s[14:15]
	v_cndmask_b32_e64 v151, v153, v151, s[26:27]
	v_mov_b64_e32 v[246:247], s[12:13]
	v_and_b32_e32 v148, 1, v148
	v_and_b32_e32 v149, 1, v149
	v_and_b32_e32 v151, 1, v151
	v_mfma_f32_16x16x32_bf16 v[168:171], v[76:79], v[246:249], 0
	v_cmp_eq_u32_e64 s[8:9], 1, v148
	v_cmp_eq_u32_e64 s[10:11], 1, v149
	v_cmp_eq_u32_e64 s[12:13], 1, v151
	v_cndmask_b32_e64 v148, 0, v229, s[8:9]
	v_cndmask_b32_e64 v149, 0, v229, s[10:11]
	v_cndmask_b32_e64 v76, 0, v229, s[12:13]
	v_perm_b32 v148, v148, v176, s3
	v_perm_b32 v149, v76, v149, s3
	v_mov_b32_e32 v151, v150
	s_waitcnt vmcnt(7)
; __device__ __forceinline__ float bf2f(bf16_t b) { return __uint_as_float(((unsigned)b) << 16); }
; __device__ __forceinline__ f32x4 mfma16(bf16x8 a, bf16x8 b, f32x4 c) { return __builtin_amdgcn_mfma_f32_16x16x32_bf16(a, b, c, 0, 0, 0); }
; template <int MODE> __device__ void mixer_gla(const Params& p, int l, int n, LAS unsigned char* lds) {
;     ...
;             for (int tj = 0; tj < 4; ++tj) {
;                 const int t = 16 * tj + c;
;                 bf16x8 mk[2];
; #pragma unroll
;                 for (int ks = 0; ks < 2; ++ks)
; #pragma unroll
;                     for (int jj = 0; jj < 8; ++jj) { const int sidx = SLOT(ks, q, jj); const bool on = dir == 0 ? sidx <= t : sidx >= t; mk[ks][jj] = on ? (short)0x3F80 : (short)0; }
; #pragma unroll
;                 for (int ks2 = 0; ks2 < 2; ++ks2) { f32x4 qe2[2], ke2[2];
; #pragma unroll
;                     for (int e2 = 0; e2 < 2; ++e2) { const int ef = 2 * ks2 + e2;
;                         f32x4 b = mfma16(laop[ef][0], mk[0], zero4); b = mfma16(laop[ef][1], mk[1], b);
; #pragma unroll
;                         for (int r = 0; r < 4; ++r) { qe2[e2][r] = bf2f((bf16_t)qn[tj][ks2][4 * e2 + r]) * 0.125f * __expf(b[r]); ke2[e2][r] = bf2f((bf16_t)kn1[tj][ks2][4 * e2 + r]) * __expf(-b[r]); } }
;                     QEop[tj][ks2] = pack8(qe2[0], qe2[1]); KEop[tj][ks2] = pack8(ke2[0], ke2[1]); }
	v_and_b32_e32 v173, 0xffff0000, v164
	v_lshlrev_b32_e32 v172, 16, v164
	v_mfma_f32_16x16x32_bf16 v[76:79], v[84:87], v[148:151], v[168:171]
	v_mul_f32_e64 v172, v172, s24
	v_mul_f32_e64 v173, v173, s24
	s_nop 5
	v_mul_f32_e32 v153, 0x3fb8aa3b, v76
	v_exp_f32_e32 v154, v153
	v_mul_f32_e32 v153, 0x3fb8aa3b, v77
	v_mul_f32_e32 v76, 0xbfb8aa3b, v76
	v_exp_f32_e32 v155, v153
	v_mul_f32_e32 v77, 0xbfb8aa3b, v77
	v_exp_f32_e32 v76, v76
	v_exp_f32_e32 v77, v77
	v_pk_mul_f32 v[154:155], v[172:173], v[154:155]
	s_waitcnt vmcnt(5)
	v_and_b32_e32 v173, 0xffff0000, v160
	v_lshlrev_b32_e32 v172, 16, v160
	v_pk_mul_f32 v[178:179], v[76:77], v[172:173]
	v_mul_f32_e32 v77, 0xbfb8aa3b, v78
	v_mul_f32_e32 v76, 0x3fb8aa3b, v78
	v_exp_f32_e32 v78, v77
	v_mul_f32_e32 v77, 0x3fb8aa3b, v79
	v_exp_f32_e32 v76, v76
	v_exp_f32_e32 v77, v77
	v_and_b32_e32 v173, 0xffff0000, v165
	v_lshlrev_b32_e32 v172, 16, v165
	v_pk_mul_f32 v[164:165], v[172:173], s[24:25] op_sel_hi:[1,0]
	v_mfma_f32_16x16x32_bf16 v[172:175], v[96:99], v[246:249], 0
	v_mul_f32_e64 v164, v164, v76
	v_mul_f32_e64 v165, v165, v77
	v_mul_f32_e32 v76, 0xbfb8aa3b, v79
	v_exp_f32_e32 v79, v76
	v_and_b32_e32 v77, 0xffff0000, v161
	v_lshlrev_b32_e32 v76, 16, v161
	v_and_b32_e32 v161, 0xffff0000, v166
	v_pk_mul_f32 v[98:99], v[78:79], v[76:77]
	v_mfma_f32_16x16x32_bf16 v[76:79], v[100:103], v[148:151], v[172:175]
	v_lshlrev_b32_e32 v160, 16, v166
	v_pk_mul_f32 v[160:161], v[160:161], s[24:25] op_sel_hi:[1,0]
	s_nop 5
	v_mul_f32_e32 v96, 0x3fb8aa3b, v76
	v_mul_f32_e32 v97, 0x3fb8aa3b, v77
	v_exp_f32_e32 v96, v96
	v_mul_f32_e32 v76, 0xbfb8aa3b, v76
	v_exp_f32_e32 v97, v97
	v_mul_f32_e32 v77, 0xbfb8aa3b, v77
	v_exp_f32_e32 v76, v76
	v_exp_f32_e32 v77, v77
	v_pk_mul_f32 v[96:97], v[160:161], v[96:97]
	v_and_b32_e32 v161, 0xffff0000, v162
	v_lshlrev_b32_e32 v160, 16, v162
	v_pk_mul_f32 v[180:181], v[76:77], v[160:161]
	v_mul_f32_e32 v77, 0xbfb8aa3b, v78
	v_mul_f32_e32 v76, 0x3fb8aa3b, v78
	v_exp_f32_e32 v78, v77
	v_mul_f32_e32 v77, 0x3fb8aa3b, v79
	v_exp_f32_e32 v76, v76
	v_exp_f32_e32 v77, v77
	v_mul_f32_e32 v79, 0xbfb8aa3b, v79
	v_exp_f32_e32 v79, v79
	v_and_b32_e32 v161, 0xffff0000, v167
	v_lshlrev_b32_e32 v160, 16, v167
	v_pk_mul_f32 v[160:161], v[160:161], s[24:25] op_sel_hi:[1,0]
	s_nop 0
	v_pk_mul_f32 v[160:161], v[160:161], v[76:77]
	v_and_b32_e32 v77, 0xffff0000, v163
	v_lshlrev_b32_e32 v76, 16, v163
	v_pk_mul_f32 v[166:167], v[78:79], v[76:77]
	v_cvt_pk_bf16_f32 v79, v160, v161
	v_mfma_f32_16x16x32_bf16 v[160:163], v[104:107], v[246:249], 0
	v_cvt_pk_bf16_f32 v76, v154, v155
	v_cvt_pk_bf16_f32 v77, v164, v165
	v_and_b32_e32 v165, 0xffff0000, v144
	v_mfma_f32_16x16x32_bf16 v[104:107], v[92:95], v[148:151], v[160:163]
	v_lshlrev_b32_e32 v164, 16, v144
	v_pk_mul_f32 v[164:165], v[164:165], s[24:25] op_sel_hi:[1,0]
	v_cvt_pk_bf16_f32 v78, v96, v97
	v_cvt_pk_bf16_f32 v97, v98, v99
	v_cvt_pk_bf16_f32 v99, v166, v167
	s_nop 2
	v_mul_f32_e32 v153, 0x3fb8aa3b, v104
	v_exp_f32_e32 v154, v153
	v_mul_f32_e32 v153, 0x3fb8aa3b, v105
	v_mul_f32_e32 v104, 0xbfb8aa3b, v104
	v_exp_f32_e32 v155, v153
	v_mul_f32_e32 v105, 0xbfb8aa3b, v105
	v_exp_f32_e32 v104, v104
	v_exp_f32_e32 v105, v105
	v_pk_mul_f32 v[154:155], v[164:165], v[154:155]
	s_waitcnt vmcnt(4)
	v_and_b32_e32 v165, 0xffff0000, v140
	v_lshlrev_b32_e32 v164, 16, v140
	v_mul_f32_e32 v140, 0x3fb8aa3b, v106
	v_pk_mul_f32 v[104:105], v[104:105], v[164:165]
	v_exp_f32_e32 v164, v140
	v_mul_f32_e32 v140, 0x3fb8aa3b, v107
	v_exp_f32_e32 v165, v140
	v_and_b32_e32 v167, 0xffff0000, v145
	v_lshlrev_b32_e32 v166, 16, v145
	v_mul_f32_e32 v106, 0xbfb8aa3b, v106
	v_pk_mul_f32 v[144:145], v[166:167], s[24:25] op_sel_hi:[1,0]
	v_mul_f32_e32 v107, 0xbfb8aa3b, v107
	v_exp_f32_e32 v106, v106
	v_pk_mul_f32 v[144:145], v[144:145], v[164:165]
	v_exp_f32_e32 v107, v107
	v_mfma_f32_16x16x32_bf16 v[164:167], v[80:83], v[246:249], 0
	v_and_b32_e32 v81, 0xffff0000, v141
	v_lshlrev_b32_e32 v80, 16, v141
	v_pk_mul_f32 v[106:107], v[106:107], v[80:81]
	v_mfma_f32_16x16x32_bf16 v[80:83], v[112:115], v[148:151], v[164:167]
	v_and_b32_e32 v149, 0xffff0000, v146
	v_lshlrev_b32_e32 v148, 16, v146
	v_pk_mul_f32 v[148:149], v[148:149], s[24:25] op_sel_hi:[1,0]
	v_and_b32_e32 v151, 0xffff0000, v147
	v_lshlrev_b32_e32 v150, 16, v147
	s_nop 2
	v_mul_f32_e32 v140, 0x3fb8aa3b, v80
	v_mul_f32_e32 v141, 0x3fb8aa3b, v81
	v_exp_f32_e32 v140, v140
	v_mul_f32_e32 v80, 0xbfb8aa3b, v80
	v_exp_f32_e32 v141, v141
	v_mul_f32_e32 v81, 0xbfb8aa3b, v81
	v_exp_f32_e32 v80, v80
	v_exp_f32_e32 v81, v81
	v_pk_mul_f32 v[140:141], v[148:149], v[140:141]
	v_and_b32_e32 v149, 0xffff0000, v142
	v_lshlrev_b32_e32 v148, 16, v142
	v_pk_mul_f32 v[148:149], v[80:81], v[148:149]
	v_mul_f32_e32 v81, 0xbfb8aa3b, v82
	v_mul_f32_e32 v80, 0x3fb8aa3b, v82
	v_exp_f32_e32 v82, v81
	v_mul_f32_e32 v81, 0x3fb8aa3b, v83
	v_exp_f32_e32 v80, v80
	v_exp_f32_e32 v81, v81
	v_mul_f32_e32 v83, 0xbfb8aa3b, v83
	v_exp_f32_e32 v83, v83
	v_pk_mul_f32 v[146:147], v[150:151], s[24:25] op_sel_hi:[1,0]
	v_cvt_pk_bf16_f32 v96, v178, v179
	v_pk_mul_f32 v[146:147], v[146:147], v[80:81]
	v_and_b32_e32 v81, 0xffff0000, v143
	v_lshlrev_b32_e32 v80, 16, v143
	v_pk_mul_f32 v[142:143], v[82:83], v[80:81]
	v_cvt_pk_bf16_f32 v98, v180, v181
	v_cvt_pk_bf16_f32 v80, v154, v155
	v_cvt_pk_bf16_f32 v81, v144, v145
	v_cvt_pk_bf16_f32 v82, v140, v141
	v_cvt_pk_bf16_f32 v83, v146, v147
	v_cvt_pk_bf16_f32 v104, v104, v105
	v_cvt_pk_bf16_f32 v105, v106, v107
	v_cvt_pk_bf16_f32 v106, v148, v149
	v_cvt_pk_bf16_f32 v107, v142, v143
	v_cndmask_b32_e64 v140, 0, 1, s[80:81]
	v_cndmask_b32_e64 v141, 0, 1, s[82:83]
	v_cndmask_b32_e64 v140, v141, v140, s[26:27]
	v_and_b32_e32 v140, 1, v140
	v_cmp_eq_u32_e64 s[0:1], 1, v140
	v_cndmask_b32_e64 v141, 0, 1, s[86:87]
	v_cndmask_b32_e64 v142, 0, 1, s[90:91]
	v_cndmask_b32_e64 v140, 0, v229, s[0:1]
	v_perm_b32 v154, v140, v176, s3
	v_cndmask_b32_e64 v140, 0, 1, s[84:85]
	v_cndmask_b32_e64 v140, v141, v140, s[26:27]
	v_cndmask_b32_e64 v141, 0, 1, s[88:89]
	v_cndmask_b32_e64 v141, v142, v141, s[26:27]
	v_and_b32_e32 v140, 1, v140
	v_and_b32_e32 v141, 1, v141
	v_cmp_eq_u32_e64 s[18:19], 1, v140
	v_cmp_eq_u32_e64 s[22:23], 1, v141
	v_mov_b32_e32 v153, v152
	v_cndmask_b32_e64 v140, 0, v229, s[18:19]
	v_cndmask_b32_e64 v141, 0, v229, s[22:23]
	v_perm_b32 v155, v141, v140, s3
	s_waitcnt vmcnt(3)
; __device__ __forceinline__ float bf2f(bf16_t b) { return __uint_as_float(((unsigned)b) << 16); }
; __device__ __forceinline__ f32x4 mfma16(bf16x8 a, bf16x8 b, f32x4 c) { return __builtin_amdgcn_mfma_f32_16x16x32_bf16(a, b, c, 0, 0, 0); }
; template <int MODE> __device__ void mixer_gla(const Params& p, int l, int n, LAS unsigned char* lds) {
;     ...
;             for (int tj = 0; tj < 4; ++tj) {
;                 const int t = 16 * tj + c;
;                 bf16x8 mk[2];
; #pragma unroll
;                 for (int ks = 0; ks < 2; ++ks)
; #pragma unroll
;                     for (int jj = 0; jj < 8; ++jj) { const int sidx = SLOT(ks, q, jj); const bool on = dir == 0 ? sidx <= t : sidx >= t; mk[ks][jj] = on ? (short)0x3F80 : (short)0; }
; #pragma unroll
;                 for (int ks2 = 0; ks2 < 2; ++ks2) { f32x4 qe2[2], ke2[2];
; #pragma unroll
;                     for (int e2 = 0; e2 < 2; ++e2) { const int ef = 2 * ks2 + e2;
;                         f32x4 b = mfma16(laop[ef][0], mk[0], zero4); b = mfma16(laop[ef][1], mk[1], b);
; #pragma unroll
;                         for (int r = 0; r < 4; ++r) { qe2[e2][r] = bf2f((bf16_t)qn[tj][ks2][4 * e2 + r]) * 0.125f * __expf(b[r]); ke2[e2][r] = bf2f((bf16_t)kn1[tj][ks2][4 * e2 + r]) * __expf(-b[r]); } }
;                     QEop[tj][ks2] = pack8(qe2[0], qe2[1]); KEop[tj][ks2] = pack8(ke2[0], ke2[1]); }
;                 __builtin_amdgcn_sched_barrier(0);
;             }
;             const bf16_t* SP = spT + ((size_t)(dir * NCH + n) * 4 + h) * 8192 + (size_t)(64 * vh) * 64;
;             bf16x8 spf[4][2];
; #pragma unroll
;             for (int vf = 0; vf < 4; ++vf)
; #pragma unroll
;                 for (int ks = 0; ks < 2; ++ks) spf[vf][ks] = *(const bf16x8*)(SP + (16 * vf + c) * 64 + 32 * ks + 8 * q);
	v_and_b32_e32 v143, 0xffff0000, v128
	v_lshlrev_b32_e32 v142, 16, v128
	v_mfma_f32_16x16x32_bf16 v[84:87], v[84:87], v[152:155], v[168:171]
	v_mul_f32_e64 v142, v142, s24
	v_mul_f32_e64 v143, v143, s24
	v_and_b32_e32 v145, 0xffff0000, v129
	v_lshlrev_b32_e32 v144, 16, v129
	v_pk_mul_f32 v[128:129], v[144:145], s[24:25] op_sel_hi:[1,0]
	v_mfma_f32_16x16x32_bf16 v[92:95], v[92:95], v[152:155], v[160:163]
	s_nop 1
	v_mul_f32_e32 v140, 0x3fb8aa3b, v84
	v_mul_f32_e32 v141, 0x3fb8aa3b, v85
	v_exp_f32_e32 v140, v140
	v_mul_f32_e32 v84, 0xbfb8aa3b, v84
	v_exp_f32_e32 v141, v141
	v_mul_f32_e32 v85, 0xbfb8aa3b, v85
	v_exp_f32_e32 v84, v84
	v_exp_f32_e32 v85, v85
	v_pk_mul_f32 v[140:141], v[142:143], v[140:141]
	s_waitcnt vmcnt(1)
	v_and_b32_e32 v143, 0xffff0000, v124
	v_lshlrev_b32_e32 v142, 16, v124
	v_pk_mul_f32 v[142:143], v[84:85], v[142:143]
	v_mul_f32_e32 v85, 0xbfb8aa3b, v86
	v_mul_f32_e32 v84, 0x3fb8aa3b, v86
	v_exp_f32_e32 v86, v85
	v_mul_f32_e32 v85, 0x3fb8aa3b, v87
	v_exp_f32_e32 v84, v84
	v_exp_f32_e32 v85, v85
	v_mul_f32_e32 v87, 0xbfb8aa3b, v87
	v_exp_f32_e32 v87, v87
	v_and_b32_e32 v145, 0xffff0000, v131
	v_pk_mul_f32 v[128:129], v[128:129], v[84:85]
	v_and_b32_e32 v85, 0xffff0000, v125
	v_lshlrev_b32_e32 v84, 16, v125
	v_pk_mul_f32 v[124:125], v[86:87], v[84:85]
	v_mfma_f32_16x16x32_bf16 v[84:87], v[100:103], v[152:155], v[172:175]
	v_and_b32_e32 v103, 0xffff0000, v130
	v_lshlrev_b32_e32 v102, 16, v130
	v_pk_mul_f32 v[102:103], v[102:103], s[24:25] op_sel_hi:[1,0]
	v_lshlrev_b32_e32 v144, 16, v131
	v_pk_mul_f32 v[130:131], v[144:145], s[24:25] op_sel_hi:[1,0]
	s_nop 2
	v_mul_f32_e32 v100, 0x3fb8aa3b, v84
	v_mul_f32_e32 v101, 0x3fb8aa3b, v85
	v_exp_f32_e32 v100, v100
	v_mul_f32_e32 v84, 0xbfb8aa3b, v84
	v_exp_f32_e32 v101, v101
	v_mul_f32_e32 v85, 0xbfb8aa3b, v85
	v_exp_f32_e32 v84, v84
	v_exp_f32_e32 v85, v85
	v_pk_mul_f32 v[100:101], v[102:103], v[100:101]
	v_and_b32_e32 v103, 0xffff0000, v126
	v_lshlrev_b32_e32 v102, 16, v126
	v_pk_mul_f32 v[102:103], v[84:85], v[102:103]
	v_mul_f32_e32 v85, 0xbfb8aa3b, v86
	v_mul_f32_e32 v84, 0x3fb8aa3b, v86
	v_exp_f32_e32 v86, v85
	v_mul_f32_e32 v85, 0x3fb8aa3b, v87
	v_exp_f32_e32 v84, v84
	v_exp_f32_e32 v85, v85
	v_mul_f32_e32 v87, 0xbfb8aa3b, v87
	v_exp_f32_e32 v87, v87
	v_cvt_pk_bf16_f32 v102, v102, v103
	v_pk_mul_f32 v[130:131], v[130:131], v[84:85]
	v_and_b32_e32 v85, 0xffff0000, v127
	v_lshlrev_b32_e32 v84, 16, v127
	v_pk_mul_f32 v[126:127], v[86:87], v[84:85]
	v_cvt_pk_bf16_f32 v86, v100, v101
	v_cvt_pk_bf16_f32 v101, v124, v125
	v_mul_f32_e32 v124, 0x3fb8aa3b, v92
	v_mul_f32_e32 v125, 0x3fb8aa3b, v93
	v_exp_f32_e32 v124, v124
	v_mul_f32_e32 v92, 0xbfb8aa3b, v92
	v_exp_f32_e32 v125, v125
	v_mul_f32_e32 v93, 0xbfb8aa3b, v93
	v_exp_f32_e32 v92, v92
	v_exp_f32_e32 v93, v93
	v_cvt_pk_bf16_f32 v103, v126, v127
	v_and_b32_e32 v127, 0xffff0000, v108
	v_lshlrev_b32_e32 v126, 16, v108
	v_pk_mul_f32 v[126:127], v[126:127], s[24:25] op_sel_hi:[1,0]
	v_cvt_pk_bf16_f32 v85, v128, v129
	v_pk_mul_f32 v[124:125], v[126:127], v[124:125]
	s_waitcnt vmcnt(0)
	v_and_b32_e32 v127, 0xffff0000, v88
	v_lshlrev_b32_e32 v126, 16, v88
	v_mul_f32_e32 v88, 0x3fb8aa3b, v94
	v_pk_mul_f32 v[126:127], v[92:93], v[126:127]
	v_exp_f32_e32 v92, v88
	v_mul_f32_e32 v88, 0xbfb8aa3b, v94
	v_exp_f32_e32 v94, v88
	v_mul_f32_e32 v88, 0x3fb8aa3b, v95
	v_exp_f32_e32 v93, v88
	v_mul_f32_e32 v88, 0xbfb8aa3b, v95
	v_exp_f32_e32 v95, v88
	v_and_b32_e32 v129, 0xffff0000, v109
	v_lshlrev_b32_e32 v128, 16, v109
	v_pk_mul_f32 v[108:109], v[128:129], s[24:25] op_sel_hi:[1,0]
	v_cvt_pk_bf16_f32 v84, v140, v141
	v_pk_mul_f32 v[108:109], v[108:109], v[92:93]
	v_and_b32_e32 v93, 0xffff0000, v89
	v_lshlrev_b32_e32 v92, 16, v89
	v_pk_mul_f32 v[128:129], v[94:95], v[92:93]
	v_mfma_f32_16x16x32_bf16 v[92:95], v[112:115], v[152:155], v[164:167]
	v_and_b32_e32 v113, 0xffff0000, v110
	v_lshlrev_b32_e32 v112, 16, v110
	v_pk_mul_f32 v[112:113], v[112:113], s[24:25] op_sel_hi:[1,0]
	v_and_b32_e32 v115, 0xffff0000, v111
	v_lshlrev_b32_e32 v114, 16, v111
	s_nop 2
	v_mul_f32_e32 v89, 0xbfb8aa3b, v92
	v_mul_f32_e32 v88, 0x3fb8aa3b, v92
	v_exp_f32_e32 v92, v89
	v_mul_f32_e32 v89, 0x3fb8aa3b, v93
	v_exp_f32_e32 v88, v88
	v_exp_f32_e32 v89, v89
	v_mul_f32_e32 v93, 0xbfb8aa3b, v93
	v_exp_f32_e32 v93, v93
	v_pk_mul_f32 v[110:111], v[114:115], s[24:25] op_sel_hi:[1,0]
	v_pk_mul_f32 v[112:113], v[112:113], v[88:89]
	v_and_b32_e32 v89, 0xffff0000, v90
	v_lshlrev_b32_e32 v88, 16, v90
	v_pk_mul_f32 v[92:93], v[92:93], v[88:89]
	v_mul_f32_e32 v89, 0xbfb8aa3b, v94
	v_mul_f32_e32 v88, 0x3fb8aa3b, v94
	v_exp_f32_e32 v94, v89
	v_mul_f32_e32 v89, 0x3fb8aa3b, v95
	v_exp_f32_e32 v88, v88
	v_exp_f32_e32 v89, v89
	v_mul_f32_e32 v90, 0xbfb8aa3b, v95
	v_exp_f32_e32 v95, v90
	v_cvt_pk_bf16_f32 v87, v130, v131
	v_pk_mul_f32 v[110:111], v[110:111], v[88:89]
	v_and_b32_e32 v89, 0xffff0000, v91
	v_lshlrev_b32_e32 v88, 16, v91
	v_pk_mul_f32 v[94:95], v[94:95], v[88:89]
	v_cvt_pk_bf16_f32 v100, v142, v143
	v_cvt_pk_bf16_f32 v88, v124, v125
	v_cvt_pk_bf16_f32 v89, v108, v109
	v_cvt_pk_bf16_f32 v90, v112, v113
	v_cvt_pk_bf16_f32 v91, v110, v111
	v_cvt_pk_bf16_f32 v148, v126, v127
	v_cvt_pk_bf16_f32 v149, v128, v129
	v_cvt_pk_bf16_f32 v150, v92, v93
	v_cvt_pk_bf16_f32 v151, v94, v95
	s_add_i32 s14, s34, s43
	s_ashr_i32 s15, s14, 31
	s_lshl_b64 s[14:15], s[14:15], 16
	v_lshl_add_u64 v[92:93], v[220:221], 0, s[14:15]
	s_movk_i32 s2, 0x1000
	global_load_dwordx4 v[152:155], v[92:93], off
	global_load_dwordx4 v[160:163], v[92:93], off offset:64
	global_load_dwordx4 v[164:167], v[92:93], off offset:2048
	global_load_dwordx4 v[144:147], v[92:93], off offset:2112
	v_add_co_u32_e32 v92, vcc, s2, v92
; __device__ __forceinline__ f32x4 mfma16(bf16x8 a, bf16x8 b, f32x4 c) { return __builtin_amdgcn_mfma_f32_16x16x32_bf16(a, b, c, 0, 0, 0); }
; template <int MODE> __device__ void mixer_gla(const Params& p, int l, int n, LAS unsigned char* lds) {
;     ...
;             for (int ti = 0; ti < 4; ++ti)
; #pragma unroll
;                 for (int ksp = 0; ksp < 2; ++ksp) { f32x4 pm[2];
; #pragma unroll
;                     for (int j2 = 0; j2 < 2; ++j2) { const int tjj = 2 * ksp + j2;
;                         f32x4 sc = mfma16(KEop[tjj][0], QEop[ti][0], zero4); sc = mfma16(KEop[tjj][1], QEop[ti][1], sc);
; #pragma unroll
;                         for (int r = 0; r < 4; ++r) { const int j = 16 * tjj + 4 * q + r, i = 16 * ti + c; const bool keep = dir == 0 ? j <= i : j >= i; pm[j2][r] = keep ? sc[r] : 0.f; } }
;                     Pop[ti][ksp] = pack8(pm[0], pm[1]); __builtin_amdgcn_sched_barrier(0); }
	s_nop 1
	v_addc_co_u32_e32 v93, vcc, 0, v93, vcc
	global_load_dwordx4 v[128:131], v[92:93], off
	global_load_dwordx4 v[112:115], v[92:93], off offset:64
	global_load_dwordx4 v[108:111], v[92:93], off offset:2048
	s_nop 0
	global_load_dwordx4 v[92:95], v[92:93], off offset:2112
	v_mfma_f32_16x16x32_bf16 v[124:127], v[72:75], v[64:67], 0
	v_mfma_f32_16x16x32_bf16 v[124:127], v[120:123], v[68:71], v[124:127]
	v_mfma_f32_16x16x32_bf16 v[140:143], v[136:139], v[64:67], 0
	s_nop 6
	v_cndmask_b32_e64 v168, 0, v124, s[16:17]
	v_cndmask_b32_e64 v169, 0, v125, s[92:93]
	v_cndmask_b32_e64 v170, 0, v126, s[94:95]
	v_cndmask_b32_e64 v171, 0, v127, s[96:97]
	v_mfma_f32_16x16x32_bf16 v[124:127], v[156:159], v[68:71], v[140:143]
	s_nop 7
	v_cndmask_b32_e64 v140, v124, 0, s[26:27]
	v_cndmask_b32_e64 v141, v125, 0, s[26:27]
	v_cndmask_b32_e64 v142, v126, 0, s[26:27]
	v_cndmask_b32_e64 v127, v127, 0, s[26:27]
	v_cvt_pk_bf16_f32 v124, v168, v169
	v_cvt_pk_bf16_f32 v125, v170, v171
	v_cvt_pk_bf16_f32 v126, v140, v141
	v_cvt_pk_bf16_f32 v127, v142, v127
	v_mfma_f32_16x16x32_bf16 v[140:143], v[96:99], v[64:67], 0
	v_mfma_f32_16x16x32_bf16 v[140:143], v[104:107], v[68:71], v[140:143]
	v_mfma_f32_16x16x32_bf16 v[168:171], v[100:103], v[64:67], 0
	s_nop 6
	v_cndmask_b32_e64 v172, v140, 0, s[26:27]
	v_cndmask_b32_e64 v173, v141, 0, s[26:27]
	v_cndmask_b32_e64 v174, v142, 0, s[26:27]
	v_cndmask_b32_e64 v175, v143, 0, s[26:27]
	v_mfma_f32_16x16x32_bf16 v[140:143], v[148:151], v[68:71], v[168:171]
	s_nop 7
	v_cndmask_b32_e64 v168, v140, 0, s[26:27]
	v_cndmask_b32_e64 v169, v141, 0, s[26:27]
	v_cndmask_b32_e64 v170, v142, 0, s[26:27]
	v_cndmask_b32_e64 v143, v143, 0, s[26:27]
	v_cvt_pk_bf16_f32 v140, v172, v173
	v_cvt_pk_bf16_f32 v141, v174, v175
	v_cvt_pk_bf16_f32 v142, v168, v169
	v_cvt_pk_bf16_f32 v143, v170, v143
	v_mfma_f32_16x16x32_bf16 v[168:171], v[72:75], v[116:119], 0
	v_mfma_f32_16x16x32_bf16 v[168:171], v[120:123], v[132:135], v[168:171]
	v_mfma_f32_16x16x32_bf16 v[172:175], v[136:139], v[116:119], 0
	s_nop 6
	v_cndmask_b32_e64 v176, 0, v168, s[26:27]
	v_cndmask_b32_e64 v178, 0, v169, s[26:27]
	v_cndmask_b32_e64 v179, 0, v170, s[26:27]
	v_cndmask_b32_e64 v180, 0, v171, s[26:27]
	v_mfma_f32_16x16x32_bf16 v[168:171], v[156:159], v[132:135], v[172:175]
	s_nop 7
	v_cndmask_b32_e64 v172, 0, v168, s[16:17]
	v_cndmask_b32_e64 v173, 0, v169, s[20:21]
	v_cndmask_b32_e64 v174, 0, v170, s[4:5]
	v_cndmask_b32_e64 v171, 0, v171, s[6:7]
	v_cvt_pk_bf16_f32 v168, v176, v178
	v_cvt_pk_bf16_f32 v169, v179, v180
	v_cvt_pk_bf16_f32 v170, v172, v173
	v_cvt_pk_bf16_f32 v171, v174, v171
	v_mfma_f32_16x16x32_bf16 v[172:175], v[96:99], v[116:119], 0
	v_mfma_f32_16x16x32_bf16 v[172:175], v[104:107], v[132:135], v[172:175]
	v_mfma_f32_16x16x32_bf16 v[246:249], v[100:103], v[116:119], 0
	s_nop 6
	v_cndmask_b32_e64 v176, v172, 0, s[26:27]
	v_cndmask_b32_e64 v178, v173, 0, s[26:27]
	v_cndmask_b32_e64 v179, v174, 0, s[26:27]
	v_cndmask_b32_e64 v180, v175, 0, s[26:27]
	v_mfma_f32_16x16x32_bf16 v[172:175], v[148:151], v[132:135], v[246:249]
	s_nop 7
	v_cndmask_b32_e64 v181, v172, 0, s[26:27]
	v_cndmask_b32_e64 v188, v173, 0, s[26:27]
	v_cndmask_b32_e64 v189, v174, 0, s[26:27]
	v_cndmask_b32_e64 v175, v175, 0, s[26:27]
	v_cvt_pk_bf16_f32 v172, v176, v178
	v_cvt_pk_bf16_f32 v173, v179, v180
	v_cvt_pk_bf16_f32 v174, v181, v188
	v_cvt_pk_bf16_f32 v175, v189, v175
	v_mfma_f32_16x16x32_bf16 v[246:249], v[72:75], v[76:79], 0
	v_mfma_f32_16x16x32_bf16 v[178:181], v[136:139], v[76:79], 0
	v_mfma_f32_16x16x32_bf16 v[246:249], v[120:123], v[80:83], v[246:249]
	v_mfma_f32_16x16x32_bf16 v[178:181], v[156:159], v[80:83], v[178:181]
	s_nop 6
	v_cndmask_b32_e64 v176, 0, v246, s[26:27]
	v_cndmask_b32_e64 v188, 0, v247, s[26:27]
	v_cndmask_b32_e64 v189, 0, v248, s[26:27]
	v_cndmask_b32_e64 v190, 0, v249, s[26:27]
	v_cndmask_b32_e64 v191, 0, v178, s[26:27]
	v_cndmask_b32_e64 v201, 0, v179, s[26:27]
	v_cndmask_b32_e64 v246, 0, v180, s[26:27]
	v_cndmask_b32_e64 v181, 0, v181, s[26:27]
	v_cvt_pk_bf16_f32 v178, v176, v188
	v_cvt_pk_bf16_f32 v179, v189, v190
	v_cvt_pk_bf16_f32 v180, v191, v201
	v_cvt_pk_bf16_f32 v181, v246, v181
	v_mfma_f32_16x16x32_bf16 v[246:249], v[96:99], v[76:79], 0
	v_mfma_f32_16x16x32_bf16 v[188:191], v[100:103], v[76:79], 0
	v_mfma_f32_16x16x32_bf16 v[246:249], v[104:107], v[80:83], v[246:249]
	v_mfma_f32_16x16x32_bf16 v[188:191], v[148:151], v[80:83], v[188:191]
	s_nop 6
	v_cndmask_b32_e64 v176, 0, v246, s[16:17]
	v_cndmask_b32_e64 v201, 0, v247, s[8:9]
	v_cndmask_b32_e64 v246, 0, v248, s[10:11]
	v_cndmask_b32_e64 v247, 0, v249, s[12:13]
	v_cndmask_b32_e64 v248, v188, 0, s[26:27]
	v_cndmask_b32_e64 v249, v189, 0, s[26:27]
	v_cndmask_b32_e64 v224, v190, 0, s[26:27]
	v_cndmask_b32_e64 v191, v191, 0, s[26:27]
	v_cvt_pk_bf16_f32 v188, v176, v201
	v_cvt_pk_bf16_f32 v189, v246, v247
	v_cvt_pk_bf16_f32 v190, v248, v249
	v_cvt_pk_bf16_f32 v191, v224, v191
	v_mfma_f32_16x16x32_bf16 v[72:75], v[72:75], v[84:87], 0
	v_mfma_f32_16x16x32_bf16 v[72:75], v[120:123], v[88:91], v[72:75]
	v_mfma_f32_16x16x32_bf16 v[120:123], v[136:139], v[84:87], 0
	s_nop 6
	v_cndmask_b32_e64 v176, 0, v72, s[26:27]
	v_cndmask_b32_e64 v136, 0, v73, s[26:27]
	v_cndmask_b32_e64 v137, 0, v74, s[26:27]
	v_cndmask_b32_e64 v138, 0, v75, s[26:27]
	v_mfma_f32_16x16x32_bf16 v[72:75], v[156:159], v[88:91], v[120:123]
	s_nop 7
	v_cndmask_b32_e64 v120, 0, v72, s[26:27]
	v_cndmask_b32_e64 v121, 0, v73, s[26:27]
	v_cndmask_b32_e64 v122, 0, v74, s[26:27]
	v_cndmask_b32_e64 v75, 0, v75, s[26:27]
	v_cvt_pk_bf16_f32 v72, v176, v136
	v_cvt_pk_bf16_f32 v73, v137, v138
	v_cvt_pk_bf16_f32 v74, v120, v121
	v_cvt_pk_bf16_f32 v75, v122, v75
	v_mfma_f32_16x16x32_bf16 v[96:99], v[96:99], v[84:87], 0
	v_mfma_f32_16x16x32_bf16 v[96:99], v[104:107], v[88:91], v[96:99]
	v_mfma_f32_16x16x32_bf16 v[100:103], v[100:103], v[84:87], 0
	s_nop 6
	v_cndmask_b32_e64 v104, 0, v96, s[26:27]
	v_cndmask_b32_e64 v105, 0, v97, s[26:27]
	v_cndmask_b32_e64 v106, 0, v98, s[26:27]
	v_cndmask_b32_e64 v107, 0, v99, s[26:27]
	v_mfma_f32_16x16x32_bf16 v[96:99], v[148:151], v[88:91], v[100:103]
	s_nop 7
	v_cndmask_b32_e64 v100, 0, v96, s[16:17]
	v_cndmask_b32_e64 v101, 0, v97, s[0:1]
	v_cndmask_b32_e64 v102, 0, v98, s[18:19]
	v_cndmask_b32_e64 v99, 0, v99, s[22:23]
	v_cvt_pk_bf16_f32 v96, v104, v105
	v_cvt_pk_bf16_f32 v97, v106, v107
	v_cvt_pk_bf16_f32 v98, v100, v101
	v_cvt_pk_bf16_f32 v99, v102, v99
	ds_read2_b64 v[100:103], v199 offset1:4
	s_waitcnt lgkmcnt(0)
; #define LAS __attribute__((address_space(3)))
; __device__ __forceinline__ f32x4 mfma16(bf16x8 a, bf16x8 b, f32x4 c) { return __builtin_amdgcn_mfma_f32_16x16x32_bf16(a, b, c, 0, 0, 0); }
; template <int MODE> __device__ void mixer_gla(const Params& p, int l, int n, LAS unsigned char* lds) {
;     ...
;             for (int vf = 0; vf < 4; ++vf)
; #pragma unroll
;                 for (int ks = 0; ks < 2; ++ks) {
;                     const u32x2 v0 = *(const LAS u32x2*)(VTw + (16 * vf + c) * 72 + 32 * ks + 4 * q), v1 = *(const LAS u32x2*)(VTw + (16 * vf + c) * 72 + 32 * ks + 16 + 4 * q);
;                     const bf16x8 vtf = __builtin_bit_cast(bf16x8, (u32x4){v0.x, v0.y, v1.x, v1.y});
; #pragma unroll
;                     for (int ti = 0; ti < 4; ++ti) { acc[vf][ti] = mfma16(vtf, Pop[ti][ks], acc[vf][ti]); acc[vf][ti] = mfma16(spf[vf][ks], QEop[ti][ks], acc[vf][ti]); }
;                     if (ks == 1 && (vf & 1)) __builtin_amdgcn_sched_barrier(0);
;                 }
	v_mfma_f32_16x16x32_bf16 v[60:63], v[100:103], v[124:127], v[60:63]
	v_mfma_f32_16x16x32_bf16 v[44:47], v[100:103], v[168:171], v[44:47]
	v_mfma_f32_16x16x32_bf16 v[28:31], v[100:103], v[178:181], v[28:31]
	v_mfma_f32_16x16x32_bf16 v[12:15], v[100:103], v[72:75], v[12:15]
	ds_read2_b64 v[100:103], v199 offset0:8 offset1:12
	s_waitcnt vmcnt(7)
	v_mfma_f32_16x16x32_bf16 v[60:63], v[152:155], v[64:67], v[60:63]
	v_mfma_f32_16x16x32_bf16 v[44:47], v[152:155], v[116:119], v[44:47]
	v_mfma_f32_16x16x32_bf16 v[28:31], v[152:155], v[76:79], v[28:31]
	v_mfma_f32_16x16x32_bf16 v[12:15], v[152:155], v[84:87], v[12:15]
	s_waitcnt lgkmcnt(0)
	v_mfma_f32_16x16x32_bf16 v[60:63], v[100:103], v[140:143], v[60:63]
	v_mfma_f32_16x16x32_bf16 v[44:47], v[100:103], v[172:175], v[44:47]
	v_mfma_f32_16x16x32_bf16 v[28:31], v[100:103], v[188:191], v[28:31]
	v_mfma_f32_16x16x32_bf16 v[12:15], v[100:103], v[96:99], v[12:15]
	ds_read2_b64 v[100:103], v242 offset1:4
	s_waitcnt lgkmcnt(0)
	v_mfma_f32_16x16x32_bf16 v[56:59], v[100:103], v[124:127], v[56:59]
	v_mfma_f32_16x16x32_bf16 v[40:43], v[100:103], v[168:171], v[40:43]
	v_mfma_f32_16x16x32_bf16 v[24:27], v[100:103], v[178:181], v[24:27]
	v_mfma_f32_16x16x32_bf16 v[8:11], v[100:103], v[72:75], v[8:11]
	ds_read2_b64 v[100:103], v242 offset0:8 offset1:12
	s_waitcnt vmcnt(5)
	v_mfma_f32_16x16x32_bf16 v[56:59], v[164:167], v[64:67], v[56:59]
	v_mfma_f32_16x16x32_bf16 v[40:43], v[164:167], v[116:119], v[40:43]
	v_mfma_f32_16x16x32_bf16 v[24:27], v[164:167], v[76:79], v[24:27]
	v_mfma_f32_16x16x32_bf16 v[8:11], v[164:167], v[84:87], v[8:11]
	s_waitcnt lgkmcnt(0)
	v_mfma_f32_16x16x32_bf16 v[56:59], v[100:103], v[140:143], v[56:59]
	v_mfma_f32_16x16x32_bf16 v[40:43], v[100:103], v[172:175], v[40:43]
	v_mfma_f32_16x16x32_bf16 v[24:27], v[100:103], v[188:191], v[24:27]
	v_mfma_f32_16x16x32_bf16 v[8:11], v[100:103], v[96:99], v[8:11]
	v_mfma_f32_16x16x32_bf16 v[60:63], v[160:163], v[68:71], v[60:63]
	v_mfma_f32_16x16x32_bf16 v[44:47], v[160:163], v[132:135], v[44:47]
	v_mfma_f32_16x16x32_bf16 v[28:31], v[160:163], v[80:83], v[28:31]
	v_mfma_f32_16x16x32_bf16 v[12:15], v[160:163], v[88:91], v[12:15]
	s_waitcnt vmcnt(4)
	v_mfma_f32_16x16x32_bf16 v[56:59], v[144:147], v[68:71], v[56:59]
	v_mfma_f32_16x16x32_bf16 v[40:43], v[144:147], v[132:135], v[40:43]
	v_mfma_f32_16x16x32_bf16 v[24:27], v[144:147], v[80:83], v[24:27]
	v_mfma_f32_16x16x32_bf16 v[8:11], v[144:147], v[88:91], v[8:11]
	ds_read2_b64 v[100:103], v243 offset1:4
	s_waitcnt lgkmcnt(0)
	v_mfma_f32_16x16x32_bf16 v[52:55], v[100:103], v[124:127], v[52:55]
	v_mfma_f32_16x16x32_bf16 v[36:39], v[100:103], v[168:171], v[36:39]
	v_mfma_f32_16x16x32_bf16 v[20:23], v[100:103], v[178:181], v[20:23]
	v_mfma_f32_16x16x32_bf16 v[4:7], v[100:103], v[72:75], v[4:7]
	ds_read2_b64 v[100:103], v243 offset0:8 offset1:12
	s_waitcnt vmcnt(3)
	v_mfma_f32_16x16x32_bf16 v[52:55], v[128:131], v[64:67], v[52:55]
	v_mfma_f32_16x16x32_bf16 v[36:39], v[128:131], v[116:119], v[36:39]
	v_mfma_f32_16x16x32_bf16 v[20:23], v[128:131], v[76:79], v[20:23]
	v_mfma_f32_16x16x32_bf16 v[4:7], v[128:131], v[84:87], v[4:7]
	s_waitcnt lgkmcnt(0)
	v_mfma_f32_16x16x32_bf16 v[52:55], v[100:103], v[140:143], v[52:55]
	v_mfma_f32_16x16x32_bf16 v[36:39], v[100:103], v[172:175], v[36:39]
	v_mfma_f32_16x16x32_bf16 v[20:23], v[100:103], v[188:191], v[20:23]
	v_mfma_f32_16x16x32_bf16 v[4:7], v[100:103], v[96:99], v[4:7]
	ds_read2_b64 v[100:103], v244 offset1:4
	s_waitcnt lgkmcnt(0)
	v_mfma_f32_16x16x32_bf16 v[48:51], v[100:103], v[124:127], v[48:51]
	s_waitcnt vmcnt(1)
	v_mfma_f32_16x16x32_bf16 v[48:51], v[108:111], v[64:67], v[48:51]
	ds_read2_b64 v[64:67], v244 offset0:8 offset1:12
	v_mfma_f32_16x16x32_bf16 v[32:35], v[100:103], v[168:171], v[32:35]
	v_mfma_f32_16x16x32_bf16 v[16:19], v[100:103], v[178:181], v[16:19]
	v_mfma_f32_16x16x32_bf16 v[0:3], v[100:103], v[72:75], v[0:3]
	v_mfma_f32_16x16x32_bf16 v[32:35], v[108:111], v[116:119], v[32:35]
	v_mfma_f32_16x16x32_bf16 v[16:19], v[108:111], v[76:79], v[16:19]
	v_mfma_f32_16x16x32_bf16 v[0:3], v[108:111], v[84:87], v[0:3]
	s_waitcnt lgkmcnt(0)
	v_mfma_f32_16x16x32_bf16 v[48:51], v[64:67], v[140:143], v[48:51]
	v_mfma_f32_16x16x32_bf16 v[32:35], v[64:67], v[172:175], v[32:35]
	v_mfma_f32_16x16x32_bf16 v[16:19], v[64:67], v[188:191], v[16:19]
	v_mfma_f32_16x16x32_bf16 v[0:3], v[64:67], v[96:99], v[0:3]
	v_mfma_f32_16x16x32_bf16 v[52:55], v[112:115], v[68:71], v[52:55]
	v_mfma_f32_16x16x32_bf16 v[36:39], v[112:115], v[132:135], v[36:39]
	v_mfma_f32_16x16x32_bf16 v[20:23], v[112:115], v[80:83], v[20:23]
	v_mfma_f32_16x16x32_bf16 v[4:7], v[112:115], v[88:91], v[4:7]
	s_waitcnt vmcnt(0)
	v_mfma_f32_16x16x32_bf16 v[48:51], v[92:95], v[68:71], v[48:51]
	v_mfma_f32_16x16x32_bf16 v[32:35], v[92:95], v[132:135], v[32:35]
	v_mfma_f32_16x16x32_bf16 v[16:19], v[92:95], v[80:83], v[16:19]
	v_mfma_f32_16x16x32_bf16 v[0:3], v[92:95], v[88:91], v[0:3]
	s_mov_b32 s4, 1
	s_mov_b64 s[26:27], 0
	s_and_b64 vcc, exec, s[30:31]
	s_cbranch_vccnz .LBB0_160

; __device__ __forceinline__ float bf2f(bf16_t b) { return __uint_as_float(((unsigned)b) << 16); }
; __device__ __forceinline__ bf16_t f2bf(float f) { unsigned u = __float_as_uint(f); return (bf16_t)((u + 0x7fffu + ((u >> 16) & 1u)) >> 16); }
; template <int MODE> __device__ void mixer_lru(const Params& p, int l, int n, LAS unsigned char* lds) {
;     ...
;             const int ch = tid;
;             const float cw0 = p.in[4][(size_t)(l * 4 + 0) * 512 + ch], cw1 = p.in[4][(size_t)(l * 4 + 1) * 512 + ch], cw2 = p.in[4][(size_t)(l * 4 + 2) * 512 + ch], cw3 = p.in[4][(size_t)(l * 4 + 3) * 512 + ch];
;             const float cb = p.in[5][(size_t)l * 512 + ch];
;             bf16_t xs[67];
; #pragma unroll
;             for (int i = 0; i < 67; ++i) { const int s_ = t0 - 2 + i; const int sc = s_ < 0 ? 0 : (s_ >= S ? S - 1 : s_); const bf16_t v = proj[(size_t)sc * DINP + ch]; xs[i] = s_ == sc ? v : (bf16_t)0; }
; #pragma unroll
;             for (int t = 0; t < 64; ++t) { const float xc = cb + cw0 * bf2f(xs[t]) + cw1 * bf2f(xs[t + 1]) + cw2 * bf2f(xs[t + 2]) + cw3 * bf2f(xs[t + 3]); XC[t * 520 + ch] = f2bf(xc); }
.LBB0_192:
	v_mov_b32_e32 v100, v245
	s_lshl_b32 s28, s4, 6
	v_readlane_b32 s0, v253, 16
	v_readlane_b32 s1, v253, 17
	v_readlane_b32 s88, v255, 22
	v_readlane_b32 s89, v255, 23
	v_readfirstlane_b32 s29, v100
	v_and_b32_e32 v0, 0xff, v100
	v_lshlrev_b32_e32 v1, 3, v0
	v_lshlrev_b32_e32 v0, 2, v0
	s_nop 4
	s_lshr_b32 s29, s29, 8
	global_load_dwordx2 v[2:3], v1, s[14:15]
	global_load_dwordx2 v[4:5], v1, s[88:89]
	global_load_dwordx2 v[6:7], v1, s[8:9]
	global_load_dwordx2 v[8:9], v1, s[10:11]
	global_load_dwordx2 v[10:11], v1, s[12:13]
	s_lshl_b32 s30, s29, 5
	s_add_i32 s30, s30, s28
	s_add_i32 s30, s30, -2
	s_max_i32 s31, s30, 0
	s_cmp_eq_u32 s31, s30
	s_cselect_b32 s92, -1, 0
	s_mul_i32 s31, s31, 0x1600
	s_add_u32 s90, s0, s31
	s_addc_u32 s91, s1, 0
	global_load_dword v12, v0, s[90:91]
	s_add_i32 s34, s30, 1
	s_max_i32 s31, s34, 0
	s_cmp_eq_u32 s31, s34
	s_cselect_b32 s93, -1, 0
	s_mul_i32 s31, s31, 0x1600
	s_add_u32 s90, s0, s31
	s_addc_u32 s91, s1, 0
	global_load_dword v13, v0, s[90:91]
	s_add_i32 s31, s30, 2
	s_mul_i32 s31, s31, 0x1600
	s_add_u32 s90, s0, s31
	s_addc_u32 s91, s1, 0
	global_load_dword v14, v0, s[90:91]
	s_add_u32 s90, s90, 0x1600
	s_addc_u32 s91, s91, 0
	global_load_dword v15, v0, s[90:91]
	s_add_u32 s90, s90, 0x1600
	s_addc_u32 s91, s91, 0
	global_load_dword v16, v0, s[90:91]
	s_add_u32 s90, s90, 0x1600
	s_addc_u32 s91, s91, 0
	global_load_dword v17, v0, s[90:91]
	s_add_u32 s90, s90, 0x1600
	s_addc_u32 s91, s91, 0
	global_load_dword v18, v0, s[90:91]
	s_add_u32 s90, s90, 0x1600
	s_addc_u32 s91, s91, 0
	global_load_dword v19, v0, s[90:91]
	s_add_u32 s90, s90, 0x1600
	s_addc_u32 s91, s91, 0
	global_load_dword v20, v0, s[90:91]
	s_add_u32 s90, s90, 0x1600
	s_addc_u32 s91, s91, 0
	global_load_dword v21, v0, s[90:91]
	s_add_u32 s90, s90, 0x1600
	s_addc_u32 s91, s91, 0
	global_load_dword v22, v0, s[90:91]
	s_add_u32 s90, s90, 0x1600
	s_addc_u32 s91, s91, 0
	global_load_dword v23, v0, s[90:91]
	s_add_u32 s90, s90, 0x1600
	s_addc_u32 s91, s91, 0
	global_load_dword v24, v0, s[90:91]
	s_add_u32 s90, s90, 0x1600
	s_addc_u32 s91, s91, 0
	global_load_dword v25, v0, s[90:91]
	s_add_u32 s90, s90, 0x1600
	s_addc_u32 s91, s91, 0
	global_load_dword v26, v0, s[90:91]
	s_add_u32 s90, s90, 0x1600
	s_addc_u32 s91, s91, 0
	global_load_dword v27, v0, s[90:91]
	s_add_u32 s90, s90, 0x1600
	s_addc_u32 s91, s91, 0
	global_load_dword v28, v0, s[90:91]
	s_add_u32 s90, s90, 0x1600
	s_addc_u32 s91, s91, 0
	global_load_dword v29, v0, s[90:91]
	s_add_u32 s90, s90, 0x1600
	s_addc_u32 s91, s91, 0
	global_load_dword v30, v0, s[90:91]
	s_add_u32 s90, s90, 0x1600
	s_addc_u32 s91, s91, 0
	global_load_dword v31, v0, s[90:91]
	s_add_u32 s90, s90, 0x1600
	s_addc_u32 s91, s91, 0
	global_load_dword v32, v0, s[90:91]
	s_add_u32 s90, s90, 0x1600
	s_addc_u32 s91, s91, 0
	global_load_dword v33, v0, s[90:91]
	s_add_u32 s90, s90, 0x1600
	s_addc_u32 s91, s91, 0
	global_load_dword v34, v0, s[90:91]
	s_add_u32 s90, s90, 0x1600
	s_addc_u32 s91, s91, 0
	global_load_dword v35, v0, s[90:91]
	s_add_u32 s90, s90, 0x1600
	s_addc_u32 s91, s91, 0
	global_load_dword v36, v0, s[90:91]
	s_add_u32 s90, s90, 0x1600
	s_addc_u32 s91, s91, 0
	global_load_dword v37, v0, s[90:91]
	s_add_u32 s90, s90, 0x1600
	s_addc_u32 s91, s91, 0
	global_load_dword v38, v0, s[90:91]
	s_add_u32 s90, s90, 0x1600
	s_addc_u32 s91, s91, 0
	global_load_dword v39, v0, s[90:91]
	s_add_u32 s90, s90, 0x1600
	s_addc_u32 s91, s91, 0
	global_load_dword v40, v0, s[90:91]
	s_add_u32 s90, s90, 0x1600
	s_addc_u32 s91, s91, 0
	global_load_dword v41, v0, s[90:91]
	s_add_u32 s90, s90, 0x1600
	s_addc_u32 s91, s91, 0
	global_load_dword v42, v0, s[90:91]
	s_add_u32 s90, s90, 0x1600
	s_addc_u32 s91, s91, 0
	global_load_dword v43, v0, s[90:91]
	s_add_u32 s90, s90, 0x1600
	s_addc_u32 s91, s91, 0
	global_load_dword v44, v0, s[90:91]
	s_add_u32 s90, s90, 0x1600
	s_addc_u32 s91, s91, 0
	global_load_dword v45, v0, s[90:91]
	s_add_i32 s34, s30, 34
	s_min_i32 s31, s34, 0x3fff
	s_cmp_eq_u32 s31, s34
	s_cselect_b32 s94, -1, 0
	s_mul_i32 s31, s31, 0x1600
	s_add_u32 s90, s0, s31
	s_addc_u32 s91, s1, 0
	global_load_dword v46, v0, s[90:91]
	s_mul_i32 s95, s29, 0x8200
	v_add_u32_e32 v92, s95, v0
	s_waitcnt vmcnt(31)
	v_and_b32_e32 v12, s92, v12
	v_lshlrev_b32_e32 v48, 16, v12
	v_and_b32_e32 v12, 0xffff0000, v12
	v_and_b32_e32 v13, s93, v13
	v_lshlrev_b32_e32 v49, 16, v13
	v_and_b32_e32 v13, 0xffff0000, v13
	v_lshlrev_b32_e32 v50, 16, v14
	v_and_b32_e32 v14, 0xffff0000, v14
	v_lshlrev_b32_e32 v51, 16, v15
	v_and_b32_e32 v15, 0xffff0000, v15
	v_fma_f32 v84, v4, v48, v2
	v_fma_f32 v85, v5, v12, v3
	v_fmac_f32_e32 v84, v6, v49
	v_fmac_f32_e32 v85, v7, v13
	v_fmac_f32_e32 v84, v8, v50
	v_fmac_f32_e32 v85, v9, v14
	v_fmac_f32_e32 v84, v10, v51
	v_fmac_f32_e32 v85, v11, v15
	v_cvt_pk_bf16_f32 v84, v84, v85
	ds_write_b32 v92, v84
	s_waitcnt vmcnt(30)
	v_lshlrev_b32_e32 v52, 16, v16
	v_and_b32_e32 v16, 0xffff0000, v16
	v_fma_f32 v86, v4, v49, v2
	v_fma_f32 v87, v5, v13, v3
	v_fmac_f32_e32 v86, v6, v50
	v_fmac_f32_e32 v87, v7, v14
	v_fmac_f32_e32 v86, v8, v51
	v_fmac_f32_e32 v87, v9, v15
	v_fmac_f32_e32 v86, v10, v52
	v_fmac_f32_e32 v87, v11, v16
	v_cvt_pk_bf16_f32 v86, v86, v87
	ds_write_b32 v92, v86 offset:1040
	s_waitcnt vmcnt(29)
	v_lshlrev_b32_e32 v53, 16, v17
	v_and_b32_e32 v17, 0xffff0000, v17
	v_fma_f32 v84, v4, v50, v2
	v_fma_f32 v85, v5, v14, v3
	v_fmac_f32_e32 v84, v6, v51
	v_fmac_f32_e32 v85, v7, v15
	v_fmac_f32_e32 v84, v8, v52
	v_fmac_f32_e32 v85, v9, v16
	v_fmac_f32_e32 v84, v10, v53
	v_fmac_f32_e32 v85, v11, v17
	v_cvt_pk_bf16_f32 v84, v84, v85
	ds_write_b32 v92, v84 offset:2080
	s_waitcnt vmcnt(28)
; __device__ __forceinline__ float bf2f(bf16_t b) { return __uint_as_float(((unsigned)b) << 16); }
; __device__ __forceinline__ bf16_t f2bf(float f) { unsigned u = __float_as_uint(f); return (bf16_t)((u + 0x7fffu + ((u >> 16) & 1u)) >> 16); }
; template <int MODE> __device__ void mixer_lru(const Params& p, int l, int n, LAS unsigned char* lds) {
;     ...
;             for (int t = 0; t < 64; ++t) { const float xc = cb + cw0 * bf2f(xs[t]) + cw1 * bf2f(xs[t + 1]) + cw2 * bf2f(xs[t + 2]) + cw3 * bf2f(xs[t + 3]); XC[t * 520 + ch] = f2bf(xc); }
	v_lshlrev_b32_e32 v54, 16, v18
	v_and_b32_e32 v18, 0xffff0000, v18
	v_fma_f32 v86, v4, v51, v2
	v_fma_f32 v87, v5, v15, v3
	v_fmac_f32_e32 v86, v6, v52
	v_fmac_f32_e32 v87, v7, v16
	v_fmac_f32_e32 v86, v8, v53
	v_fmac_f32_e32 v87, v9, v17
	v_fmac_f32_e32 v86, v10, v54
	v_fmac_f32_e32 v87, v11, v18
	v_cvt_pk_bf16_f32 v86, v86, v87
	ds_write_b32 v92, v86 offset:3120
	s_waitcnt vmcnt(27)
	v_lshlrev_b32_e32 v55, 16, v19
	v_and_b32_e32 v19, 0xffff0000, v19
	v_fma_f32 v84, v4, v52, v2
	v_fma_f32 v85, v5, v16, v3
	v_fmac_f32_e32 v84, v6, v53
	v_fmac_f32_e32 v85, v7, v17
	v_fmac_f32_e32 v84, v8, v54
	v_fmac_f32_e32 v85, v9, v18
	v_fmac_f32_e32 v84, v10, v55
	v_fmac_f32_e32 v85, v11, v19
	v_cvt_pk_bf16_f32 v84, v84, v85
	ds_write_b32 v92, v84 offset:4160
	s_waitcnt vmcnt(26)
	v_lshlrev_b32_e32 v56, 16, v20
	v_and_b32_e32 v20, 0xffff0000, v20
	v_fma_f32 v86, v4, v53, v2
	v_fma_f32 v87, v5, v17, v3
	v_fmac_f32_e32 v86, v6, v54
	v_fmac_f32_e32 v87, v7, v18
	v_fmac_f32_e32 v86, v8, v55
	v_fmac_f32_e32 v87, v9, v19
	v_fmac_f32_e32 v86, v10, v56
	v_fmac_f32_e32 v87, v11, v20
	v_cvt_pk_bf16_f32 v86, v86, v87
	ds_write_b32 v92, v86 offset:5200
	s_waitcnt vmcnt(25)
	v_lshlrev_b32_e32 v57, 16, v21
	v_and_b32_e32 v21, 0xffff0000, v21
	v_fma_f32 v84, v4, v54, v2
	v_fma_f32 v85, v5, v18, v3
	v_fmac_f32_e32 v84, v6, v55
	v_fmac_f32_e32 v85, v7, v19
	v_fmac_f32_e32 v84, v8, v56
	v_fmac_f32_e32 v85, v9, v20
	v_fmac_f32_e32 v84, v10, v57
	v_fmac_f32_e32 v85, v11, v21
	v_cvt_pk_bf16_f32 v84, v84, v85
	ds_write_b32 v92, v84 offset:6240
	s_waitcnt vmcnt(24)
	v_lshlrev_b32_e32 v58, 16, v22
	v_and_b32_e32 v22, 0xffff0000, v22
	v_fma_f32 v86, v4, v55, v2
	v_fma_f32 v87, v5, v19, v3
	v_fmac_f32_e32 v86, v6, v56
	v_fmac_f32_e32 v87, v7, v20
	v_fmac_f32_e32 v86, v8, v57
	v_fmac_f32_e32 v87, v9, v21
	v_fmac_f32_e32 v86, v10, v58
	v_fmac_f32_e32 v87, v11, v22
	v_cvt_pk_bf16_f32 v86, v86, v87
	ds_write_b32 v92, v86 offset:7280
	s_waitcnt vmcnt(23)
	v_lshlrev_b32_e32 v59, 16, v23
	v_and_b32_e32 v23, 0xffff0000, v23
	v_fma_f32 v84, v4, v56, v2
	v_fma_f32 v85, v5, v20, v3
	v_fmac_f32_e32 v84, v6, v57
	v_fmac_f32_e32 v85, v7, v21
	v_fmac_f32_e32 v84, v8, v58
	v_fmac_f32_e32 v85, v9, v22
	v_fmac_f32_e32 v84, v10, v59
	v_fmac_f32_e32 v85, v11, v23
	v_cvt_pk_bf16_f32 v84, v84, v85
	ds_write_b32 v92, v84 offset:8320
	s_waitcnt vmcnt(22)
	v_lshlrev_b32_e32 v60, 16, v24
	v_and_b32_e32 v24, 0xffff0000, v24
	v_fma_f32 v86, v4, v57, v2
	v_fma_f32 v87, v5, v21, v3
	v_fmac_f32_e32 v86, v6, v58
	v_fmac_f32_e32 v87, v7, v22
	v_fmac_f32_e32 v86, v8, v59
	v_fmac_f32_e32 v87, v9, v23
	v_fmac_f32_e32 v86, v10, v60
	v_fmac_f32_e32 v87, v11, v24
	v_cvt_pk_bf16_f32 v86, v86, v87
	ds_write_b32 v92, v86 offset:9360
	s_waitcnt vmcnt(21)
	v_lshlrev_b32_e32 v61, 16, v25
	v_and_b32_e32 v25, 0xffff0000, v25
	v_fma_f32 v84, v4, v58, v2
	v_fma_f32 v85, v5, v22, v3
	v_fmac_f32_e32 v84, v6, v59
	v_fmac_f32_e32 v85, v7, v23
	v_fmac_f32_e32 v84, v8, v60
	v_fmac_f32_e32 v85, v9, v24
	v_fmac_f32_e32 v84, v10, v61
	v_fmac_f32_e32 v85, v11, v25
	v_cvt_pk_bf16_f32 v84, v84, v85
	ds_write_b32 v92, v84 offset:10400
	s_waitcnt vmcnt(20)
	v_lshlrev_b32_e32 v62, 16, v26
	v_and_b32_e32 v26, 0xffff0000, v26
	v_fma_f32 v86, v4, v59, v2
	v_fma_f32 v87, v5, v23, v3
	v_fmac_f32_e32 v86, v6, v60
	v_fmac_f32_e32 v87, v7, v24
	v_fmac_f32_e32 v86, v8, v61
	v_fmac_f32_e32 v87, v9, v25
	v_fmac_f32_e32 v86, v10, v62
	v_fmac_f32_e32 v87, v11, v26
	v_cvt_pk_bf16_f32 v86, v86, v87
	ds_write_b32 v92, v86 offset:11440
	s_waitcnt vmcnt(19)
	v_lshlrev_b32_e32 v63, 16, v27
	v_and_b32_e32 v27, 0xffff0000, v27
	v_fma_f32 v84, v4, v60, v2
	v_fma_f32 v85, v5, v24, v3
	v_fmac_f32_e32 v84, v6, v61
	v_fmac_f32_e32 v85, v7, v25
	v_fmac_f32_e32 v84, v8, v62
	v_fmac_f32_e32 v85, v9, v26
	v_fmac_f32_e32 v84, v10, v63
	v_fmac_f32_e32 v85, v11, v27
	v_cvt_pk_bf16_f32 v84, v84, v85
	ds_write_b32 v92, v84 offset:12480
	s_waitcnt vmcnt(18)
	v_lshlrev_b32_e32 v64, 16, v28
	v_and_b32_e32 v28, 0xffff0000, v28
	v_fma_f32 v86, v4, v61, v2
	v_fma_f32 v87, v5, v25, v3
	v_fmac_f32_e32 v86, v6, v62
	v_fmac_f32_e32 v87, v7, v26
	v_fmac_f32_e32 v86, v8, v63
	v_fmac_f32_e32 v87, v9, v27
	v_fmac_f32_e32 v86, v10, v64
	v_fmac_f32_e32 v87, v11, v28
	v_cvt_pk_bf16_f32 v86, v86, v87
	ds_write_b32 v92, v86 offset:13520
	s_waitcnt vmcnt(17)
	v_lshlrev_b32_e32 v65, 16, v29
	v_and_b32_e32 v29, 0xffff0000, v29
	v_fma_f32 v84, v4, v62, v2
	v_fma_f32 v85, v5, v26, v3
	v_fmac_f32_e32 v84, v6, v63
	v_fmac_f32_e32 v85, v7, v27
	v_fmac_f32_e32 v84, v8, v64
	v_fmac_f32_e32 v85, v9, v28
	v_fmac_f32_e32 v84, v10, v65
	v_fmac_f32_e32 v85, v11, v29
	v_cvt_pk_bf16_f32 v84, v84, v85
	ds_write_b32 v92, v84 offset:14560
	s_waitcnt vmcnt(16)
	v_lshlrev_b32_e32 v66, 16, v30
	v_and_b32_e32 v30, 0xffff0000, v30
	v_fma_f32 v86, v4, v63, v2
	v_fma_f32 v87, v5, v27, v3
	v_fmac_f32_e32 v86, v6, v64
	v_fmac_f32_e32 v87, v7, v28
	v_fmac_f32_e32 v86, v8, v65
	v_fmac_f32_e32 v87, v9, v29
	v_fmac_f32_e32 v86, v10, v66
	v_fmac_f32_e32 v87, v11, v30
	v_cvt_pk_bf16_f32 v86, v86, v87
	ds_write_b32 v92, v86 offset:15600
	s_waitcnt vmcnt(15)
	v_lshlrev_b32_e32 v67, 16, v31
	v_and_b32_e32 v31, 0xffff0000, v31
	v_fma_f32 v84, v4, v64, v2
	v_fma_f32 v85, v5, v28, v3
	v_fmac_f32_e32 v84, v6, v65
	v_fmac_f32_e32 v85, v7, v29
	v_fmac_f32_e32 v84, v8, v66
	v_fmac_f32_e32 v85, v9, v30
	v_fmac_f32_e32 v84, v10, v67
	v_fmac_f32_e32 v85, v11, v31
	v_cvt_pk_bf16_f32 v84, v84, v85
	ds_write_b32 v92, v84 offset:16640
	s_waitcnt vmcnt(14)
; __device__ __forceinline__ float bf2f(bf16_t b) { return __uint_as_float(((unsigned)b) << 16); }
; __device__ __forceinline__ bf16_t f2bf(float f) { unsigned u = __float_as_uint(f); return (bf16_t)((u + 0x7fffu + ((u >> 16) & 1u)) >> 16); }
; template <int MODE> __device__ void mixer_lru(const Params& p, int l, int n, LAS unsigned char* lds) {
;     ...
; #pragma unroll
;             for (int i = 0; i < 67; ++i) { const int s_ = t0 - 2 + i; const int sc = s_ < 0 ? 0 : (s_ >= S ? S - 1 : s_); const bf16_t v = proj[(size_t)sc * DINP + ch]; xs[i] = s_ == sc ? v : (bf16_t)0; }
; #pragma unroll
;             for (int t = 0; t < 64; ++t) { const float xc = cb + cw0 * bf2f(xs[t]) + cw1 * bf2f(xs[t + 1]) + cw2 * bf2f(xs[t + 2]) + cw3 * bf2f(xs[t + 3]); XC[t * 520 + ch] = f2bf(xc); }
	v_lshlrev_b32_e32 v68, 16, v32
	v_and_b32_e32 v32, 0xffff0000, v32
	v_fma_f32 v86, v4, v65, v2
	v_fma_f32 v87, v5, v29, v3
	v_fmac_f32_e32 v86, v6, v66
	v_fmac_f32_e32 v87, v7, v30
	v_fmac_f32_e32 v86, v8, v67
	v_fmac_f32_e32 v87, v9, v31
	v_fmac_f32_e32 v86, v10, v68
	v_fmac_f32_e32 v87, v11, v32
	v_cvt_pk_bf16_f32 v86, v86, v87
	ds_write_b32 v92, v86 offset:17680
	s_waitcnt vmcnt(13)
	v_lshlrev_b32_e32 v69, 16, v33
	v_and_b32_e32 v33, 0xffff0000, v33
	v_fma_f32 v84, v4, v66, v2
	v_fma_f32 v85, v5, v30, v3
	v_fmac_f32_e32 v84, v6, v67
	v_fmac_f32_e32 v85, v7, v31
	v_fmac_f32_e32 v84, v8, v68
	v_fmac_f32_e32 v85, v9, v32
	v_fmac_f32_e32 v84, v10, v69
	v_fmac_f32_e32 v85, v11, v33
	v_cvt_pk_bf16_f32 v84, v84, v85
	ds_write_b32 v92, v84 offset:18720
	s_waitcnt vmcnt(12)
	v_lshlrev_b32_e32 v70, 16, v34
	v_and_b32_e32 v34, 0xffff0000, v34
	v_fma_f32 v86, v4, v67, v2
	v_fma_f32 v87, v5, v31, v3
	v_fmac_f32_e32 v86, v6, v68
	v_fmac_f32_e32 v87, v7, v32
	v_fmac_f32_e32 v86, v8, v69
	v_fmac_f32_e32 v87, v9, v33
	v_fmac_f32_e32 v86, v10, v70
	v_fmac_f32_e32 v87, v11, v34
	v_cvt_pk_bf16_f32 v86, v86, v87
	ds_write_b32 v92, v86 offset:19760
	s_waitcnt vmcnt(11)
	v_lshlrev_b32_e32 v71, 16, v35
	v_and_b32_e32 v35, 0xffff0000, v35
	v_fma_f32 v84, v4, v68, v2
	v_fma_f32 v85, v5, v32, v3
	v_fmac_f32_e32 v84, v6, v69
	v_fmac_f32_e32 v85, v7, v33
	v_fmac_f32_e32 v84, v8, v70
	v_fmac_f32_e32 v85, v9, v34
	v_fmac_f32_e32 v84, v10, v71
	v_fmac_f32_e32 v85, v11, v35
	v_cvt_pk_bf16_f32 v84, v84, v85
	ds_write_b32 v92, v84 offset:20800
	s_waitcnt vmcnt(10)
	v_lshlrev_b32_e32 v72, 16, v36
	v_and_b32_e32 v36, 0xffff0000, v36
	v_fma_f32 v86, v4, v69, v2
	v_fma_f32 v87, v5, v33, v3
	v_fmac_f32_e32 v86, v6, v70
	v_fmac_f32_e32 v87, v7, v34
	v_fmac_f32_e32 v86, v8, v71
	v_fmac_f32_e32 v87, v9, v35
	v_fmac_f32_e32 v86, v10, v72
	v_fmac_f32_e32 v87, v11, v36
	v_cvt_pk_bf16_f32 v86, v86, v87
	ds_write_b32 v92, v86 offset:21840
	s_waitcnt vmcnt(9)
	v_lshlrev_b32_e32 v73, 16, v37
	v_and_b32_e32 v37, 0xffff0000, v37
	v_fma_f32 v84, v4, v70, v2
	v_fma_f32 v85, v5, v34, v3
	v_fmac_f32_e32 v84, v6, v71
	v_fmac_f32_e32 v85, v7, v35
	v_fmac_f32_e32 v84, v8, v72
	v_fmac_f32_e32 v85, v9, v36
	v_fmac_f32_e32 v84, v10, v73
	v_fmac_f32_e32 v85, v11, v37
	v_cvt_pk_bf16_f32 v84, v84, v85
	ds_write_b32 v92, v84 offset:22880
	s_waitcnt vmcnt(8)
	v_lshlrev_b32_e32 v74, 16, v38
	v_and_b32_e32 v38, 0xffff0000, v38
	v_fma_f32 v86, v4, v71, v2
	v_fma_f32 v87, v5, v35, v3
	v_fmac_f32_e32 v86, v6, v72
	v_fmac_f32_e32 v87, v7, v36
	v_fmac_f32_e32 v86, v8, v73
	v_fmac_f32_e32 v87, v9, v37
	v_fmac_f32_e32 v86, v10, v74
	v_fmac_f32_e32 v87, v11, v38
	v_cvt_pk_bf16_f32 v86, v86, v87
	ds_write_b32 v92, v86 offset:23920
	s_waitcnt vmcnt(7)
	v_lshlrev_b32_e32 v75, 16, v39
	v_and_b32_e32 v39, 0xffff0000, v39
	v_fma_f32 v84, v4, v72, v2
	v_fma_f32 v85, v5, v36, v3
	v_fmac_f32_e32 v84, v6, v73
	v_fmac_f32_e32 v85, v7, v37
	v_fmac_f32_e32 v84, v8, v74
	v_fmac_f32_e32 v85, v9, v38
	v_fmac_f32_e32 v84, v10, v75
	v_fmac_f32_e32 v85, v11, v39
	v_cvt_pk_bf16_f32 v84, v84, v85
	ds_write_b32 v92, v84 offset:24960
	s_waitcnt vmcnt(6)
	v_lshlrev_b32_e32 v76, 16, v40
	v_and_b32_e32 v40, 0xffff0000, v40
	v_fma_f32 v86, v4, v73, v2
	v_fma_f32 v87, v5, v37, v3
	v_fmac_f32_e32 v86, v6, v74
	v_fmac_f32_e32 v87, v7, v38
	v_fmac_f32_e32 v86, v8, v75
	v_fmac_f32_e32 v87, v9, v39
	v_fmac_f32_e32 v86, v10, v76
	v_fmac_f32_e32 v87, v11, v40
	v_cvt_pk_bf16_f32 v86, v86, v87
	ds_write_b32 v92, v86 offset:26000
	s_waitcnt vmcnt(5)
	v_lshlrev_b32_e32 v77, 16, v41
	v_and_b32_e32 v41, 0xffff0000, v41
	v_fma_f32 v84, v4, v74, v2
	v_fma_f32 v85, v5, v38, v3
	v_fmac_f32_e32 v84, v6, v75
	v_fmac_f32_e32 v85, v7, v39
	v_fmac_f32_e32 v84, v8, v76
	v_fmac_f32_e32 v85, v9, v40
	v_fmac_f32_e32 v84, v10, v77
	v_fmac_f32_e32 v85, v11, v41
	v_cvt_pk_bf16_f32 v84, v84, v85
	ds_write_b32 v92, v84 offset:27040
	s_waitcnt vmcnt(4)
	v_lshlrev_b32_e32 v78, 16, v42
	v_and_b32_e32 v42, 0xffff0000, v42
	v_fma_f32 v86, v4, v75, v2
	v_fma_f32 v87, v5, v39, v3
	v_fmac_f32_e32 v86, v6, v76
	v_fmac_f32_e32 v87, v7, v40
	v_fmac_f32_e32 v86, v8, v77
	v_fmac_f32_e32 v87, v9, v41
	v_fmac_f32_e32 v86, v10, v78
	v_fmac_f32_e32 v87, v11, v42
	v_cvt_pk_bf16_f32 v86, v86, v87
	ds_write_b32 v92, v86 offset:28080
	s_waitcnt vmcnt(3)
	v_lshlrev_b32_e32 v79, 16, v43
	v_and_b32_e32 v43, 0xffff0000, v43
	v_fma_f32 v84, v4, v76, v2
	v_fma_f32 v85, v5, v40, v3
	v_fmac_f32_e32 v84, v6, v77
	v_fmac_f32_e32 v85, v7, v41
	v_fmac_f32_e32 v84, v8, v78
	v_fmac_f32_e32 v85, v9, v42
	v_fmac_f32_e32 v84, v10, v79
	v_fmac_f32_e32 v85, v11, v43
	v_cvt_pk_bf16_f32 v84, v84, v85
	ds_write_b32 v92, v84 offset:29120
	s_waitcnt vmcnt(2)
	v_lshlrev_b32_e32 v80, 16, v44
	v_and_b32_e32 v44, 0xffff0000, v44
	v_fma_f32 v86, v4, v77, v2
	v_fma_f32 v87, v5, v41, v3
	v_fmac_f32_e32 v86, v6, v78
	v_fmac_f32_e32 v87, v7, v42
	v_fmac_f32_e32 v86, v8, v79
	v_fmac_f32_e32 v87, v9, v43
	v_fmac_f32_e32 v86, v10, v80
	v_fmac_f32_e32 v87, v11, v44
	v_cvt_pk_bf16_f32 v86, v86, v87
	ds_write_b32 v92, v86 offset:30160
	s_waitcnt vmcnt(1)
	v_lshlrev_b32_e32 v81, 16, v45
	v_and_b32_e32 v45, 0xffff0000, v45
	v_fma_f32 v84, v4, v78, v2
	v_fma_f32 v85, v5, v42, v3
	v_fmac_f32_e32 v84, v6, v79
	v_fmac_f32_e32 v85, v7, v43
	v_fmac_f32_e32 v84, v8, v80
	v_fmac_f32_e32 v85, v9, v44
	v_fmac_f32_e32 v84, v10, v81
	v_fmac_f32_e32 v85, v11, v45
	v_cvt_pk_bf16_f32 v84, v84, v85
	ds_write_b32 v92, v84 offset:31200
	s_waitcnt vmcnt(0)
	v_and_b32_e32 v46, s94, v46
	v_lshlrev_b32_e32 v82, 16, v46
	v_and_b32_e32 v46, 0xffff0000, v46
	v_fma_f32 v86, v4, v79, v2
	v_fma_f32 v87, v5, v43, v3
	v_fmac_f32_e32 v86, v6, v80
	v_fmac_f32_e32 v87, v7, v44
	v_fmac_f32_e32 v86, v8, v81
	v_fmac_f32_e32 v87, v9, v45
	v_fmac_f32_e32 v86, v10, v82
	v_fmac_f32_e32 v87, v11, v46
	v_cvt_pk_bf16_f32 v86, v86, v87
	ds_write_b32 v92, v86 offset:32240
	v_ashrrev_i32_e32 v102, 6, v100
	v_ashrrev_i32_e32 v103, 31, v102
	v_and_b32_e32 v127, 15, v100
	v_and_b32_e32 v124, 0xffffffc0, v100
	v_ashrrev_i32_e32 v125, 31, v124
	v_lshlrev_b32_e32 v176, 7, v127
	v_readlane_b32 s0, v254, 17
	v_lshlrev_b64 v[6:7], 13, v[102:103]
	v_readlane_b32 s1, v254, 18
	s_nop 1
	v_lshlrev_b64 v[112:113], 2, v[124:125]
	v_lshl_add_u64 v[114:115], s[0:1], 0, v[6:7]
	v_lshl_add_u64 v[6:7], v[114:115], 0, v[176:177]
	v_and_b32_e32 v176, 48, v100
	v_lshl_add_u64 v[0:1], s[16:17], 0, v[112:113]
	v_lshl_add_u64 v[80:81], v[6:7], 0, v[176:177]
	v_lshl_add_u64 v[76:77], v[0:1], 0, v[176:177]
	v_add_co_u32_e32 v0, vcc, 0x10000, v80
	v_lshl_add_u64 v[2:3], s[18:19], 0, v[112:113]
	v_lshl_add_u64 v[4:5], s[20:21], 0, v[112:113]
	s_mov_b64 s[0:1], 0x10000
	v_addc_co_u32_e32 v1, vcc, 0, v81, vcc
	s_waitcnt lgkmcnt(0)
	s_barrier
; template <int DIR> __device__ __forceinline__ void lru_dir(const Params& p, int l, int n, int h, int lane, LAS bf16_t* XC, LAS float* STA, LAS float* STU) {
;     ...
;     const bf16_t* LWa = LW + ((size_t)(DIR * 2 + 0) * 8 + h) * 4096 + c * 64 + 8 * q; const bf16_t* LWx = LW + ((size_t)(DIR * 2 + 1) * 8 + h) * 4096 + c * 64 + 8 * q;
;     bf16x8 wa[4][2], wx[4][2]; f32x4 sp4[4], ba4[4], bx4[4];
; #pragma unroll
;     for (int nf = 0; nf < 4; ++nf) {
; #pragma unroll
;         for (int ks = 0; ks < 2; ++ks) { wa[nf][ks] = *(const bf16x8*)(LWa + nf * 1024 + 32 * ks); wx[nf][ks] = *(const bf16x8*)(LWx + nf * 1024 + 32 * ks); }
;         const f32x4 lam4 = *(const f32x4*)(lam + 16 * nf + 4 * q); ba4[nf] = *(const f32x4*)(b_a + 16 * nf + 4 * q); bx4[nf] = *(const f32x4*)(b_x + 16 * nf + 4 * q);
; #pragma unroll
;         for (int r = 0; r < 4; ++r) { const float e = __expf(-lam4[r]); const float l1p = e < 0.05f ? e * (1.0f - e * (0.5f - e * (0.33333334f - e * 0.25f))) : __logf(1.0f + e); sp4[nf][r] = -8.0f * l1p; }
	v_lshl_add_u64 v[78:79], v[80:81], 0, s[0:1]
	v_lshl_add_u64 v[88:89], v[2:3], 0, v[176:177]
	v_lshl_add_u64 v[92:93], v[4:5], 0, v[176:177]
	global_load_dwordx4 v[24:27], v[76:77], off
	s_nop 0
	global_load_dwordx4 v[0:3], v[0:1], off
	s_nop 0
	global_load_dwordx4 v[4:7], v[80:81], off
	global_load_dwordx4 v[8:11], v[80:81], off offset:64
	global_load_dwordx4 v[12:15], v[78:79], off offset:64
	global_load_dwordx4 v[16:19], v[88:89], off
	global_load_dwordx4 v[20:23], v[92:93], off
	s_mov_b32 s6, 0x3d4ccccd
	s_waitcnt vmcnt(6)
	v_mul_f32_e32 v24, 0xbfb8aa3b, v24
	v_exp_f32_e32 v24, v24
	s_nop 0
	v_cmp_ngt_f32_e32 vcc, s6, v24
	s_and_saveexec_b64 s[0:1], vcc
	s_xor_b64 s[30:31], exec, s[0:1]
	s_cbranch_execz .LBB0_194
	v_add_f32_e32 v24, 1.0, v24
	v_cmp_gt_f32_e32 vcc, s25, v24
	s_nop 1
	v_cndmask_b32_e64 v28, 0, 32, vcc
	v_ldexp_f32 v24, v24, v28
	v_log_f32_e32 v24, v24
	s_nop 0
	v_mul_f32_e32 v28, 0x3f317217, v24
	v_fma_f32 v28, v24, s36, -v28
	v_fmac_f32_e32 v28, 0x3377d1cf, v24
	v_fmac_f32_e32 v28, 0x3f317217, v24
	v_cmp_lt_f32_e64 s[0:1], |v24|, s37
	s_nop 1
	v_cndmask_b32_e64 v24, v24, v28, s[0:1]
	v_cndmask_b32_e32 v28, 0, v232, vcc
	v_sub_f32_e32 v101, v24, v28

; #define LAS __attribute__((address_space(3)))
; __device__ __forceinline__ float sigmoidf_(float x) { return __builtin_amdgcn_rcpf(1.0f + __expf(-x)); }
; __device__ __forceinline__ f32x4 mfma16(bf16x8 a, bf16x8 b, f32x4 c) { return __builtin_amdgcn_mfma_f32_16x16x32_bf16(a, b, c, 0, 0, 0); }
; template <int DIR> __device__ __forceinline__ void lru_dir(const Params& p, int l, int n, int h, int lane, LAS bf16_t* XC, LAS float* STA, LAS float* STU) {
;     ...
;         for (int r = 0; r < 4; ++r) { const float e = __expf(-lam4[r]); const float l1p = e < 0.05f ? e * (1.0f - e * (0.5f - e * (0.33333334f - e * 0.25f))) : __logf(1.0f + e); sp4[nf][r] = -8.0f * l1p; }
;     }
;     float hcar = 0.f, P = 1.f;
; #pragma unroll 1
;     for (int g = 0; g < 4; ++g) {
;         const int mi = DIR == 0 ? g : 3 - g;
;         bf16_t hfp[16];
;         if (DIR == 1) {
; #pragma unroll
;             for (int s = 0; s < 16; ++s) hfp[s] = y[(size_t)(t0 + 16 * mi + s) * D + 64 * h + j];
;         }
;         bf16x8 xf[2];
; #pragma unroll
;         for (int ks = 0; ks < 2; ++ks) xf[ks] = *(const LAS bf16x8*)(XC + (16 * mi + c) * 520 + 64 * h + 32 * ks + 8 * q);
;         f32x4 za[4], zx[4];
; #pragma unroll
;         for (int nf = 0; nf < 4; ++nf) { za[nf] = (f32x4){0.f, 0.f, 0.f, 0.f}; zx[nf] = za[nf];
;             za[nf] = mfma16(wa[nf][0], xf[0], za[nf]); za[nf] = mfma16(wa[nf][1], xf[1], za[nf]);
;             zx[nf] = mfma16(wx[nf][0], xf[0], zx[nf]); zx[nf] = mfma16(wx[nf][1], xf[1], zx[nf]); }
; #pragma unroll
;         for (int nf = 0; nf < 4; ++nf) {
;             const int jo = 16 * nf + 4 * q;
;             const bf16x4 xc4 = *(const LAS bf16x4*)(XC + (16 * mi + c) * 520 + 64 * h + jo);
;             const f32x4 zav = za[nf] + ba4[nf], zxv = zx[nf] + bx4[nf];
;             f32x4 av, uv;
; #pragma unroll
;             for (int r = 0; r < 4; ++r) {
;                 const float ra = sigmoidf_(zav[r]), ix = sigmoidf_(zxv[r]);
;                 const float la = ra * sp4[nf][r];
;                 av[r] = __expf(la);
;                 const float x2 = 2.0f * la;
;                 const float om = -x2 * (1.0f + x2 * (0.5f + x2 * (0.16666667f + x2 * (0.041666668f + x2 * (0.0083333338f + x2 * (0.0013888889f + x2 * 0.0001984127f))))));
.LBB0_254:
	s_andn2_saveexec_b64 s[0:1], s[30:31]
	v_fmamk_f32 v99, v118, 0xbe800000, v226
	v_fma_f32 v99, -v118, v99, 0.5
	v_fma_f32 v99, -v118, v99, 1.0
	v_mul_f32_e32 v99, v118, v99
	s_or_b64 exec, exec, s[0:1]
	s_movk_i32 s0, 0x2200
	v_bfe_u32 v128, v100, 4, 2
	v_mul_f32_e32 v136, 0xc1000000, v96
	v_mul_lo_u32 v96, v102, s0
	v_readlane_b32 s0, v254, 23
	s_ashr_i32 s29, s28, 31
	v_and_b32_e32 v126, 63, v100
	v_lshlrev_b32_e32 v132, 2, v128
	v_mul_f32_e32 v135, 0xc1000000, v97
	v_add_u32_e32 v96, s0, v96
	v_mul_u32_u24_e32 v97, 0x44, v127
	s_lshl_b64 s[0:1], s[28:29], 11
	v_lshlrev_b64 v[118:119], 1, v[124:125]
	v_mul_f32_e32 v137, 0xc1000000, v117
	v_mul_f32_e32 v138, 0xc1000000, v116
	v_lshlrev_b32_e32 v97, 2, v97
	v_lshlrev_b32_e32 v120, 2, v132
	v_lshl_add_u64 v[116:117], s[0:1], 0, v[118:119]
	v_lshlrev_b32_e32 v176, 1, v126
	v_add3_u32 v154, v96, v97, v120
	v_lshl_add_u32 v155, v126, 2, v96
	v_lshl_add_u64 v[96:97], v[116:117], 0, v[176:177]
	v_lshl_add_u64 v[122:123], s[56:57], 0, v[96:97]
	v_lshlrev_b32_e32 v96, 1, v100
	v_and_b32_e32 v96, 0xffffff80, v96
	v_lshlrev_b32_e32 v133, 3, v128
	v_mad_u32_u24 v96, v127, s7, v96
	v_lshlrev_b32_e32 v97, 4, v128
	v_lshlrev_b32_e32 v121, 6, v127
	v_mul_f32_e32 v134, 0xc1000000, v98
	v_mul_f32_e32 v139, 0xc1000000, v111
	v_mul_f32_e32 v140, 0xc1000000, v110
	v_mul_f32_e32 v141, 0xc1000000, v109
	v_mul_f32_e32 v142, 0xc1000000, v108
	v_mul_f32_e32 v143, 0xc1000000, v107
	v_mul_f32_e32 v144, 0xc1000000, v106
	v_mul_f32_e32 v145, 0xc1000000, v105
	v_mul_f32_e32 v146, 0xc1000000, v104
	v_mul_f32_e32 v147, 0xc1000000, v103
	v_mul_f32_e32 v148, 0xc1000000, v101
	v_mul_f32_e32 v149, 0xc1000000, v99
	v_add3_u32 v150, v96, v97, 0
	v_add3_u32 v151, v96, v133, 0
	v_mov_b32_e32 v129, 1.0
	v_mov_b32_e32 v130, 0
	s_mov_b64 s[0:1], 0
	s_waitcnt vmcnt(0)
	s_lshl_b32 s64, s28, 11
	s_add_u32 s66, s56, s64
	s_addc_u32 s67, s57, 0
	s_add_u32 s66, s66, 0x1859000
	s_addc_u32 s67, s67, 0
	v_lshlrev_b32_e32 v220, 1, v245
.Llru0_loop:
	ds_read_b128 v[172:175], v150
	ds_read_b128 v[178:181], v150 offset:64
	ds_read_b64 v[182:183], v151
	ds_read_b64 v[184:185], v151 offset:32
	ds_read_b64 v[186:187], v151 offset:64
	ds_read_b64 v[188:189], v151 offset:96
	s_add_u32 s64, s66, s0
	s_addc_u32 s65, s67, 0
	s_waitcnt lgkmcnt(4)
	v_mfma_f32_16x16x32_bf16 v[156:159], v[4:7], v[172:175], 0
	v_mfma_f32_16x16x32_bf16 v[96:99], v[0:3], v[172:175], 0
	v_mfma_f32_16x16x32_bf16 v[160:163], v[24:27], v[172:175], 0
	v_mfma_f32_16x16x32_bf16 v[100:103], v[32:35], v[172:175], 0
	v_mfma_f32_16x16x32_bf16 v[164:167], v[48:51], v[172:175], 0
	v_mfma_f32_16x16x32_bf16 v[104:107], v[56:59], v[172:175], 0
	v_mfma_f32_16x16x32_bf16 v[168:171], v[72:75], v[172:175], 0
	v_mfma_f32_16x16x32_bf16 v[108:111], v[80:83], v[172:175], 0
	v_mfma_f32_16x16x32_bf16 v[156:159], v[8:11], v[178:181], v[156:159]
	v_mfma_f32_16x16x32_bf16 v[96:99], v[12:15], v[178:181], v[96:99]
	v_mfma_f32_16x16x32_bf16 v[160:163], v[28:31], v[178:181], v[160:163]
	v_mfma_f32_16x16x32_bf16 v[100:103], v[36:39], v[178:181], v[100:103]
	v_mfma_f32_16x16x32_bf16 v[164:167], v[52:55], v[178:181], v[164:167]
	v_mfma_f32_16x16x32_bf16 v[104:107], v[60:63], v[178:181], v[104:107]
	v_mfma_f32_16x16x32_bf16 v[168:171], v[76:79], v[178:181], v[168:171]
	v_mfma_f32_16x16x32_bf16 v[108:111], v[84:87], v[178:181], v[108:111]
	s_waitcnt lgkmcnt(0)
	v_lshlrev_b32_e32 v204, 16, v182
	v_and_b32_e32 v205, 0xffff0000, v182
	v_lshlrev_b32_e32 v206, 16, v183
	v_and_b32_e32 v207, 0xffff0000, v183
	v_lshlrev_b32_e32 v208, 16, v184
	v_and_b32_e32 v209, 0xffff0000, v184
	v_lshlrev_b32_e32 v210, 16, v185
	v_and_b32_e32 v211, 0xffff0000, v185
	v_lshlrev_b32_e32 v212, 16, v186
	v_and_b32_e32 v213, 0xffff0000, v186
	v_lshlrev_b32_e32 v214, 16, v187
	v_and_b32_e32 v215, 0xffff0000, v187
	v_lshlrev_b32_e32 v216, 16, v188
	v_and_b32_e32 v217, 0xffff0000, v188
	v_lshlrev_b32_e32 v218, 16, v189
	v_and_b32_e32 v219, 0xffff0000, v189
	v_add_f32_e32 v192, v16, v156
	v_add_f32_e32 v195, v17, v157
	v_add_f32_e32 v198, v18, v158
	v_add_f32_e32 v201, v19, v159
	v_add_f32_e32 v193, v20, v96
	v_add_f32_e32 v196, v21, v97
	v_add_f32_e32 v199, v22, v98
	v_add_f32_e32 v202, v23, v99
	v_mul_f32_e32 v192, 0xbfb8aa3b, v192
	v_mul_f32_e32 v195, 0xbfb8aa3b, v195
	v_mul_f32_e32 v198, 0xbfb8aa3b, v198
	v_mul_f32_e32 v201, 0xbfb8aa3b, v201
	v_mul_f32_e32 v193, 0xbfb8aa3b, v193
	v_mul_f32_e32 v196, 0xbfb8aa3b, v196
	v_mul_f32_e32 v199, 0xbfb8aa3b, v199
	v_mul_f32_e32 v202, 0xbfb8aa3b, v202
	v_exp_f32_e32 v192, v192
	v_exp_f32_e32 v195, v195
	v_exp_f32_e32 v198, v198
	v_exp_f32_e32 v201, v201
	v_exp_f32_e32 v193, v193
	v_exp_f32_e32 v196, v196
	v_exp_f32_e32 v199, v199
	v_exp_f32_e32 v202, v202
	v_add_f32_e32 v192, 1.0, v192
	v_add_f32_e32 v195, 1.0, v195
	v_add_f32_e32 v198, 1.0, v198
	v_add_f32_e32 v201, 1.0, v201
	v_add_f32_e32 v193, 1.0, v193
	v_add_f32_e32 v196, 1.0, v196
	v_add_f32_e32 v199, 1.0, v199
	v_add_f32_e32 v202, 1.0, v202
	v_rcp_f32_e32 v192, v192
	v_rcp_f32_e32 v195, v195
	v_rcp_f32_e32 v198, v198
	v_rcp_f32_e32 v201, v201
	v_rcp_f32_e32 v193, v193
	v_rcp_f32_e32 v196, v196
	v_rcp_f32_e32 v199, v199
	v_rcp_f32_e32 v202, v202
	v_mul_f32_e32 v192, v148, v192
	v_mul_f32_e32 v195, v147, v195
	v_mul_f32_e32 v198, v146, v198
	v_mul_f32_e32 v201, v145, v201
	v_mul_f32_e32 v194, 0x3fb8aa3b, v192
	v_mul_f32_e32 v197, 0x3fb8aa3b, v195
	v_mul_f32_e32 v200, 0x3fb8aa3b, v198
	v_mul_f32_e32 v203, 0x3fb8aa3b, v201
	v_add_f32_e32 v192, v192, v192
	v_add_f32_e32 v195, v195, v195
	v_add_f32_e32 v198, v198, v198
	v_add_f32_e32 v201, v201, v201
	v_exp_f32_e32 v156, v194
	v_exp_f32_e32 v157, v197
	v_exp_f32_e32 v158, v200
; #define LAS __attribute__((address_space(3)))
; __device__ __forceinline__ float bf2f(bf16_t b) { return __uint_as_float(((unsigned)b) << 16); }
; __device__ __forceinline__ float sigmoidf_(float x) { return __builtin_amdgcn_rcpf(1.0f + __expf(-x)); }
; template <int DIR> __device__ __forceinline__ void lru_dir(const Params& p, int l, int n, int h, int lane, LAS bf16_t* XC, LAS float* STA, LAS float* STU) {
;     ...
;         for (int nf = 0; nf < 4; ++nf) {
;             const int jo = 16 * nf + 4 * q;
;             const bf16x4 xc4 = *(const LAS bf16x4*)(XC + (16 * mi + c) * 520 + 64 * h + jo);
;             const f32x4 zav = za[nf] + ba4[nf], zxv = zx[nf] + bx4[nf];
;             f32x4 av, uv;
; #pragma unroll
;             for (int r = 0; r < 4; ++r) {
;                 const float ra = sigmoidf_(zav[r]), ix = sigmoidf_(zxv[r]);
;                 const float la = ra * sp4[nf][r];
;                 av[r] = __expf(la);
;                 const float x2 = 2.0f * la;
;                 const float om = -x2 * (1.0f + x2 * (0.5f + x2 * (0.16666667f + x2 * (0.041666668f + x2 * (0.0083333338f + x2 * (0.0013888889f + x2 * 0.0001984127f))))));
;                 uv[r] = bf2f((bf16_t)xc4[r]) * ix * __builtin_amdgcn_sqrtf(fmaxf(om, 0.f));
;             }
;             *(LAS f32x4*)(STA + c * 68 + jo) = av; *(LAS f32x4*)(STU + c * 68 + jo) = uv;
	v_exp_f32_e32 v159, v203
	v_fmamk_f32 v194, v192, 0x39500d01, v227
	v_fmamk_f32 v197, v195, 0x39500d01, v227
	v_fmamk_f32 v200, v198, 0x39500d01, v227
	v_fmamk_f32 v203, v201, 0x39500d01, v227
	v_fmaak_f32 v194, v192, v194, 0x3c088889
	v_fmaak_f32 v197, v195, v197, 0x3c088889
	v_fmaak_f32 v200, v198, v200, 0x3c088889
	v_fmaak_f32 v203, v201, v203, 0x3c088889
	v_fmaak_f32 v194, v192, v194, 0x3d2aaaab
	v_fmaak_f32 v197, v195, v197, 0x3d2aaaab
	v_fmaak_f32 v200, v198, v200, 0x3d2aaaab
	v_fmaak_f32 v203, v201, v203, 0x3d2aaaab
	v_fmaak_f32 v194, v192, v194, 0x3e2aaaab
	v_fmaak_f32 v197, v195, v197, 0x3e2aaaab
	v_fmaak_f32 v200, v198, v200, 0x3e2aaaab
	v_fmaak_f32 v203, v201, v203, 0x3e2aaaab
	v_fma_f32 v194, v192, v194, 0.5
	v_fma_f32 v197, v195, v197, 0.5
	v_fma_f32 v200, v198, v200, 0.5
	v_fma_f32 v203, v201, v203, 0.5
	v_fma_f32 v194, v192, v194, 1.0
	v_fma_f32 v197, v195, v197, 1.0
	v_fma_f32 v200, v198, v200, 1.0
	v_fma_f32 v203, v201, v203, 1.0
	v_mul_f32_e64 v192, v194, -v192
	v_mul_f32_e64 v195, v197, -v195
	v_mul_f32_e64 v198, v200, -v198
	v_mul_f32_e64 v201, v203, -v201
	v_max_f32_e32 v192, 0, v192
	v_max_f32_e32 v195, 0, v195
	v_max_f32_e32 v198, 0, v198
	v_max_f32_e32 v201, 0, v201
	v_sqrt_f32_e32 v192, v192
	v_sqrt_f32_e32 v195, v195
	v_sqrt_f32_e32 v198, v198
	v_sqrt_f32_e32 v201, v201
	v_mul_f32_e32 v193, v193, v204
	v_mul_f32_e32 v196, v196, v205
	v_mul_f32_e32 v199, v199, v206
	v_mul_f32_e32 v202, v202, v207
	v_mul_f32_e32 v96, v193, v192
	v_mul_f32_e32 v97, v196, v195
	v_mul_f32_e32 v98, v199, v198
	v_mul_f32_e32 v99, v202, v201
	ds_write_b128 v154, v[156:159]
	ds_write_b128 v154, v[96:99] offset:4352
	v_add_f32_e32 v192, v40, v160
	v_add_f32_e32 v195, v41, v161
	v_add_f32_e32 v198, v42, v162
	v_add_f32_e32 v201, v43, v163
	v_add_f32_e32 v193, v44, v100
	v_add_f32_e32 v196, v45, v101
	v_add_f32_e32 v199, v46, v102
	v_add_f32_e32 v202, v47, v103
	v_mul_f32_e32 v192, 0xbfb8aa3b, v192
	v_mul_f32_e32 v195, 0xbfb8aa3b, v195
	v_mul_f32_e32 v198, 0xbfb8aa3b, v198
	v_mul_f32_e32 v201, 0xbfb8aa3b, v201
	v_mul_f32_e32 v193, 0xbfb8aa3b, v193
	v_mul_f32_e32 v196, 0xbfb8aa3b, v196
	v_mul_f32_e32 v199, 0xbfb8aa3b, v199
	v_mul_f32_e32 v202, 0xbfb8aa3b, v202
	v_exp_f32_e32 v192, v192
	v_exp_f32_e32 v195, v195
	v_exp_f32_e32 v198, v198
	v_exp_f32_e32 v201, v201
	v_exp_f32_e32 v193, v193
	v_exp_f32_e32 v196, v196
	v_exp_f32_e32 v199, v199
	v_exp_f32_e32 v202, v202
	v_add_f32_e32 v192, 1.0, v192
	v_add_f32_e32 v195, 1.0, v195
	v_add_f32_e32 v198, 1.0, v198
	v_add_f32_e32 v201, 1.0, v201
	v_add_f32_e32 v193, 1.0, v193
	v_add_f32_e32 v196, 1.0, v196
	v_add_f32_e32 v199, 1.0, v199
	v_add_f32_e32 v202, 1.0, v202
	v_rcp_f32_e32 v192, v192
	v_rcp_f32_e32 v195, v195
	v_rcp_f32_e32 v198, v198
	v_rcp_f32_e32 v201, v201
	v_rcp_f32_e32 v193, v193
	v_rcp_f32_e32 v196, v196
	v_rcp_f32_e32 v199, v199
	v_rcp_f32_e32 v202, v202
	v_mul_f32_e32 v192, v144, v192
	v_mul_f32_e32 v195, v143, v195
	v_mul_f32_e32 v198, v142, v198
	v_mul_f32_e32 v201, v141, v201
	v_mul_f32_e32 v194, 0x3fb8aa3b, v192
	v_mul_f32_e32 v197, 0x3fb8aa3b, v195
	v_mul_f32_e32 v200, 0x3fb8aa3b, v198
	v_mul_f32_e32 v203, 0x3fb8aa3b, v201
	v_add_f32_e32 v192, v192, v192
	v_add_f32_e32 v195, v195, v195
	v_add_f32_e32 v198, v198, v198
	v_add_f32_e32 v201, v201, v201
	v_exp_f32_e32 v160, v194
	v_exp_f32_e32 v161, v197
	v_exp_f32_e32 v162, v200
	v_exp_f32_e32 v163, v203
	v_fmamk_f32 v194, v192, 0x39500d01, v227
	v_fmamk_f32 v197, v195, 0x39500d01, v227
	v_fmamk_f32 v200, v198, 0x39500d01, v227
	v_fmamk_f32 v203, v201, 0x39500d01, v227
	v_fmaak_f32 v194, v192, v194, 0x3c088889
	v_fmaak_f32 v197, v195, v197, 0x3c088889
	v_fmaak_f32 v200, v198, v200, 0x3c088889
	v_fmaak_f32 v203, v201, v203, 0x3c088889
	v_fmaak_f32 v194, v192, v194, 0x3d2aaaab
	v_fmaak_f32 v197, v195, v197, 0x3d2aaaab
	v_fmaak_f32 v200, v198, v200, 0x3d2aaaab
	v_fmaak_f32 v203, v201, v203, 0x3d2aaaab
	v_fmaak_f32 v194, v192, v194, 0x3e2aaaab
	v_fmaak_f32 v197, v195, v197, 0x3e2aaaab
	v_fmaak_f32 v200, v198, v200, 0x3e2aaaab
	v_fmaak_f32 v203, v201, v203, 0x3e2aaaab
	v_fma_f32 v194, v192, v194, 0.5
	v_fma_f32 v197, v195, v197, 0.5
	v_fma_f32 v200, v198, v200, 0.5
	v_fma_f32 v203, v201, v203, 0.5
	v_fma_f32 v194, v192, v194, 1.0
	v_fma_f32 v197, v195, v197, 1.0
	v_fma_f32 v200, v198, v200, 1.0
	v_fma_f32 v203, v201, v203, 1.0
	v_mul_f32_e64 v192, v194, -v192
	v_mul_f32_e64 v195, v197, -v195
	v_mul_f32_e64 v198, v200, -v198
	v_mul_f32_e64 v201, v203, -v201
	v_max_f32_e32 v192, 0, v192
	v_max_f32_e32 v195, 0, v195
	v_max_f32_e32 v198, 0, v198
	v_max_f32_e32 v201, 0, v201
	v_sqrt_f32_e32 v192, v192
	v_sqrt_f32_e32 v195, v195
	v_sqrt_f32_e32 v198, v198
	v_sqrt_f32_e32 v201, v201
	v_mul_f32_e32 v193, v193, v208
	v_mul_f32_e32 v196, v196, v209
	v_mul_f32_e32 v199, v199, v210
	v_mul_f32_e32 v202, v202, v211
	v_mul_f32_e32 v100, v193, v192
	v_mul_f32_e32 v101, v196, v195
	v_mul_f32_e32 v102, v199, v198
	v_mul_f32_e32 v103, v202, v201
	ds_write_b128 v154, v[160:163] offset:64
	ds_write_b128 v154, v[100:103] offset:4416
	v_add_f32_e32 v192, v64, v164
	v_add_f32_e32 v195, v65, v165
	v_add_f32_e32 v198, v66, v166
	v_add_f32_e32 v201, v67, v167
	v_add_f32_e32 v193, v68, v104
	v_add_f32_e32 v196, v69, v105
	v_add_f32_e32 v199, v70, v106
	v_add_f32_e32 v202, v71, v107
	v_mul_f32_e32 v192, 0xbfb8aa3b, v192
	v_mul_f32_e32 v195, 0xbfb8aa3b, v195
	v_mul_f32_e32 v198, 0xbfb8aa3b, v198
	v_mul_f32_e32 v201, 0xbfb8aa3b, v201
	v_mul_f32_e32 v193, 0xbfb8aa3b, v193
	v_mul_f32_e32 v196, 0xbfb8aa3b, v196
	v_mul_f32_e32 v199, 0xbfb8aa3b, v199
	v_mul_f32_e32 v202, 0xbfb8aa3b, v202
	v_exp_f32_e32 v192, v192
	v_exp_f32_e32 v195, v195
	v_exp_f32_e32 v198, v198
; #define LAS __attribute__((address_space(3)))
; __device__ __forceinline__ float bf2f(bf16_t b) { return __uint_as_float(((unsigned)b) << 16); }
; __device__ __forceinline__ float sigmoidf_(float x) { return __builtin_amdgcn_rcpf(1.0f + __expf(-x)); }
; #define LDS_FENCE() asm volatile("s_waitcnt lgkmcnt(0)" ::: "memory")
; template <int DIR> __device__ __forceinline__ void lru_dir(const Params& p, int l, int n, int h, int lane, LAS bf16_t* XC, LAS float* STA, LAS float* STU) {
;     ...
;         for (int nf = 0; nf < 4; ++nf) {
;             const int jo = 16 * nf + 4 * q;
;             const bf16x4 xc4 = *(const LAS bf16x4*)(XC + (16 * mi + c) * 520 + 64 * h + jo);
;             const f32x4 zav = za[nf] + ba4[nf], zxv = zx[nf] + bx4[nf];
;             f32x4 av, uv;
; #pragma unroll
;             for (int r = 0; r < 4; ++r) {
;                 const float ra = sigmoidf_(zav[r]), ix = sigmoidf_(zxv[r]);
;                 const float la = ra * sp4[nf][r];
;                 av[r] = __expf(la);
;                 const float x2 = 2.0f * la;
;                 const float om = -x2 * (1.0f + x2 * (0.5f + x2 * (0.16666667f + x2 * (0.041666668f + x2 * (0.0083333338f + x2 * (0.0013888889f + x2 * 0.0001984127f))))));
;                 uv[r] = bf2f((bf16_t)xc4[r]) * ix * __builtin_amdgcn_sqrtf(fmaxf(om, 0.f));
;             }
;             *(LAS f32x4*)(STA + c * 68 + jo) = av; *(LAS f32x4*)(STU + c * 68 + jo) = uv;
;         }
;         LDS_FENCE();
	v_exp_f32_e32 v201, v201
	v_exp_f32_e32 v193, v193
	v_exp_f32_e32 v196, v196
	v_exp_f32_e32 v199, v199
	v_exp_f32_e32 v202, v202
	v_add_f32_e32 v192, 1.0, v192
	v_add_f32_e32 v195, 1.0, v195
	v_add_f32_e32 v198, 1.0, v198
	v_add_f32_e32 v201, 1.0, v201
	v_add_f32_e32 v193, 1.0, v193
	v_add_f32_e32 v196, 1.0, v196
	v_add_f32_e32 v199, 1.0, v199
	v_add_f32_e32 v202, 1.0, v202
	v_rcp_f32_e32 v192, v192
	v_rcp_f32_e32 v195, v195
	v_rcp_f32_e32 v198, v198
	v_rcp_f32_e32 v201, v201
	v_rcp_f32_e32 v193, v193
	v_rcp_f32_e32 v196, v196
	v_rcp_f32_e32 v199, v199
	v_rcp_f32_e32 v202, v202
	v_mul_f32_e32 v192, v140, v192
	v_mul_f32_e32 v195, v139, v195
	v_mul_f32_e32 v198, v138, v198
	v_mul_f32_e32 v201, v137, v201
	v_mul_f32_e32 v194, 0x3fb8aa3b, v192
	v_mul_f32_e32 v197, 0x3fb8aa3b, v195
	v_mul_f32_e32 v200, 0x3fb8aa3b, v198
	v_mul_f32_e32 v203, 0x3fb8aa3b, v201
	v_add_f32_e32 v192, v192, v192
	v_add_f32_e32 v195, v195, v195
	v_add_f32_e32 v198, v198, v198
	v_add_f32_e32 v201, v201, v201
	v_exp_f32_e32 v164, v194
	v_exp_f32_e32 v165, v197
	v_exp_f32_e32 v166, v200
	v_exp_f32_e32 v167, v203
	v_fmamk_f32 v194, v192, 0x39500d01, v227
	v_fmamk_f32 v197, v195, 0x39500d01, v227
	v_fmamk_f32 v200, v198, 0x39500d01, v227
	v_fmamk_f32 v203, v201, 0x39500d01, v227
	v_fmaak_f32 v194, v192, v194, 0x3c088889
	v_fmaak_f32 v197, v195, v197, 0x3c088889
	v_fmaak_f32 v200, v198, v200, 0x3c088889
	v_fmaak_f32 v203, v201, v203, 0x3c088889
	v_fmaak_f32 v194, v192, v194, 0x3d2aaaab
	v_fmaak_f32 v197, v195, v197, 0x3d2aaaab
	v_fmaak_f32 v200, v198, v200, 0x3d2aaaab
	v_fmaak_f32 v203, v201, v203, 0x3d2aaaab
	v_fmaak_f32 v194, v192, v194, 0x3e2aaaab
	v_fmaak_f32 v197, v195, v197, 0x3e2aaaab
	v_fmaak_f32 v200, v198, v200, 0x3e2aaaab
	v_fmaak_f32 v203, v201, v203, 0x3e2aaaab
	v_fma_f32 v194, v192, v194, 0.5
	v_fma_f32 v197, v195, v197, 0.5
	v_fma_f32 v200, v198, v200, 0.5
	v_fma_f32 v203, v201, v203, 0.5
	v_fma_f32 v194, v192, v194, 1.0
	v_fma_f32 v197, v195, v197, 1.0
	v_fma_f32 v200, v198, v200, 1.0
	v_fma_f32 v203, v201, v203, 1.0
	v_mul_f32_e64 v192, v194, -v192
	v_mul_f32_e64 v195, v197, -v195
	v_mul_f32_e64 v198, v200, -v198
	v_mul_f32_e64 v201, v203, -v201
	v_max_f32_e32 v192, 0, v192
	v_max_f32_e32 v195, 0, v195
	v_max_f32_e32 v198, 0, v198
	v_max_f32_e32 v201, 0, v201
	v_sqrt_f32_e32 v192, v192
	v_sqrt_f32_e32 v195, v195
	v_sqrt_f32_e32 v198, v198
	v_sqrt_f32_e32 v201, v201
	v_mul_f32_e32 v193, v193, v212
	v_mul_f32_e32 v196, v196, v213
	v_mul_f32_e32 v199, v199, v214
	v_mul_f32_e32 v202, v202, v215
	v_mul_f32_e32 v104, v193, v192
	v_mul_f32_e32 v105, v196, v195
	v_mul_f32_e32 v106, v199, v198
	v_mul_f32_e32 v107, v202, v201
	ds_write_b128 v154, v[164:167] offset:128
	ds_write_b128 v154, v[104:107] offset:4480
	v_add_f32_e32 v192, v88, v168
	v_add_f32_e32 v195, v89, v169
	v_add_f32_e32 v198, v90, v170
	v_add_f32_e32 v201, v91, v171
	v_add_f32_e32 v193, v92, v108
	v_add_f32_e32 v196, v93, v109
	v_add_f32_e32 v199, v94, v110
	v_add_f32_e32 v202, v95, v111
	v_mul_f32_e32 v192, 0xbfb8aa3b, v192
	v_mul_f32_e32 v195, 0xbfb8aa3b, v195
	v_mul_f32_e32 v198, 0xbfb8aa3b, v198
	v_mul_f32_e32 v201, 0xbfb8aa3b, v201
	v_mul_f32_e32 v193, 0xbfb8aa3b, v193
	v_mul_f32_e32 v196, 0xbfb8aa3b, v196
	v_mul_f32_e32 v199, 0xbfb8aa3b, v199
	v_mul_f32_e32 v202, 0xbfb8aa3b, v202
	v_exp_f32_e32 v192, v192
	v_exp_f32_e32 v195, v195
	v_exp_f32_e32 v198, v198
	v_exp_f32_e32 v201, v201
	v_exp_f32_e32 v193, v193
	v_exp_f32_e32 v196, v196
	v_exp_f32_e32 v199, v199
	v_exp_f32_e32 v202, v202
	v_add_f32_e32 v192, 1.0, v192
	v_add_f32_e32 v195, 1.0, v195
	v_add_f32_e32 v198, 1.0, v198
	v_add_f32_e32 v201, 1.0, v201
	v_add_f32_e32 v193, 1.0, v193
	v_add_f32_e32 v196, 1.0, v196
	v_add_f32_e32 v199, 1.0, v199
	v_add_f32_e32 v202, 1.0, v202
	v_rcp_f32_e32 v192, v192
	v_rcp_f32_e32 v195, v195
	v_rcp_f32_e32 v198, v198
	v_rcp_f32_e32 v201, v201
	v_rcp_f32_e32 v193, v193
	v_rcp_f32_e32 v196, v196
	v_rcp_f32_e32 v199, v199
	v_rcp_f32_e32 v202, v202
	v_mul_f32_e32 v192, v136, v192
	v_mul_f32_e32 v195, v135, v195
	v_mul_f32_e32 v198, v134, v198
	v_mul_f32_e32 v201, v149, v201
	v_mul_f32_e32 v194, 0x3fb8aa3b, v192
	v_mul_f32_e32 v197, 0x3fb8aa3b, v195
	v_mul_f32_e32 v200, 0x3fb8aa3b, v198
	v_mul_f32_e32 v203, 0x3fb8aa3b, v201
	v_add_f32_e32 v192, v192, v192
	v_add_f32_e32 v195, v195, v195
	v_add_f32_e32 v198, v198, v198
	v_add_f32_e32 v201, v201, v201
	v_exp_f32_e32 v168, v194
	v_exp_f32_e32 v169, v197
	v_exp_f32_e32 v170, v200
	v_exp_f32_e32 v171, v203
	v_fmamk_f32 v194, v192, 0x39500d01, v227
	v_fmamk_f32 v197, v195, 0x39500d01, v227
	v_fmamk_f32 v200, v198, 0x39500d01, v227
	v_fmamk_f32 v203, v201, 0x39500d01, v227
	v_fmaak_f32 v194, v192, v194, 0x3c088889
	v_fmaak_f32 v197, v195, v197, 0x3c088889
	v_fmaak_f32 v200, v198, v200, 0x3c088889
	v_fmaak_f32 v203, v201, v203, 0x3c088889
	v_fmaak_f32 v194, v192, v194, 0x3d2aaaab
	v_fmaak_f32 v197, v195, v197, 0x3d2aaaab
	v_fmaak_f32 v200, v198, v200, 0x3d2aaaab
	v_fmaak_f32 v203, v201, v203, 0x3d2aaaab
	v_fmaak_f32 v194, v192, v194, 0x3e2aaaab
	v_fmaak_f32 v197, v195, v197, 0x3e2aaaab
	v_fmaak_f32 v200, v198, v200, 0x3e2aaaab
	v_fmaak_f32 v203, v201, v203, 0x3e2aaaab
	v_fma_f32 v194, v192, v194, 0.5
	v_fma_f32 v197, v195, v197, 0.5
	v_fma_f32 v200, v198, v200, 0.5
	v_fma_f32 v203, v201, v203, 0.5
	v_fma_f32 v194, v192, v194, 1.0
	v_fma_f32 v197, v195, v197, 1.0
	v_fma_f32 v200, v198, v200, 1.0
	v_fma_f32 v203, v201, v203, 1.0
	v_mul_f32_e64 v192, v194, -v192
	v_mul_f32_e64 v195, v197, -v195
	v_mul_f32_e64 v198, v200, -v198
	v_mul_f32_e64 v201, v203, -v201
	v_max_f32_e32 v192, 0, v192
	v_max_f32_e32 v195, 0, v195
	v_max_f32_e32 v198, 0, v198
	v_max_f32_e32 v201, 0, v201
	v_sqrt_f32_e32 v192, v192
	v_sqrt_f32_e32 v195, v195
	v_sqrt_f32_e32 v198, v198
	v_sqrt_f32_e32 v201, v201
	v_mul_f32_e32 v193, v193, v216
	v_mul_f32_e32 v196, v196, v217
	v_mul_f32_e32 v199, v199, v218
	v_mul_f32_e32 v202, v202, v219
	v_mul_f32_e32 v108, v193, v192
	v_mul_f32_e32 v109, v196, v195
	v_mul_f32_e32 v110, v199, v198
	v_mul_f32_e32 v111, v202, v201
	ds_write_b128 v154, v[168:171] offset:192
	ds_write_b128 v154, v[108:111] offset:4544
	s_waitcnt lgkmcnt(0)
; __device__ __forceinline__ float bf2f(bf16_t b) { return __uint_as_float(((unsigned)b) << 16); }
; __device__ __forceinline__ unsigned cvtpk(float lo, float hi) { const f32x2 v = (f32x2){lo, hi}; const bf16v2 b = __builtin_convertvector(v, bf16v2); return __builtin_bit_cast(unsigned, b); }
; #define LDS_FENCE() asm volatile("s_waitcnt lgkmcnt(0)" ::: "memory")
; template <int DIR> __device__ __forceinline__ void lru_dir(const Params& p, int l, int n, int h, int lane, LAS bf16_t* XC, LAS float* STA, LAS float* STU) {
;     ...
;         float aa[16], uu[16];
; #pragma unroll
;         for (int s = 0; s < 16; ++s) { aa[s] = STA[s * 68 + j]; uu[s] = STU[s * 68 + j]; }
;         LDS_FENCE();
; #pragma unroll
;         for (int s = 0; s < 16; ++s) {
;             const int tl = DIR == 0 ? s : 15 - s;
;             hcar = aa[tl] * hcar + uu[tl]; P *= aa[tl];
;             const size_t row = (size_t)(t0 + 16 * mi + tl);
;             if (DIR == 0) { const unsigned w = cvtpk(hcar, P); y[row * D + 64 * h + j] = (bf16_t)(w & 0xffffu); y[row * D + 512 + 64 * h + j] = (bf16_t)(w >> 16); }
;             else { const unsigned w = cvtpk(bf2f(hfp[tl]) + hcar, P); y[row * D + 64 * h + j] = (bf16_t)(w & 0xffffu); __builtin_nontemporal_store((bf16_t)(w >> 16), PB + row * 512 + 64 * h + j); }
;         }
	ds_read_b32 v204, v155
	ds_read_b32 v172, v155 offset:4352
	ds_read_b32 v205, v155 offset:272
	ds_read_b32 v173, v155 offset:4624
	ds_read_b32 v206, v155 offset:544
	ds_read_b32 v174, v155 offset:4896
	ds_read_b32 v207, v155 offset:816
	ds_read_b32 v175, v155 offset:5168
	ds_read_b32 v208, v155 offset:1088
	ds_read_b32 v178, v155 offset:5440
	ds_read_b32 v209, v155 offset:1360
	ds_read_b32 v179, v155 offset:5712
	ds_read_b32 v210, v155 offset:1632
	ds_read_b32 v180, v155 offset:5984
	ds_read_b32 v211, v155 offset:1904
	ds_read_b32 v181, v155 offset:6256
	s_waitcnt lgkmcnt(14)
	v_fma_f32 v130, v130, v204, v172
	v_mul_f32_e32 v129, v129, v204
	v_cvt_pk_bf16_f32 v190, v130, v129
	global_store_short v220, v190, s[64:65] offset:-4096
	global_store_short_d16_hi v220, v190, s[64:65] offset:-3072
	ds_read_b32 v212, v155 offset:2176
	ds_read_b32 v182, v155 offset:6528
	s_waitcnt lgkmcnt(14)
	v_fma_f32 v130, v130, v205, v173
	v_mul_f32_e32 v129, v129, v205
	v_cvt_pk_bf16_f32 v191, v130, v129
	global_store_short v220, v191, s[64:65] offset:-2048
	global_store_short_d16_hi v220, v191, s[64:65] offset:-1024
	ds_read_b32 v213, v155 offset:2448
	ds_read_b32 v183, v155 offset:6800
	s_waitcnt lgkmcnt(14)
	v_fma_f32 v130, v130, v206, v174
	v_mul_f32_e32 v129, v129, v206
	v_cvt_pk_bf16_f32 v190, v130, v129
	global_store_short v220, v190, s[64:65] offset:0
	global_store_short_d16_hi v220, v190, s[64:65] offset:1024
	ds_read_b32 v214, v155 offset:2720
	ds_read_b32 v184, v155 offset:7072
	s_waitcnt lgkmcnt(14)
	v_fma_f32 v130, v130, v207, v175
	v_mul_f32_e32 v129, v129, v207
	v_cvt_pk_bf16_f32 v191, v130, v129
	global_store_short v220, v191, s[64:65] offset:2048
	global_store_short_d16_hi v220, v191, s[64:65] offset:3072
	ds_read_b32 v215, v155 offset:2992
	ds_read_b32 v185, v155 offset:7344
	s_waitcnt lgkmcnt(14)
	v_fma_f32 v130, v130, v208, v178
	v_mul_f32_e32 v129, v129, v208
	v_cvt_pk_bf16_f32 v190, v130, v129
	s_add_u32 s64, s64, 0x2000
	s_addc_u32 s65, s65, 0
	global_store_short v220, v190, s[64:65] offset:-4096
	global_store_short_d16_hi v220, v190, s[64:65] offset:-3072
	ds_read_b32 v216, v155 offset:3264
	ds_read_b32 v186, v155 offset:7616
	s_waitcnt lgkmcnt(14)
	v_fma_f32 v130, v130, v209, v179
	v_mul_f32_e32 v129, v129, v209
	v_cvt_pk_bf16_f32 v191, v130, v129
	global_store_short v220, v191, s[64:65] offset:-2048
	global_store_short_d16_hi v220, v191, s[64:65] offset:-1024
	ds_read_b32 v217, v155 offset:3536
	ds_read_b32 v187, v155 offset:7888
	s_waitcnt lgkmcnt(14)
	v_fma_f32 v130, v130, v210, v180
	v_mul_f32_e32 v129, v129, v210
	v_cvt_pk_bf16_f32 v190, v130, v129
	global_store_short v220, v190, s[64:65] offset:0
	global_store_short_d16_hi v220, v190, s[64:65] offset:1024
	ds_read_b32 v218, v155 offset:3808
	ds_read_b32 v188, v155 offset:8160
	s_waitcnt lgkmcnt(14)
	v_fma_f32 v130, v130, v211, v181
	v_mul_f32_e32 v129, v129, v211
	v_cvt_pk_bf16_f32 v191, v130, v129
	global_store_short v220, v191, s[64:65] offset:2048
	global_store_short_d16_hi v220, v191, s[64:65] offset:3072
	ds_read_b32 v219, v155 offset:4080
	ds_read_b32 v189, v155 offset:8432
	s_waitcnt lgkmcnt(14)
	v_fma_f32 v130, v130, v212, v182
	v_mul_f32_e32 v129, v129, v212
	v_cvt_pk_bf16_f32 v190, v130, v129
	s_add_u32 s64, s64, 0x2000
	s_addc_u32 s65, s65, 0
	global_store_short v220, v190, s[64:65] offset:-4096
	global_store_short_d16_hi v220, v190, s[64:65] offset:-3072
	s_waitcnt lgkmcnt(12)
	v_fma_f32 v130, v130, v213, v183
	v_mul_f32_e32 v129, v129, v213
	v_cvt_pk_bf16_f32 v191, v130, v129
	global_store_short v220, v191, s[64:65] offset:-2048
	global_store_short_d16_hi v220, v191, s[64:65] offset:-1024
	s_waitcnt lgkmcnt(10)
	v_fma_f32 v130, v130, v214, v184
	v_mul_f32_e32 v129, v129, v214
	v_cvt_pk_bf16_f32 v190, v130, v129
	global_store_short v220, v190, s[64:65] offset:0
	global_store_short_d16_hi v220, v190, s[64:65] offset:1024
	s_waitcnt lgkmcnt(8)
	v_fma_f32 v130, v130, v215, v185
	v_mul_f32_e32 v129, v129, v215
	v_cvt_pk_bf16_f32 v191, v130, v129
	global_store_short v220, v191, s[64:65] offset:2048
	global_store_short_d16_hi v220, v191, s[64:65] offset:3072
	s_waitcnt lgkmcnt(6)
	v_fma_f32 v130, v130, v216, v186
	v_mul_f32_e32 v129, v129, v216
	v_cvt_pk_bf16_f32 v190, v130, v129
	s_add_u32 s64, s64, 0x2000
	s_addc_u32 s65, s65, 0
	global_store_short v220, v190, s[64:65] offset:-4096
	global_store_short_d16_hi v220, v190, s[64:65] offset:-3072
	s_waitcnt lgkmcnt(4)
	v_fma_f32 v130, v130, v217, v187
	v_mul_f32_e32 v129, v129, v217
	v_cvt_pk_bf16_f32 v191, v130, v129
	global_store_short v220, v191, s[64:65] offset:-2048
	global_store_short_d16_hi v220, v191, s[64:65] offset:-1024
	s_waitcnt lgkmcnt(2)
	v_fma_f32 v130, v130, v218, v188
	v_mul_f32_e32 v129, v129, v218
	v_cvt_pk_bf16_f32 v190, v130, v129
	global_store_short v220, v190, s[64:65] offset:0
	global_store_short_d16_hi v220, v190, s[64:65] offset:1024
	s_waitcnt lgkmcnt(0)
	v_fma_f32 v130, v130, v219, v189
	v_mul_f32_e32 v129, v129, v219
	v_cvt_pk_bf16_f32 v191, v130, v129
	global_store_short v220, v191, s[64:65] offset:2048
	global_store_short_d16_hi v220, v191, s[64:65] offset:3072
	s_add_u32 s0, s0, 0x8000
	s_addc_u32 s1, s1, 0
	v_add_u32_e32 v150, 0x4100, v150
	v_add_u32_e32 v151, 0x4100, v151
	s_cmp_lg_u32 s0, 0x20000
	s_cbranch_scc1 .Llru0_loop
; template <int DIR> __device__ __forceinline__ void lru_dir(const Params& p, int l, int n, int h, int lane, LAS bf16_t* XC, LAS float* STA, LAS float* STU) {
;     ...
;     const float* lam = p.in[10] + (size_t)(l * 2 + DIR) * 512 + 64 * h; const float* b_a = p.in[7] + (size_t)(l * 2 + DIR) * 512 + 64 * h; const float* b_x = p.in[9] + (size_t)(l * 2 + DIR) * 512 + 64 * h;
;     const bf16_t* LWa = LW + ((size_t)(DIR * 2 + 0) * 8 + h) * 4096 + c * 64 + 8 * q; const bf16_t* LWx = LW + ((size_t)(DIR * 2 + 1) * 8 + h) * 4096 + c * 64 + 8 * q;
;     bf16x8 wa[4][2], wx[4][2]; f32x4 sp4[4], ba4[4], bx4[4];
; #pragma unroll
;     for (int nf = 0; nf < 4; ++nf) {
; #pragma unroll
;         for (int ks = 0; ks < 2; ++ks) { wa[nf][ks] = *(const bf16x8*)(LWa + nf * 1024 + 32 * ks); wx[nf][ks] = *(const bf16x8*)(LWx + nf * 1024 + 32 * ks); }
;         const f32x4 lam4 = *(const f32x4*)(lam + 16 * nf + 4 * q); ba4[nf] = *(const f32x4*)(b_a + 16 * nf + 4 * q); bx4[nf] = *(const f32x4*)(b_x + 16 * nf + 4 * q);
; #pragma unroll
;         for (int r = 0; r < 4; ++r) { const float e = __expf(-lam4[r]); const float l1p = e < 0.05f ? e * (1.0f - e * (0.5f - e * (0.33333334f - e * 0.25f))) : __logf(1.0f + e); sp4[nf][r] = -8.0f * l1p; }
;     ...
;     Aprod[(size_t)(DIR * NCH + n) * 512 + 64 * h + j] = P; Hend[(size_t)(DIR * NCH + n) * 512 + 64 * h + j] = hcar;
	v_add_u32_e32 v156, 0x1000, v155
	v_add_u32_e32 v157, 0x1200, v155
	v_add_u32_e32 v158, 0x400, v155
	v_add_u32_e32 v159, 0x1400, v155
	v_add_u32_e32 v160, 0x1600, v155
	v_add_u32_e32 v161, 0x800, v155
	v_add_u32_e32 v162, 0x1800, v155
	v_add_u32_e32 v163, 0x1a00, v155
	v_add_u32_e32 v164, 0xc00, v155
	v_add_u32_e32 v165, 0x1c00, v155
	v_add_u32_e32 v166, 0x1e00, v155
	s_ashr_i32 s5, s4, 31
	s_lshl_b64 s[0:1], s[4:5], 9
	v_lshl_add_u64 v[0:1], s[0:1], 0, v[124:125]
	v_or_b32_e32 v0, v0, v126
	v_readlane_b32 s0, v254, 11
	v_lshlrev_b64 v[0:1], 2, v[0:1]
	v_readlane_b32 s1, v254, 12
	v_lshlrev_b32_e32 v6, 1, v121
	v_mov_b32_e32 v7, v177
	v_lshl_add_u64 v[2:3], s[0:1], 0, v[0:1]
	v_readlane_b32 s0, v254, 13
	v_readlane_b32 s1, v254, 14
	v_lshlrev_b32_e32 v8, 1, v133
	v_mov_b32_e32 v9, v177
	v_lshl_add_u64 v[6:7], v[114:115], 0, v[6:7]
	v_lshl_add_u64 v[0:1], s[0:1], 0, v[0:1]
	v_lshl_add_u64 v[6:7], v[6:7], 0, v[8:9]
	s_mov_b64 s[0:1], 0x20000
	v_lshl_add_u64 v[80:81], v[6:7], 0, s[0:1]
	s_mov_b64 s[0:1], 0x30000
	global_store_dword v[0:1], v130, off
	v_lshl_add_u64 v[0:1], s[22:23], 0, v[112:113]
	v_lshl_add_u64 v[78:79], v[6:7], 0, s[0:1]
	v_mov_b32_e32 v121, v177
	s_mov_b32 s0, 0x20000
	v_lshl_add_u64 v[76:77], v[0:1], 0, v[120:121]
	v_add_co_u32_e32 v0, vcc, s0, v6
	v_lshl_add_u64 v[4:5], s[38:39], 0, v[112:113]
	s_nop 0
	v_addc_co_u32_e32 v1, vcc, 0, v7, vcc
	v_lshl_add_u64 v[92:93], v[4:5], 0, v[120:121]
	v_add_co_u32_e32 v4, vcc, 0x30000, v6
	global_store_dword v[2:3], v129, off
	v_lshl_add_u64 v[2:3], s[26:27], 0, v[112:113]
	v_addc_co_u32_e32 v5, vcc, 0, v7, vcc
	v_lshl_add_u64 v[88:89], v[2:3], 0, v[120:121]
	global_load_dwordx4 v[24:27], v[76:77], off
	s_nop 0
	global_load_dwordx4 v[0:3], v[0:1], off
	s_nop 0
	global_load_dwordx4 v[4:7], v[4:5], off
	s_nop 0
	global_load_dwordx4 v[8:11], v[80:81], off offset:64
	global_load_dwordx4 v[12:15], v[78:79], off offset:64
	global_load_dwordx4 v[16:19], v[88:89], off
	global_load_dwordx4 v[20:23], v[92:93], off
	s_waitcnt vmcnt(6)
	v_mul_f32_e32 v24, 0xbfb8aa3b, v24
	v_exp_f32_e32 v24, v24
	s_nop 0
	v_cmp_ngt_f32_e32 vcc, s6, v24
	s_and_saveexec_b64 s[0:1], vcc
	s_xor_b64 s[30:31], exec, s[0:1]
	s_cbranch_execz .LBB0_260
	v_add_f32_e32 v24, 1.0, v24
	v_cmp_gt_f32_e32 vcc, s25, v24
	s_nop 1
	v_cndmask_b32_e64 v28, 0, 32, vcc
	v_ldexp_f32 v24, v24, v28
	v_log_f32_e32 v24, v24
	s_nop 0
	v_mul_f32_e32 v28, 0x3f317217, v24
	v_fma_f32 v28, v24, s36, -v28
	v_fmac_f32_e32 v28, 0x3377d1cf, v24
	v_fmac_f32_e32 v28, 0x3f317217, v24
	v_cmp_lt_f32_e64 s[0:1], |v24|, s37
	s_nop 1
	v_cndmask_b32_e64 v24, v24, v28, s[0:1]
	v_cndmask_b32_e32 v28, 0, v232, vcc
	v_sub_f32_e32 v100, v24, v28

; __device__ __forceinline__ f32x4 mfma16(bf16x8 a, bf16x8 b, f32x4 c) { return __builtin_amdgcn_mfma_f32_16x16x32_bf16(a, b, c, 0, 0, 0); }
; template <int MODE> __device__ void mixer_gla(const Params& p, int l, int n, LAS unsigned char* lds) {
;     ...
;             bf16x8 lrf[4], gwf[4]; float bgv[4];
; #pragma unroll
;             for (int tt = 0; tt < 4; ++tt) { lrf[tt] = (bf16x8){0, 0, 0, 0, 0, 0, 0, 0}; if (q < 2) lrf[tt] = *(const bf16x8*)(proj + (size_t)(t0 + 16 * tt + c) * DINP + 2560 + dir * 16 + 8 * q); }
; #pragma unroll
;             for (int ef = 0; ef < 4; ++ef) { gwf[ef] = *(const bf16x8*)(GW + (size_t)(dir * 256 + 64 * h + SIGC(ef, c)) * 32 + 8 * q); bgv[ef] = p.in[13][(size_t)(l * 2 + dir) * 256 + 64 * h + SIGC(ef, c)]; }
; #pragma unroll
;             for (int ef = 0; ef < 4; ++ef) { tot[ef] = 0.f;
; #pragma unroll
;                 for (int ks = 0; ks < 2; ++ks) { f32x4 la2[2];
; #pragma unroll
;                     for (int t2 = 0; t2 < 2; ++t2) { const f32x4 z = mfma16(lrf[2 * ks + t2], gwf[ef], zero4);
; #pragma unroll
;                         for (int r = 0; r < 4; ++r) { const float zz = z[r] + bgv[ef]; const float la = (fminf(zz, 0.f) - __logf(1.0f + __expf(-fabsf(zz)))) * (1.0f / 16.0f); la2[t2][r] = la; tot[ef] += la; } }
.LBB0_338:
	s_or_b64 exec, exec, s[0:1]
	s_lshl_b32 s4, s5, 8
	v_add_u32_e32 v30, s4, v88
	v_or_b32_e32 v16, v30, v90
	v_ashrrev_i32_e32 v17, 31, v16
	v_lshlrev_b64 v[16:17], 6, v[16:17]
	v_lshl_add_u64 v[16:17], v[92:93], 0, v[16:17]
	s_or_b32 s0, s5, s13
	global_load_dwordx4 v[24:27], v[16:17], off
	s_ashr_i32 s1, s0, 31
	s_lshl_b64 s[0:1], s[0:1], 10
	v_lshl_add_u64 v[28:29], v[114:115], 0, s[0:1]
	global_load_dword v40, v[28:29], off
	v_or_b32_e32 v16, v30, v117
	v_or_b32_e32 v20, v30, v118
	v_or_b32_e32 v30, v30, v119
	v_ashrrev_i32_e32 v17, 31, v16
	v_ashrrev_i32_e32 v21, 31, v20
	v_ashrrev_i32_e32 v31, 31, v30
	v_lshlrev_b64 v[16:17], 6, v[16:17]
	v_lshlrev_b64 v[20:21], 6, v[20:21]
	v_lshlrev_b64 v[30:31], 6, v[30:31]
	v_lshl_add_u64 v[16:17], v[92:93], 0, v[16:17]
	v_lshl_add_u64 v[20:21], v[92:93], 0, v[20:21]
	v_lshl_add_u64 v[30:31], v[92:93], 0, v[30:31]
	global_load_dwordx4 v[16:19], v[16:17], off
	s_nop 0
	global_load_dword v78, v[28:29], off offset:16
	s_nop 0
	global_load_dwordx4 v[20:23], v[20:21], off
	s_nop 0
	global_load_dword v77, v[28:29], off offset:128
	global_load_dwordx4 v[44:47], v[30:31], off
	global_load_dword v76, v[28:29], off offset:144
	s_waitcnt vmcnt(7)
	v_mfma_f32_16x16x32_bf16 v[28:31], v[12:15], v[24:27], 0
	s_waitcnt vmcnt(6)
	s_nop 6
	v_add_f32_e32 v41, v40, v28
	v_min_f32_e32 v28, 0, v41
	v_mul_f32_e64 v41, |v41|, s33
	v_exp_f32_e32 v41, v41
	v_add_f32_e32 v31, v40, v31
	v_add_f32_e32 v41, 1.0, v41
	v_log_f32_e32 v41, v41
	s_nop 0
	v_mul_f32_e32 v42, 0x3f317217, v41
	v_fma_f32 v42, v41, s36, -v42
	v_fmac_f32_e32 v42, 0x3377d1cf, v41
	v_fmac_f32_e32 v42, 0x3f317217, v41
	v_add_f32_e32 v41, v40, v29
	v_min_f32_e32 v29, 0, v41
	v_mul_f32_e64 v41, |v41|, s33
	v_exp_f32_e32 v41, v41
	s_nop 0
	v_add_f32_e32 v41, 1.0, v41
	v_log_f32_e32 v41, v41
	s_nop 0
	v_mul_f32_e32 v43, 0x3f317217, v41
	v_fma_f32 v43, v41, s36, -v43
	v_fmac_f32_e32 v43, 0x3377d1cf, v41
	v_fmac_f32_e32 v43, 0x3f317217, v41
	v_pk_add_f32 v[28:29], v[28:29], v[42:43] neg_lo:[0,1] neg_hi:[0,1]
	s_nop 0
	v_pk_mul_f32 v[68:69], v[28:29], s[50:51] op_sel_hi:[1,0]
	v_add_f32_e32 v29, v40, v30
	v_add_f32_e32 v28, 0, v68
	v_add_f32_e32 v41, v69, v28
	v_min_f32_e32 v28, 0, v29
	v_mul_f32_e64 v29, |v29|, s33
	v_exp_f32_e32 v29, v29
	s_nop 0
	v_add_f32_e32 v29, 1.0, v29
	v_log_f32_e32 v29, v29
	s_nop 0
	v_mul_f32_e32 v30, 0x3f317217, v29
	v_fma_f32 v30, v29, s36, -v30
	v_fmac_f32_e32 v30, 0x3377d1cf, v29
	v_fmac_f32_e32 v30, 0x3f317217, v29
	v_min_f32_e32 v29, 0, v31
	v_mul_f32_e64 v31, |v31|, s33
	v_exp_f32_e32 v31, v31
	s_nop 0
	v_add_f32_e32 v31, 1.0, v31
	v_log_f32_e32 v31, v31
	s_nop 0
	v_mul_f32_e32 v42, 0x3f317217, v31
	v_fma_f32 v42, v31, s36, -v42
	v_fmac_f32_e32 v42, 0x3377d1cf, v31
	v_fmac_f32_e32 v42, 0x3f317217, v31
	v_mov_b32_e32 v31, v42
	v_pk_add_f32 v[28:29], v[28:29], v[30:31] neg_lo:[0,1] neg_hi:[0,1]
	s_nop 0
	v_pk_mul_f32 v[70:71], v[28:29], s[50:51] op_sel_hi:[1,0]
	s_nop 0
	v_add_f32_e32 v28, v70, v41
	v_add_f32_e32 v41, v71, v28
	v_mfma_f32_16x16x32_bf16 v[28:31], v[8:11], v[24:27], 0
	s_nop 7
	v_add_f32_e32 v42, v40, v28
	v_min_f32_e32 v28, 0, v42
	v_mul_f32_e64 v42, |v42|, s33
	v_exp_f32_e32 v42, v42
	v_add_f32_e32 v31, v40, v31
	v_add_f32_e32 v42, 1.0, v42
	v_log_f32_e32 v42, v42
	s_nop 0
	v_mul_f32_e32 v43, 0x3f317217, v42
	v_fma_f32 v43, v42, s36, -v43
	v_fmac_f32_e32 v43, 0x3377d1cf, v42
	v_fmac_f32_e32 v43, 0x3f317217, v42
	v_mov_b32_e32 v42, v43
	v_add_f32_e32 v43, v40, v29
	v_min_f32_e32 v29, 0, v43
	v_mul_f32_e64 v43, |v43|, s33
	v_exp_f32_e32 v43, v43
	s_nop 0
	v_add_f32_e32 v43, 1.0, v43
	v_log_f32_e32 v43, v43
	s_nop 0
	v_mul_f32_e32 v48, 0x3f317217, v43
	v_fma_f32 v48, v43, s36, -v48
	v_fmac_f32_e32 v48, 0x3377d1cf, v43
	v_fmac_f32_e32 v48, 0x3f317217, v43
	v_mov_b32_e32 v43, v48
	v_pk_add_f32 v[28:29], v[28:29], v[42:43] neg_lo:[0,1] neg_hi:[0,1]
	s_nop 0
	v_pk_mul_f32 v[72:73], v[28:29], s[50:51] op_sel_hi:[1,0]
	v_add_f32_e32 v29, v40, v30
	v_add_f32_e32 v28, v72, v41
	v_add_f32_e32 v41, v73, v28
	v_min_f32_e32 v28, 0, v29
	v_mul_f32_e64 v29, |v29|, s33
	v_exp_f32_e32 v29, v29
	s_nop 0
	v_add_f32_e32 v29, 1.0, v29
	v_log_f32_e32 v29, v29
	s_nop 0
	v_mul_f32_e32 v30, 0x3f317217, v29
	v_fma_f32 v30, v29, s36, -v30
	v_fmac_f32_e32 v30, 0x3377d1cf, v29
	v_fmac_f32_e32 v30, 0x3f317217, v29
	v_min_f32_e32 v29, 0, v31
	v_mul_f32_e64 v31, |v31|, s33
	v_exp_f32_e32 v31, v31
	s_nop 0
	v_add_f32_e32 v31, 1.0, v31
	v_log_f32_e32 v31, v31
	s_nop 0
	v_mul_f32_e32 v42, 0x3f317217, v31
	v_fma_f32 v42, v31, s36, -v42
	v_fmac_f32_e32 v42, 0x3377d1cf, v31
	v_fmac_f32_e32 v42, 0x3f317217, v31
	v_mov_b32_e32 v31, v42
	v_pk_add_f32 v[28:29], v[28:29], v[30:31] neg_lo:[0,1] neg_hi:[0,1]
	s_nop 0
	v_pk_mul_f32 v[74:75], v[28:29], s[50:51] op_sel_hi:[1,0]
	s_nop 0
	v_add_f32_e32 v28, v74, v41
	v_add_f32_e32 v41, v75, v28
	v_mfma_f32_16x16x32_bf16 v[28:31], v[36:39], v[24:27], 0
	v_mfma_f32_16x16x32_bf16 v[24:27], v[32:35], v[24:27], 0
	s_nop 6
	v_add_f32_e32 v42, v40, v28
	v_min_f32_e32 v28, 0, v42
	v_mul_f32_e64 v42, |v42|, s33
	v_exp_f32_e32 v42, v42
	v_add_f32_e32 v31, v40, v31
	v_add_f32_e32 v27, v40, v27
	v_add_f32_e32 v42, 1.0, v42
	v_log_f32_e32 v42, v42
	s_nop 0
	v_mul_f32_e32 v43, 0x3f317217, v42
	v_fma_f32 v43, v42, s36, -v43
	v_fmac_f32_e32 v43, 0x3377d1cf, v42
	v_fmac_f32_e32 v43, 0x3f317217, v42
	v_mov_b32_e32 v42, v43
	v_add_f32_e32 v43, v40, v29
	v_min_f32_e32 v29, 0, v43
	v_mul_f32_e64 v43, |v43|, s33
	v_exp_f32_e32 v43, v43
	s_nop 0
	v_add_f32_e32 v43, 1.0, v43
	v_log_f32_e32 v43, v43
	s_nop 0
	v_mul_f32_e32 v48, 0x3f317217, v43
	v_fma_f32 v48, v43, s36, -v48
	v_fmac_f32_e32 v48, 0x3377d1cf, v43
; __device__ __forceinline__ f32x4 mfma16(bf16x8 a, bf16x8 b, f32x4 c) { return __builtin_amdgcn_mfma_f32_16x16x32_bf16(a, b, c, 0, 0, 0); }
; template <int MODE> __device__ void mixer_gla(const Params& p, int l, int n, LAS unsigned char* lds) {
;     ...
;             for (int ef = 0; ef < 4; ++ef) { tot[ef] = 0.f;
; #pragma unroll
;                 for (int ks = 0; ks < 2; ++ks) { f32x4 la2[2];
; #pragma unroll
;                     for (int t2 = 0; t2 < 2; ++t2) { const f32x4 z = mfma16(lrf[2 * ks + t2], gwf[ef], zero4);
; #pragma unroll
;                         for (int r = 0; r < 4; ++r) { const float zz = z[r] + bgv[ef]; const float la = (fminf(zz, 0.f) - __logf(1.0f + __expf(-fabsf(zz)))) * (1.0f / 16.0f); la2[t2][r] = la; tot[ef] += la; } }
;     ...
;             for (int ef = 0; ef < 4; ++ef) { float tt = tot[ef]; tt += __shfl_xor(tt, 16); tt += __shfl_xor(tt, 32);
;                 if (vh == 0 && q == 0) dec[((size_t)(dir * NCH + n) * 4 + h) * 64 + SIGC(ef, c)] = __expf(tt); }
	v_fmac_f32_e32 v48, 0x3f317217, v43
	v_mov_b32_e32 v43, v48
	v_pk_add_f32 v[28:29], v[28:29], v[42:43] neg_lo:[0,1] neg_hi:[0,1]
	s_nop 0
	v_pk_mul_f32 v[80:81], v[28:29], s[50:51] op_sel_hi:[1,0]
	v_add_f32_e32 v29, v40, v30
	v_add_f32_e32 v28, v80, v41
	v_add_f32_e32 v41, v81, v28
	v_min_f32_e32 v28, 0, v29
	v_mul_f32_e64 v29, |v29|, s33
	v_exp_f32_e32 v29, v29
	s_nop 0
	v_add_f32_e32 v29, 1.0, v29
	v_log_f32_e32 v29, v29
	s_nop 0
	v_mul_f32_e32 v30, 0x3f317217, v29
	v_fma_f32 v30, v29, s36, -v30
	v_fmac_f32_e32 v30, 0x3377d1cf, v29
	v_fmac_f32_e32 v30, 0x3f317217, v29
	v_min_f32_e32 v29, 0, v31
	v_mul_f32_e64 v31, |v31|, s33
	v_exp_f32_e32 v31, v31
	s_nop 0
	v_add_f32_e32 v31, 1.0, v31
	v_log_f32_e32 v31, v31
	s_nop 0
	v_mul_f32_e32 v42, 0x3f317217, v31
	v_fma_f32 v42, v31, s36, -v42
	v_fmac_f32_e32 v42, 0x3377d1cf, v31
	v_fmac_f32_e32 v42, 0x3f317217, v31
	v_mov_b32_e32 v31, v42
	v_pk_add_f32 v[28:29], v[28:29], v[30:31] neg_lo:[0,1] neg_hi:[0,1]
	s_nop 0
	v_pk_mul_f32 v[82:83], v[28:29], s[50:51] op_sel_hi:[1,0]
	s_nop 0
	v_add_f32_e32 v28, v82, v41
	v_add_f32_e32 v30, v83, v28
	v_add_f32_e32 v28, v40, v24
	v_min_f32_e32 v24, 0, v28
	v_mul_f32_e64 v28, |v28|, s33
	v_exp_f32_e32 v28, v28
	s_nop 0
	v_add_f32_e32 v28, 1.0, v28
	v_log_f32_e32 v28, v28
	s_nop 0
	v_mul_f32_e32 v29, 0x3f317217, v28
	v_fma_f32 v29, v28, s36, -v29
	v_fmac_f32_e32 v29, 0x3377d1cf, v28
	v_fmac_f32_e32 v29, 0x3f317217, v28
	v_mov_b32_e32 v28, v29
	v_add_f32_e32 v29, v40, v25
	v_min_f32_e32 v25, 0, v29
	v_mul_f32_e64 v29, |v29|, s33
	v_exp_f32_e32 v29, v29
	s_nop 0
	v_add_f32_e32 v29, 1.0, v29
	v_log_f32_e32 v29, v29
	s_nop 0
	v_mul_f32_e32 v31, 0x3f317217, v29
	v_fma_f32 v31, v29, s36, -v31
	v_fmac_f32_e32 v31, 0x3377d1cf, v29
	v_fmac_f32_e32 v31, 0x3f317217, v29
	v_mov_b32_e32 v29, v31
	v_pk_add_f32 v[24:25], v[24:25], v[28:29] neg_lo:[0,1] neg_hi:[0,1]
	s_nop 0
	v_pk_mul_f32 v[84:85], v[24:25], s[50:51] op_sel_hi:[1,0]
	v_add_f32_e32 v25, v40, v26
	v_add_f32_e32 v24, v84, v30
	v_add_f32_e32 v28, v85, v24
	v_min_f32_e32 v24, 0, v25
	v_mul_f32_e64 v25, |v25|, s33
	v_exp_f32_e32 v25, v25
	s_nop 0
	v_add_f32_e32 v25, 1.0, v25
	v_log_f32_e32 v25, v25
	s_nop 0
	v_mul_f32_e32 v26, 0x3f317217, v25
	v_fma_f32 v26, v25, s36, -v26
	v_fmac_f32_e32 v26, 0x3377d1cf, v25
	v_fmac_f32_e32 v26, 0x3f317217, v25
	v_min_f32_e32 v25, 0, v27
	v_mul_f32_e64 v27, |v27|, s33
	v_exp_f32_e32 v27, v27
	s_nop 0
	v_add_f32_e32 v27, 1.0, v27
	v_log_f32_e32 v27, v27
	s_nop 0
	v_mul_f32_e32 v29, 0x3f317217, v27
	v_fma_f32 v29, v27, s36, -v29
	v_fmac_f32_e32 v29, 0x3377d1cf, v27
	v_fmac_f32_e32 v29, 0x3f317217, v27
	v_mov_b32_e32 v27, v29
	v_pk_add_f32 v[24:25], v[24:25], v[26:27] neg_lo:[0,1] neg_hi:[0,1]
	s_nop 0
	v_pk_mul_f32 v[86:87], v[24:25], s[50:51] op_sel_hi:[1,0]
	s_nop 0
	v_add_f32_e32 v24, v86, v28
	v_add_f32_e32 v79, v87, v24
	s_waitcnt vmcnt(5)
	v_mfma_f32_16x16x32_bf16 v[64:67], v[12:15], v[16:19], 0
	v_mfma_f32_16x16x32_bf16 v[60:63], v[8:11], v[16:19], 0
	v_mfma_f32_16x16x32_bf16 v[56:59], v[36:39], v[16:19], 0
	v_mfma_f32_16x16x32_bf16 v[52:55], v[32:35], v[16:19], 0
	s_waitcnt vmcnt(3)
	v_mfma_f32_16x16x32_bf16 v[48:51], v[12:15], v[20:23], 0
	v_mfma_f32_16x16x32_bf16 v[40:43], v[8:11], v[20:23], 0
	v_mfma_f32_16x16x32_bf16 v[28:31], v[36:39], v[20:23], 0
	v_mfma_f32_16x16x32_bf16 v[24:27], v[32:35], v[20:23], 0
	s_waitcnt vmcnt(1)
	v_mfma_f32_16x16x32_bf16 v[20:23], v[12:15], v[44:47], 0
	v_mfma_f32_16x16x32_bf16 v[16:19], v[8:11], v[44:47], 0
	v_mfma_f32_16x16x32_bf16 v[12:15], v[36:39], v[44:47], 0
	v_mfma_f32_16x16x32_bf16 v[8:11], v[32:35], v[44:47], 0
	ds_bpermute_b32 v32, v91, v79
	s_add_i32 s8, s4, s12
	s_ashr_i32 s9, s8, 31
	s_lshl_b64 s[0:1], s[8:9], 10
	v_lshlrev_b32_e32 v176, 2, v90
	s_waitcnt lgkmcnt(0)
	v_add_f32_e32 v34, v79, v32
	ds_bpermute_b32 v35, v116, v34
	v_lshl_add_u64 v[32:33], v[94:95], 0, s[0:1]
	s_and_saveexec_b64 s[0:1], s[40:41]
	s_cbranch_execz .LBB0_340
	s_waitcnt lgkmcnt(0)
	v_add_f32_e32 v34, v34, v35
	v_mul_f32_e32 v34, 0x3fb8aa3b, v34
	v_exp_f32_e32 v36, v34
	v_lshl_add_u64 v[34:35], v[32:33], 0, v[176:177]
	global_store_dword v[34:35], v36, off
.LBB0_340:
	s_or_b64 exec, exec, s[0:1]
	s_waitcnt lgkmcnt(0)
	v_add_f32_e32 v35, v78, v64
	v_min_f32_e32 v34, 0, v35
	v_mul_f32_e64 v35, |v35|, s33
	v_exp_f32_e32 v35, v35
	v_add_f32_e32 v37, v78, v65
	v_add_f32_e32 v39, v78, v67
	v_add_f32_e32 v57, v78, v57
	v_add_f32_e32 v35, 1.0, v35
	v_add_f32_e32 v59, v78, v59
	v_add_f32_e32 v55, v78, v55
	v_log_f32_e32 v35, v35
	s_nop 0
	v_mul_f32_e32 v36, 0x3f317217, v35
	v_fma_f32 v36, v35, s36, -v36
	v_fmac_f32_e32 v36, 0x3377d1cf, v35
	v_fmac_f32_e32 v36, 0x3f317217, v35
	v_min_f32_e32 v35, 0, v37
	v_mul_f32_e64 v37, |v37|, s33
	v_exp_f32_e32 v37, v37
	s_nop 0
	v_add_f32_e32 v37, 1.0, v37
	v_log_f32_e32 v37, v37
	s_nop 0
	v_mul_f32_e32 v38, 0x3f317217, v37
	v_fma_f32 v38, v37, s36, -v38
	v_fmac_f32_e32 v38, 0x3377d1cf, v37
	v_fmac_f32_e32 v38, 0x3f317217, v37
	v_mov_b32_e32 v37, v38
	v_pk_add_f32 v[34:35], v[34:35], v[36:37] neg_lo:[0,1] neg_hi:[0,1]
	v_add_f32_e32 v37, v78, v66
	v_pk_mul_f32 v[34:35], v[34:35], s[50:51] op_sel_hi:[1,0]
	s_nop 0
	v_add_f32_e32 v36, 0, v34
	v_add_f32_e32 v44, v35, v36
	v_min_f32_e32 v36, 0, v37
	v_mul_f32_e64 v37, |v37|, s33
	v_exp_f32_e32 v37, v37
	s_nop 0
	v_add_f32_e32 v37, 1.0, v37
	v_log_f32_e32 v37, v37
	s_nop 0
	v_mul_f32_e32 v38, 0x3f317217, v37
	v_fma_f32 v38, v37, s36, -v38
	v_fmac_f32_e32 v38, 0x3377d1cf, v37
	v_fmac_f32_e32 v38, 0x3f317217, v37
	v_min_f32_e32 v37, 0, v39
	v_mul_f32_e64 v39, |v39|, s33
	v_exp_f32_e32 v39, v39
	s_nop 0
	v_add_f32_e32 v39, 1.0, v39
	v_log_f32_e32 v39, v39
	s_nop 0
; __device__ __forceinline__ f32x4 mfma16(bf16x8 a, bf16x8 b, f32x4 c) { return __builtin_amdgcn_mfma_f32_16x16x32_bf16(a, b, c, 0, 0, 0); }
; template <int MODE> __device__ void mixer_gla(const Params& p, int l, int n, LAS unsigned char* lds) {
;     ...
;             for (int ef = 0; ef < 4; ++ef) { tot[ef] = 0.f;
; #pragma unroll
;                 for (int ks = 0; ks < 2; ++ks) { f32x4 la2[2];
; #pragma unroll
;                     for (int t2 = 0; t2 < 2; ++t2) { const f32x4 z = mfma16(lrf[2 * ks + t2], gwf[ef], zero4);
; #pragma unroll
;                         for (int r = 0; r < 4; ++r) { const float zz = z[r] + bgv[ef]; const float la = (fminf(zz, 0.f) - __logf(1.0f + __expf(-fabsf(zz)))) * (1.0f / 16.0f); la2[t2][r] = la; tot[ef] += la; } }
;                     laop[ef][ks] = pack8(la2[0], la2[1]); __builtin_amdgcn_sched_barrier(0); } }
;     ...
;             for (int ef = 0; ef < 4; ++ef) { float tt = tot[ef]; tt += __shfl_xor(tt, 16); tt += __shfl_xor(tt, 32);
;                 if (vh == 0 && q == 0) dec[((size_t)(dir * NCH + n) * 4 + h) * 64 + SIGC(ef, c)] = __expf(tt); }
	v_mul_f32_e32 v45, 0x3f317217, v39
	v_fma_f32 v45, v39, s36, -v45
	v_fmac_f32_e32 v45, 0x3377d1cf, v39
	v_fmac_f32_e32 v45, 0x3f317217, v39
	v_mov_b32_e32 v39, v45
	v_pk_add_f32 v[36:37], v[36:37], v[38:39] neg_lo:[0,1] neg_hi:[0,1]
	v_add_f32_e32 v39, v78, v60
	v_pk_mul_f32 v[36:37], v[36:37], s[50:51] op_sel_hi:[1,0]
	v_add_f32_e32 v45, v78, v61
	v_add_f32_e32 v38, v36, v44
	v_add_f32_e32 v46, v37, v38
	v_min_f32_e32 v38, 0, v39
	v_mul_f32_e64 v39, |v39|, s33
	v_exp_f32_e32 v39, v39
	s_nop 0
	v_add_f32_e32 v39, 1.0, v39
	v_log_f32_e32 v39, v39
	s_nop 0
	v_mul_f32_e32 v44, 0x3f317217, v39
	v_fma_f32 v44, v39, s36, -v44
	v_fmac_f32_e32 v44, 0x3377d1cf, v39
	v_fmac_f32_e32 v44, 0x3f317217, v39
	v_min_f32_e32 v39, 0, v45
	v_mul_f32_e64 v45, |v45|, s33
	v_exp_f32_e32 v45, v45
	s_nop 0
	v_add_f32_e32 v45, 1.0, v45
	v_log_f32_e32 v45, v45
	s_nop 0
	v_mul_f32_e32 v47, 0x3f317217, v45
	v_fma_f32 v47, v45, s36, -v47
	v_fmac_f32_e32 v47, 0x3377d1cf, v45
	v_fmac_f32_e32 v47, 0x3f317217, v45
	v_mov_b32_e32 v45, v47
	v_pk_add_f32 v[38:39], v[38:39], v[44:45] neg_lo:[0,1] neg_hi:[0,1]
	v_add_f32_e32 v45, v78, v62
	v_pk_mul_f32 v[38:39], v[38:39], s[50:51] op_sel_hi:[1,0]
	v_add_f32_e32 v47, v78, v63
	v_add_f32_e32 v44, v38, v46
	v_add_f32_e32 v60, v39, v44
	v_min_f32_e32 v44, 0, v45
	v_mul_f32_e64 v45, |v45|, s33
	v_exp_f32_e32 v45, v45
	s_nop 0
	v_add_f32_e32 v45, 1.0, v45
	v_log_f32_e32 v45, v45
	s_nop 0
	v_mul_f32_e32 v46, 0x3f317217, v45
	v_fma_f32 v46, v45, s36, -v46
	v_fmac_f32_e32 v46, 0x3377d1cf, v45
	v_fmac_f32_e32 v46, 0x3f317217, v45
	v_min_f32_e32 v45, 0, v47
	v_mul_f32_e64 v47, |v47|, s33
	v_exp_f32_e32 v47, v47
	s_nop 0
	v_add_f32_e32 v47, 1.0, v47
	v_log_f32_e32 v47, v47
	s_nop 0
	v_mul_f32_e32 v61, 0x3f317217, v47
	v_fma_f32 v61, v47, s36, -v61
	v_fmac_f32_e32 v61, 0x3377d1cf, v47
	v_fmac_f32_e32 v61, 0x3f317217, v47
	v_mov_b32_e32 v47, v61
	v_pk_add_f32 v[44:45], v[44:45], v[46:47] neg_lo:[0,1] neg_hi:[0,1]
	v_add_f32_e32 v47, v78, v56
	v_pk_mul_f32 v[44:45], v[44:45], s[50:51] op_sel_hi:[1,0]
	s_nop 0
	v_add_f32_e32 v46, v44, v60
	v_add_f32_e32 v60, v45, v46
	v_min_f32_e32 v46, 0, v47
	v_mul_f32_e64 v47, |v47|, s33
	v_exp_f32_e32 v47, v47
	s_nop 0
	v_add_f32_e32 v47, 1.0, v47
	v_log_f32_e32 v47, v47
	s_nop 0
	v_mul_f32_e32 v56, 0x3f317217, v47
	v_fma_f32 v56, v47, s36, -v56
	v_fmac_f32_e32 v56, 0x3377d1cf, v47
	v_fmac_f32_e32 v56, 0x3f317217, v47
	v_min_f32_e32 v47, 0, v57
	v_mul_f32_e64 v57, |v57|, s33
	v_exp_f32_e32 v57, v57
	s_nop 0
	v_add_f32_e32 v57, 1.0, v57
	v_log_f32_e32 v57, v57
	s_nop 0
	v_mul_f32_e32 v61, 0x3f317217, v57
	v_fma_f32 v61, v57, s36, -v61
	v_fmac_f32_e32 v61, 0x3377d1cf, v57
	v_fmac_f32_e32 v61, 0x3f317217, v57
	v_mov_b32_e32 v57, v61
	v_pk_add_f32 v[46:47], v[46:47], v[56:57] neg_lo:[0,1] neg_hi:[0,1]
	v_add_f32_e32 v57, v78, v58
	v_pk_mul_f32 v[46:47], v[46:47], s[50:51] op_sel_hi:[1,0]
	s_nop 0
	v_add_f32_e32 v56, v46, v60
	v_add_f32_e32 v60, v47, v56
	v_min_f32_e32 v56, 0, v57
	v_mul_f32_e64 v57, |v57|, s33
	v_exp_f32_e32 v57, v57
	s_nop 0
	v_add_f32_e32 v57, 1.0, v57
	v_log_f32_e32 v57, v57
	s_nop 0
	v_mul_f32_e32 v58, 0x3f317217, v57
	v_fma_f32 v58, v57, s36, -v58
	v_fmac_f32_e32 v58, 0x3377d1cf, v57
	v_fmac_f32_e32 v58, 0x3f317217, v57
	v_min_f32_e32 v57, 0, v59
	v_mul_f32_e64 v59, |v59|, s33
	v_exp_f32_e32 v59, v59
	s_nop 0
	v_add_f32_e32 v59, 1.0, v59
	v_log_f32_e32 v59, v59
	s_nop 0
	v_mul_f32_e32 v61, 0x3f317217, v59
	v_fma_f32 v61, v59, s36, -v61
	v_fmac_f32_e32 v61, 0x3377d1cf, v59
	v_fmac_f32_e32 v61, 0x3f317217, v59
	v_mov_b32_e32 v59, v61
	v_pk_add_f32 v[56:57], v[56:57], v[58:59] neg_lo:[0,1] neg_hi:[0,1]
	s_nop 0
	v_pk_mul_f32 v[56:57], v[56:57], s[50:51] op_sel_hi:[1,0]
	s_nop 0
	v_add_f32_e32 v58, v56, v60
	v_add_f32_e32 v60, v57, v58
	v_add_f32_e32 v58, v78, v52
	v_min_f32_e32 v52, 0, v58
	v_mul_f32_e64 v58, |v58|, s33
	v_exp_f32_e32 v58, v58
	s_nop 0
	v_add_f32_e32 v58, 1.0, v58
	v_log_f32_e32 v58, v58
	s_nop 0
	v_mul_f32_e32 v59, 0x3f317217, v58
	v_fma_f32 v59, v58, s36, -v59
	v_fmac_f32_e32 v59, 0x3377d1cf, v58
	v_fmac_f32_e32 v59, 0x3f317217, v58
	v_mov_b32_e32 v58, v59
	v_add_f32_e32 v59, v78, v53
	v_min_f32_e32 v53, 0, v59
	v_mul_f32_e64 v59, |v59|, s33
	v_exp_f32_e32 v59, v59
	s_nop 0
	v_add_f32_e32 v59, 1.0, v59
	v_log_f32_e32 v59, v59
	s_nop 0
	v_mul_f32_e32 v61, 0x3f317217, v59
	v_fma_f32 v61, v59, s36, -v61
	v_fmac_f32_e32 v61, 0x3377d1cf, v59
	v_fmac_f32_e32 v61, 0x3f317217, v59
	v_mov_b32_e32 v59, v61
	v_pk_add_f32 v[52:53], v[52:53], v[58:59] neg_lo:[0,1] neg_hi:[0,1]
	s_nop 0
	v_pk_mul_f32 v[58:59], v[52:53], s[50:51] op_sel_hi:[1,0]
	v_add_f32_e32 v53, v78, v54
	v_add_f32_e32 v52, v58, v60
	v_add_f32_e32 v60, v59, v52
	v_min_f32_e32 v52, 0, v53
	v_mul_f32_e64 v53, |v53|, s33
	v_exp_f32_e32 v53, v53
	s_nop 0
	v_add_f32_e32 v53, 1.0, v53
	v_log_f32_e32 v53, v53
	s_nop 0
	v_mul_f32_e32 v54, 0x3f317217, v53
	v_fma_f32 v54, v53, s36, -v54
	v_fmac_f32_e32 v54, 0x3377d1cf, v53
	v_fmac_f32_e32 v54, 0x3f317217, v53
	v_min_f32_e32 v53, 0, v55
	v_mul_f32_e64 v55, |v55|, s33
	v_exp_f32_e32 v55, v55
	s_nop 0
	v_add_f32_e32 v55, 1.0, v55
	v_log_f32_e32 v55, v55
	s_nop 0
	v_mul_f32_e32 v61, 0x3f317217, v55
	v_fma_f32 v61, v55, s36, -v61
	v_fmac_f32_e32 v61, 0x3377d1cf, v55
	v_fmac_f32_e32 v61, 0x3f317217, v55
	v_mov_b32_e32 v55, v61
	v_pk_add_f32 v[52:53], v[52:53], v[54:55] neg_lo:[0,1] neg_hi:[0,1]
	s_nop 0
	v_pk_mul_f32 v[64:65], v[52:53], s[50:51] op_sel_hi:[1,0]
	s_nop 0
	v_add_f32_e32 v52, v64, v60
	v_add_f32_e32 v52, v65, v52
	ds_bpermute_b32 v53, v91, v52
	s_waitcnt lgkmcnt(0)
	v_add_f32_e32 v52, v52, v53
	ds_bpermute_b32 v53, v116, v52
	s_and_saveexec_b64 s[0:1], s[40:41]
	s_cbranch_execz .LBB0_342
	s_waitcnt lgkmcnt(0)
	v_add_f32_e32 v52, v52, v53
	v_mul_f32_e32 v52, 0x3fb8aa3b, v52
	v_exp_f32_e32 v54, v52
	v_lshl_add_u64 v[52:53], v[32:33], 0, v[176:177]
	global_store_dword v[52:53], v54, off offset:16
; __device__ __forceinline__ f32x4 mfma16(bf16x8 a, bf16x8 b, f32x4 c) { return __builtin_amdgcn_mfma_f32_16x16x32_bf16(a, b, c, 0, 0, 0); }
; template <int MODE> __device__ void mixer_gla(const Params& p, int l, int n, LAS unsigned char* lds) {
;     ...
;             for (int ef = 0; ef < 4; ++ef) { tot[ef] = 0.f;
; #pragma unroll
;                 for (int ks = 0; ks < 2; ++ks) { f32x4 la2[2];
; #pragma unroll
;                     for (int t2 = 0; t2 < 2; ++t2) { const f32x4 z = mfma16(lrf[2 * ks + t2], gwf[ef], zero4);
; #pragma unroll
;                         for (int r = 0; r < 4; ++r) { const float zz = z[r] + bgv[ef]; const float la = (fminf(zz, 0.f) - __logf(1.0f + __expf(-fabsf(zz)))) * (1.0f / 16.0f); la2[t2][r] = la; tot[ef] += la; } }
;                     laop[ef][ks] = pack8(la2[0], la2[1]); __builtin_amdgcn_sched_barrier(0); } }
;     ...
;             for (int ef = 0; ef < 4; ++ef) { float tt = tot[ef]; tt += __shfl_xor(tt, 16); tt += __shfl_xor(tt, 32);
;                 if (vh == 0 && q == 0) dec[((size_t)(dir * NCH + n) * 4 + h) * 64 + SIGC(ef, c)] = __expf(tt); }
.LBB0_342:
	s_or_b64 exec, exec, s[0:1]
	v_add_f32_e32 v52, v77, v48
	v_min_f32_e32 v48, 0, v52
	v_mul_f32_e64 v52, |v52|, s33
	v_exp_f32_e32 v52, v52
	s_nop 0
	v_add_f32_e32 v52, 1.0, v52
	s_waitcnt lgkmcnt(0)
	s_nop 0
	v_log_f32_e32 v52, v52
	s_nop 0
	v_mul_f32_e32 v53, 0x3f317217, v52
	v_fma_f32 v53, v52, s36, -v53
	v_fmac_f32_e32 v53, 0x3377d1cf, v52
	v_fmac_f32_e32 v53, 0x3f317217, v52
	v_mov_b32_e32 v52, v53
	v_add_f32_e32 v53, v77, v49
	v_min_f32_e32 v49, 0, v53
	v_mul_f32_e64 v53, |v53|, s33
	v_exp_f32_e32 v53, v53
	s_nop 0
	v_add_f32_e32 v53, 1.0, v53
	v_log_f32_e32 v53, v53
	s_nop 0
	v_mul_f32_e32 v54, 0x3f317217, v53
	v_fma_f32 v54, v53, s36, -v54
	v_fmac_f32_e32 v54, 0x3377d1cf, v53
	v_fmac_f32_e32 v54, 0x3f317217, v53
	v_mov_b32_e32 v53, v54
	v_pk_add_f32 v[48:49], v[48:49], v[52:53] neg_lo:[0,1] neg_hi:[0,1]
	s_nop 0
	v_pk_mul_f32 v[48:49], v[48:49], s[50:51] op_sel_hi:[1,0]
	s_nop 0
	v_add_f32_e32 v52, 0, v48
	v_add_f32_e32 v54, v49, v52
	v_add_f32_e32 v52, v77, v50
	v_min_f32_e32 v50, 0, v52
	v_mul_f32_e64 v52, |v52|, s33
	v_exp_f32_e32 v52, v52
	s_nop 0
	v_add_f32_e32 v52, 1.0, v52
	v_log_f32_e32 v52, v52
	s_nop 0
	v_mul_f32_e32 v53, 0x3f317217, v52
	v_fma_f32 v53, v52, s36, -v53
	v_fmac_f32_e32 v53, 0x3377d1cf, v52
	v_fmac_f32_e32 v53, 0x3f317217, v52
	v_mov_b32_e32 v52, v53
	v_add_f32_e32 v53, v77, v51
	v_min_f32_e32 v51, 0, v53
	v_mul_f32_e64 v53, |v53|, s33
	v_exp_f32_e32 v53, v53
	s_nop 0
	v_add_f32_e32 v53, 1.0, v53
	v_log_f32_e32 v53, v53
	s_nop 0
	v_mul_f32_e32 v55, 0x3f317217, v53
	v_fma_f32 v55, v53, s36, -v55
	v_fmac_f32_e32 v55, 0x3377d1cf, v53
	v_fmac_f32_e32 v55, 0x3f317217, v53
	v_mov_b32_e32 v53, v55
	v_pk_add_f32 v[50:51], v[50:51], v[52:53] neg_lo:[0,1] neg_hi:[0,1]
	s_nop 0
	v_pk_mul_f32 v[50:51], v[50:51], s[50:51] op_sel_hi:[1,0]
	s_nop 0
	v_add_f32_e32 v52, v50, v54
	v_add_f32_e32 v54, v51, v52
	v_add_f32_e32 v52, v77, v40
	v_min_f32_e32 v40, 0, v52
	v_mul_f32_e64 v52, |v52|, s33
	v_exp_f32_e32 v52, v52
	s_nop 0
	v_add_f32_e32 v52, 1.0, v52
	v_log_f32_e32 v52, v52
	s_nop 0
	v_mul_f32_e32 v53, 0x3f317217, v52
	v_fma_f32 v53, v52, s36, -v53
	v_fmac_f32_e32 v53, 0x3377d1cf, v52
	v_fmac_f32_e32 v53, 0x3f317217, v52
	v_mov_b32_e32 v52, v53
	v_add_f32_e32 v53, v77, v41
	v_min_f32_e32 v41, 0, v53
	v_mul_f32_e64 v53, |v53|, s33
	v_exp_f32_e32 v53, v53
	s_nop 0
	v_add_f32_e32 v53, 1.0, v53
	v_log_f32_e32 v53, v53
	s_nop 0
	v_mul_f32_e32 v55, 0x3f317217, v53
	v_fma_f32 v55, v53, s36, -v55
	v_fmac_f32_e32 v55, 0x3377d1cf, v53
	v_fmac_f32_e32 v55, 0x3f317217, v53
	v_mov_b32_e32 v53, v55
	v_pk_add_f32 v[40:41], v[40:41], v[52:53] neg_lo:[0,1] neg_hi:[0,1]
	s_nop 0
	v_pk_mul_f32 v[40:41], v[40:41], s[50:51] op_sel_hi:[1,0]
	s_nop 0
	v_add_f32_e32 v52, v40, v54
	v_add_f32_e32 v54, v41, v52
	v_add_f32_e32 v52, v77, v42
	v_min_f32_e32 v42, 0, v52
	v_mul_f32_e64 v52, |v52|, s33
	v_exp_f32_e32 v52, v52
	s_nop 0
	v_add_f32_e32 v52, 1.0, v52
	v_log_f32_e32 v52, v52
	s_nop 0
	v_mul_f32_e32 v53, 0x3f317217, v52
	v_fma_f32 v53, v52, s36, -v53
	v_fmac_f32_e32 v53, 0x3377d1cf, v52
	v_fmac_f32_e32 v53, 0x3f317217, v52
	v_mov_b32_e32 v52, v53
	v_add_f32_e32 v53, v77, v43
	v_min_f32_e32 v43, 0, v53
	v_mul_f32_e64 v53, |v53|, s33
	v_exp_f32_e32 v53, v53
	s_nop 0
	v_add_f32_e32 v53, 1.0, v53
	v_log_f32_e32 v53, v53
	s_nop 0
	v_mul_f32_e32 v55, 0x3f317217, v53
	v_fma_f32 v55, v53, s36, -v55
	v_fmac_f32_e32 v55, 0x3377d1cf, v53
	v_fmac_f32_e32 v55, 0x3f317217, v53
	v_mov_b32_e32 v53, v55
	v_pk_add_f32 v[42:43], v[42:43], v[52:53] neg_lo:[0,1] neg_hi:[0,1]
	s_nop 0
	v_pk_mul_f32 v[42:43], v[42:43], s[50:51] op_sel_hi:[1,0]
	s_nop 0
	v_add_f32_e32 v52, v42, v54
	v_add_f32_e32 v54, v43, v52
	v_add_f32_e32 v52, v77, v28
	v_min_f32_e32 v28, 0, v52
	v_mul_f32_e64 v52, |v52|, s33
	v_exp_f32_e32 v52, v52
	s_nop 0
	v_add_f32_e32 v52, 1.0, v52
	v_log_f32_e32 v52, v52
	s_nop 0
	v_mul_f32_e32 v53, 0x3f317217, v52
	v_fma_f32 v53, v52, s36, -v53
	v_fmac_f32_e32 v53, 0x3377d1cf, v52
	v_fmac_f32_e32 v53, 0x3f317217, v52
	v_mov_b32_e32 v52, v53
	v_add_f32_e32 v53, v77, v29
	v_min_f32_e32 v29, 0, v53
	v_mul_f32_e64 v53, |v53|, s33
	v_exp_f32_e32 v53, v53
	s_nop 0
	v_add_f32_e32 v53, 1.0, v53
	v_log_f32_e32 v53, v53
	s_nop 0
	v_mul_f32_e32 v55, 0x3f317217, v53
	v_fma_f32 v55, v53, s36, -v55
	v_fmac_f32_e32 v55, 0x3377d1cf, v53
	v_fmac_f32_e32 v55, 0x3f317217, v53
	v_mov_b32_e32 v53, v55
	v_pk_add_f32 v[28:29], v[28:29], v[52:53] neg_lo:[0,1] neg_hi:[0,1]
	s_nop 0
	v_pk_mul_f32 v[28:29], v[28:29], s[50:51] op_sel_hi:[1,0]
	s_nop 0
	v_add_f32_e32 v52, v28, v54
	v_add_f32_e32 v54, v29, v52
	v_add_f32_e32 v52, v77, v30
	v_min_f32_e32 v30, 0, v52
	v_mul_f32_e64 v52, |v52|, s33
	v_exp_f32_e32 v52, v52
	s_nop 0
	v_add_f32_e32 v52, 1.0, v52
	v_log_f32_e32 v52, v52
	s_nop 0
	v_mul_f32_e32 v53, 0x3f317217, v52
	v_fma_f32 v53, v52, s36, -v53
	v_fmac_f32_e32 v53, 0x3377d1cf, v52
	v_fmac_f32_e32 v53, 0x3f317217, v52
	v_mov_b32_e32 v52, v53
	v_add_f32_e32 v53, v77, v31
	v_min_f32_e32 v31, 0, v53
	v_mul_f32_e64 v53, |v53|, s33
	v_exp_f32_e32 v53, v53
	s_nop 0
	v_add_f32_e32 v53, 1.0, v53
	v_log_f32_e32 v53, v53
	s_nop 0
	v_mul_f32_e32 v55, 0x3f317217, v53
	v_fma_f32 v55, v53, s36, -v55
	v_fmac_f32_e32 v55, 0x3377d1cf, v53
	v_fmac_f32_e32 v55, 0x3f317217, v53
	v_mov_b32_e32 v53, v55
	v_pk_add_f32 v[30:31], v[30:31], v[52:53] neg_lo:[0,1] neg_hi:[0,1]
	s_nop 0
	v_pk_mul_f32 v[30:31], v[30:31], s[50:51] op_sel_hi:[1,0]
	s_nop 0
	v_add_f32_e32 v52, v30, v54
	v_add_f32_e32 v54, v31, v52
	v_add_f32_e32 v52, v77, v24
	v_min_f32_e32 v24, 0, v52
	v_mul_f32_e64 v52, |v52|, s33
	v_exp_f32_e32 v52, v52
	s_nop 0
	v_add_f32_e32 v52, 1.0, v52
	v_log_f32_e32 v52, v52
	s_nop 0
; __device__ __forceinline__ f32x4 mfma16(bf16x8 a, bf16x8 b, f32x4 c) { return __builtin_amdgcn_mfma_f32_16x16x32_bf16(a, b, c, 0, 0, 0); }
; template <int MODE> __device__ void mixer_gla(const Params& p, int l, int n, LAS unsigned char* lds) {
;     ...
;             for (int ef = 0; ef < 4; ++ef) { tot[ef] = 0.f;
; #pragma unroll
;                 for (int ks = 0; ks < 2; ++ks) { f32x4 la2[2];
; #pragma unroll
;                     for (int t2 = 0; t2 < 2; ++t2) { const f32x4 z = mfma16(lrf[2 * ks + t2], gwf[ef], zero4);
; #pragma unroll
;                         for (int r = 0; r < 4; ++r) { const float zz = z[r] + bgv[ef]; const float la = (fminf(zz, 0.f) - __logf(1.0f + __expf(-fabsf(zz)))) * (1.0f / 16.0f); la2[t2][r] = la; tot[ef] += la; } }
;                     laop[ef][ks] = pack8(la2[0], la2[1]); __builtin_amdgcn_sched_barrier(0); } }
;     ...
;             for (int ef = 0; ef < 4; ++ef) { float tt = tot[ef]; tt += __shfl_xor(tt, 16); tt += __shfl_xor(tt, 32);
;                 if (vh == 0 && q == 0) dec[((size_t)(dir * NCH + n) * 4 + h) * 64 + SIGC(ef, c)] = __expf(tt); }
	v_mul_f32_e32 v53, 0x3f317217, v52
	v_fma_f32 v53, v52, s36, -v53
	v_fmac_f32_e32 v53, 0x3377d1cf, v52
	v_fmac_f32_e32 v53, 0x3f317217, v52
	v_mov_b32_e32 v52, v53
	v_add_f32_e32 v53, v77, v25
	v_min_f32_e32 v25, 0, v53
	v_mul_f32_e64 v53, |v53|, s33
	v_exp_f32_e32 v53, v53
	s_nop 0
	v_add_f32_e32 v53, 1.0, v53
	v_log_f32_e32 v53, v53
	s_nop 0
	v_mul_f32_e32 v55, 0x3f317217, v53
	v_fma_f32 v55, v53, s36, -v55
	v_fmac_f32_e32 v55, 0x3377d1cf, v53
	v_fmac_f32_e32 v55, 0x3f317217, v53
	v_mov_b32_e32 v53, v55
	v_pk_add_f32 v[24:25], v[24:25], v[52:53] neg_lo:[0,1] neg_hi:[0,1]
	s_nop 0
	v_pk_mul_f32 v[24:25], v[24:25], s[50:51] op_sel_hi:[1,0]
	s_nop 0
	v_add_f32_e32 v52, v24, v54
	v_add_f32_e32 v54, v25, v52
	v_add_f32_e32 v52, v77, v26
	v_min_f32_e32 v26, 0, v52
	v_mul_f32_e64 v52, |v52|, s33
	v_exp_f32_e32 v52, v52
	s_nop 0
	v_add_f32_e32 v52, 1.0, v52
	v_log_f32_e32 v52, v52
	s_nop 0
	v_mul_f32_e32 v53, 0x3f317217, v52
	v_fma_f32 v53, v52, s36, -v53
	v_fmac_f32_e32 v53, 0x3377d1cf, v52
	v_fmac_f32_e32 v53, 0x3f317217, v52
	v_mov_b32_e32 v52, v53
	v_add_f32_e32 v53, v77, v27
	v_min_f32_e32 v27, 0, v53
	v_mul_f32_e64 v53, |v53|, s33
	v_exp_f32_e32 v53, v53
	s_nop 0
	v_add_f32_e32 v53, 1.0, v53
	v_log_f32_e32 v53, v53
	s_nop 0
	v_mul_f32_e32 v55, 0x3f317217, v53
	v_fma_f32 v55, v53, s36, -v55
	v_fmac_f32_e32 v55, 0x3377d1cf, v53
	v_fmac_f32_e32 v55, 0x3f317217, v53
	v_mov_b32_e32 v53, v55
	v_pk_add_f32 v[26:27], v[26:27], v[52:53] neg_lo:[0,1] neg_hi:[0,1]
	s_nop 0
	v_pk_mul_f32 v[26:27], v[26:27], s[50:51] op_sel_hi:[1,0]
	s_nop 0
	v_add_f32_e32 v52, v26, v54
	v_add_f32_e32 v52, v27, v52
	ds_bpermute_b32 v53, v91, v52
	s_waitcnt lgkmcnt(0)
	v_add_f32_e32 v52, v52, v53
	ds_bpermute_b32 v53, v116, v52
	s_and_saveexec_b64 s[0:1], s[40:41]
	s_cbranch_execz .LBB0_344
	s_waitcnt lgkmcnt(0)
	v_add_f32_e32 v52, v52, v53
	v_mul_f32_e32 v52, 0x3fb8aa3b, v52
	v_exp_f32_e32 v54, v52
	v_lshl_add_u64 v[52:53], v[32:33], 0, v[176:177]
	global_store_dword v[52:53], v54, off offset:128
.LBB0_344:
	s_or_b64 exec, exec, s[0:1]
	s_waitcnt vmcnt(0)
	v_add_f32_e32 v52, v76, v20
	v_min_f32_e32 v20, 0, v52
	v_mul_f32_e64 v52, |v52|, s33
	v_exp_f32_e32 v52, v52
	s_nop 0
	v_add_f32_e32 v52, 1.0, v52
	s_waitcnt lgkmcnt(0)
	s_nop 0
	v_log_f32_e32 v52, v52
	s_nop 0
	v_mul_f32_e32 v53, 0x3f317217, v52
	v_fma_f32 v53, v52, s36, -v53
	v_fmac_f32_e32 v53, 0x3377d1cf, v52
	v_fmac_f32_e32 v53, 0x3f317217, v52
	v_mov_b32_e32 v52, v53
	v_add_f32_e32 v53, v76, v21
	v_min_f32_e32 v21, 0, v53
	v_mul_f32_e64 v53, |v53|, s33
	v_exp_f32_e32 v53, v53
	s_nop 0
	v_add_f32_e32 v53, 1.0, v53
	v_log_f32_e32 v53, v53
	s_nop 0
	v_mul_f32_e32 v54, 0x3f317217, v53
	v_fma_f32 v54, v53, s36, -v54
	v_fmac_f32_e32 v54, 0x3377d1cf, v53
	v_fmac_f32_e32 v54, 0x3f317217, v53
	v_mov_b32_e32 v53, v54
	v_pk_add_f32 v[20:21], v[20:21], v[52:53] neg_lo:[0,1] neg_hi:[0,1]
	s_nop 0
	v_pk_mul_f32 v[20:21], v[20:21], s[50:51] op_sel_hi:[1,0]
	s_nop 0
	v_add_f32_e32 v52, 0, v20
	v_add_f32_e32 v54, v21, v52
	v_add_f32_e32 v52, v76, v22
	v_min_f32_e32 v22, 0, v52
	v_mul_f32_e64 v52, |v52|, s33
	v_exp_f32_e32 v52, v52
	s_nop 0
	v_add_f32_e32 v52, 1.0, v52
	v_log_f32_e32 v52, v52
	s_nop 0
	v_mul_f32_e32 v53, 0x3f317217, v52
	v_fma_f32 v53, v52, s36, -v53
	v_fmac_f32_e32 v53, 0x3377d1cf, v52
	v_fmac_f32_e32 v53, 0x3f317217, v52
	v_mov_b32_e32 v52, v53
	v_add_f32_e32 v53, v76, v23
	v_min_f32_e32 v23, 0, v53
	v_mul_f32_e64 v53, |v53|, s33
	v_exp_f32_e32 v53, v53
	s_nop 0
	v_add_f32_e32 v53, 1.0, v53
	v_log_f32_e32 v53, v53
	s_nop 0
	v_mul_f32_e32 v55, 0x3f317217, v53
	v_fma_f32 v55, v53, s36, -v55
	v_fmac_f32_e32 v55, 0x3377d1cf, v53
	v_fmac_f32_e32 v55, 0x3f317217, v53
	v_mov_b32_e32 v53, v55
	v_pk_add_f32 v[22:23], v[22:23], v[52:53] neg_lo:[0,1] neg_hi:[0,1]
	s_nop 0
	v_pk_mul_f32 v[22:23], v[22:23], s[50:51] op_sel_hi:[1,0]
	s_nop 0
	v_add_f32_e32 v52, v22, v54
	v_add_f32_e32 v54, v23, v52
	v_add_f32_e32 v52, v76, v16
	v_min_f32_e32 v16, 0, v52
	v_mul_f32_e64 v52, |v52|, s33
	v_exp_f32_e32 v52, v52
	s_nop 0
	v_add_f32_e32 v52, 1.0, v52
	v_log_f32_e32 v52, v52
	s_nop 0
	v_mul_f32_e32 v53, 0x3f317217, v52
	v_fma_f32 v53, v52, s36, -v53
	v_fmac_f32_e32 v53, 0x3377d1cf, v52
	v_fmac_f32_e32 v53, 0x3f317217, v52
	v_mov_b32_e32 v52, v53
	v_add_f32_e32 v53, v76, v17
	v_min_f32_e32 v17, 0, v53
	v_mul_f32_e64 v53, |v53|, s33
	v_exp_f32_e32 v53, v53
	s_nop 0
	v_add_f32_e32 v53, 1.0, v53
	v_log_f32_e32 v53, v53
	s_nop 0
	v_mul_f32_e32 v55, 0x3f317217, v53
	v_fma_f32 v55, v53, s36, -v55
	v_fmac_f32_e32 v55, 0x3377d1cf, v53
	v_fmac_f32_e32 v55, 0x3f317217, v53
	v_mov_b32_e32 v53, v55
	v_pk_add_f32 v[16:17], v[16:17], v[52:53] neg_lo:[0,1] neg_hi:[0,1]
	s_nop 0
	v_pk_mul_f32 v[16:17], v[16:17], s[50:51] op_sel_hi:[1,0]
	s_nop 0
	v_add_f32_e32 v52, v16, v54
	v_add_f32_e32 v54, v17, v52
	v_add_f32_e32 v52, v76, v18
	v_min_f32_e32 v18, 0, v52
; __device__ __forceinline__ f32x4 mfma16(bf16x8 a, bf16x8 b, f32x4 c) { return __builtin_amdgcn_mfma_f32_16x16x32_bf16(a, b, c, 0, 0, 0); }
; template <int MODE> __device__ void mixer_gla(const Params& p, int l, int n, LAS unsigned char* lds) {
;     ...
;             for (int ef = 0; ef < 4; ++ef) { tot[ef] = 0.f;
; #pragma unroll
;                 for (int ks = 0; ks < 2; ++ks) { f32x4 la2[2];
; #pragma unroll
;                     for (int t2 = 0; t2 < 2; ++t2) { const f32x4 z = mfma16(lrf[2 * ks + t2], gwf[ef], zero4);
; #pragma unroll
;                         for (int r = 0; r < 4; ++r) { const float zz = z[r] + bgv[ef]; const float la = (fminf(zz, 0.f) - __logf(1.0f + __expf(-fabsf(zz)))) * (1.0f / 16.0f); la2[t2][r] = la; tot[ef] += la; } }
;                     laop[ef][ks] = pack8(la2[0], la2[1]); __builtin_amdgcn_sched_barrier(0); } }
;     ...
;             for (int ef = 0; ef < 4; ++ef) { float tt = tot[ef]; tt += __shfl_xor(tt, 16); tt += __shfl_xor(tt, 32);
;                 if (vh == 0 && q == 0) dec[((size_t)(dir * NCH + n) * 4 + h) * 64 + SIGC(ef, c)] = __expf(tt); }
	v_mul_f32_e64 v52, |v52|, s33
	v_exp_f32_e32 v52, v52
	s_nop 0
	v_add_f32_e32 v52, 1.0, v52
	v_log_f32_e32 v52, v52
	s_nop 0
	v_mul_f32_e32 v53, 0x3f317217, v52
	v_fma_f32 v53, v52, s36, -v53
	v_fmac_f32_e32 v53, 0x3377d1cf, v52
	v_fmac_f32_e32 v53, 0x3f317217, v52
	v_mov_b32_e32 v52, v53
	v_add_f32_e32 v53, v76, v19
	v_min_f32_e32 v19, 0, v53
	v_mul_f32_e64 v53, |v53|, s33
	v_exp_f32_e32 v53, v53
	s_nop 0
	v_add_f32_e32 v53, 1.0, v53
	v_log_f32_e32 v53, v53
	s_nop 0
	v_mul_f32_e32 v55, 0x3f317217, v53
	v_fma_f32 v55, v53, s36, -v55
	v_fmac_f32_e32 v55, 0x3377d1cf, v53
	v_fmac_f32_e32 v55, 0x3f317217, v53
	v_mov_b32_e32 v53, v55
	v_pk_add_f32 v[18:19], v[18:19], v[52:53] neg_lo:[0,1] neg_hi:[0,1]
	s_nop 0
	v_pk_mul_f32 v[18:19], v[18:19], s[50:51] op_sel_hi:[1,0]
	s_nop 0
	v_add_f32_e32 v52, v18, v54
	v_add_f32_e32 v54, v19, v52
	v_add_f32_e32 v52, v76, v12
	v_min_f32_e32 v12, 0, v52
	v_mul_f32_e64 v52, |v52|, s33
	v_exp_f32_e32 v52, v52
	s_nop 0
	v_add_f32_e32 v52, 1.0, v52
	v_log_f32_e32 v52, v52
	s_nop 0
	v_mul_f32_e32 v53, 0x3f317217, v52
	v_fma_f32 v53, v52, s36, -v53
	v_fmac_f32_e32 v53, 0x3377d1cf, v52
	v_fmac_f32_e32 v53, 0x3f317217, v52
	v_mov_b32_e32 v52, v53
	v_add_f32_e32 v53, v76, v13
	v_min_f32_e32 v13, 0, v53
	v_mul_f32_e64 v53, |v53|, s33
	v_exp_f32_e32 v53, v53
	s_nop 0
	v_add_f32_e32 v53, 1.0, v53
	v_log_f32_e32 v53, v53
	s_nop 0
	v_mul_f32_e32 v55, 0x3f317217, v53
	v_fma_f32 v55, v53, s36, -v55
	v_fmac_f32_e32 v55, 0x3377d1cf, v53
	v_fmac_f32_e32 v55, 0x3f317217, v53
	v_mov_b32_e32 v53, v55
	v_pk_add_f32 v[12:13], v[12:13], v[52:53] neg_lo:[0,1] neg_hi:[0,1]
	s_nop 0
	v_pk_mul_f32 v[12:13], v[12:13], s[50:51] op_sel_hi:[1,0]
	s_nop 0
	v_add_f32_e32 v52, v12, v54
	v_add_f32_e32 v54, v13, v52
	v_add_f32_e32 v52, v76, v14
	v_min_f32_e32 v14, 0, v52
	v_mul_f32_e64 v52, |v52|, s33
	v_exp_f32_e32 v52, v52
	s_nop 0
	v_add_f32_e32 v52, 1.0, v52
	v_log_f32_e32 v52, v52
	s_nop 0
	v_mul_f32_e32 v53, 0x3f317217, v52
	v_fma_f32 v53, v52, s36, -v53
	v_fmac_f32_e32 v53, 0x3377d1cf, v52
	v_fmac_f32_e32 v53, 0x3f317217, v52
	v_mov_b32_e32 v52, v53
	v_add_f32_e32 v53, v76, v15
	v_min_f32_e32 v15, 0, v53
	v_mul_f32_e64 v53, |v53|, s33
	v_exp_f32_e32 v53, v53
	s_nop 0
	v_add_f32_e32 v53, 1.0, v53
	v_log_f32_e32 v53, v53
	s_nop 0
	v_mul_f32_e32 v55, 0x3f317217, v53
	v_fma_f32 v55, v53, s36, -v55
	v_fmac_f32_e32 v55, 0x3377d1cf, v53
	v_fmac_f32_e32 v55, 0x3f317217, v53
	v_mov_b32_e32 v53, v55
	v_pk_add_f32 v[14:15], v[14:15], v[52:53] neg_lo:[0,1] neg_hi:[0,1]
	s_nop 0
	v_pk_mul_f32 v[14:15], v[14:15], s[50:51] op_sel_hi:[1,0]
	s_nop 0
	v_add_f32_e32 v52, v14, v54
	v_add_f32_e32 v54, v15, v52
	v_add_f32_e32 v52, v76, v8
	v_min_f32_e32 v8, 0, v52
	v_mul_f32_e64 v52, |v52|, s33
	v_exp_f32_e32 v52, v52
	s_nop 0
	v_add_f32_e32 v52, 1.0, v52
	v_log_f32_e32 v52, v52
	s_nop 0
	v_mul_f32_e32 v53, 0x3f317217, v52
	v_fma_f32 v53, v52, s36, -v53
	v_fmac_f32_e32 v53, 0x3377d1cf, v52
	v_fmac_f32_e32 v53, 0x3f317217, v52
	v_mov_b32_e32 v52, v53
	v_add_f32_e32 v53, v76, v9
	v_min_f32_e32 v9, 0, v53
	v_mul_f32_e64 v53, |v53|, s33
	v_exp_f32_e32 v53, v53
	s_nop 0
	v_add_f32_e32 v53, 1.0, v53
	v_log_f32_e32 v53, v53
	s_nop 0
	v_mul_f32_e32 v55, 0x3f317217, v53
	v_fma_f32 v55, v53, s36, -v55
	v_fmac_f32_e32 v55, 0x3377d1cf, v53
	v_fmac_f32_e32 v55, 0x3f317217, v53
	v_mov_b32_e32 v53, v55
	v_pk_add_f32 v[8:9], v[8:9], v[52:53] neg_lo:[0,1] neg_hi:[0,1]
	s_nop 0
	v_pk_mul_f32 v[8:9], v[8:9], s[50:51] op_sel_hi:[1,0]
	s_nop 0
	v_add_f32_e32 v52, v8, v54
	v_add_f32_e32 v54, v9, v52
	v_add_f32_e32 v52, v76, v10
	v_min_f32_e32 v10, 0, v52
	v_mul_f32_e64 v52, |v52|, s33
	v_exp_f32_e32 v52, v52
	s_nop 0
	v_add_f32_e32 v52, 1.0, v52
	v_log_f32_e32 v52, v52
	s_nop 0
	v_mul_f32_e32 v53, 0x3f317217, v52
	v_fma_f32 v53, v52, s36, -v53
	v_fmac_f32_e32 v53, 0x3377d1cf, v52
	v_fmac_f32_e32 v53, 0x3f317217, v52
	v_mov_b32_e32 v52, v53
	v_add_f32_e32 v53, v76, v11
	v_min_f32_e32 v11, 0, v53
	v_mul_f32_e64 v53, |v53|, s33
	v_exp_f32_e32 v53, v53
	s_nop 0
	v_add_f32_e32 v53, 1.0, v53
	v_log_f32_e32 v53, v53
	s_nop 0
	v_mul_f32_e32 v55, 0x3f317217, v53
	v_fma_f32 v55, v53, s36, -v55
	v_fmac_f32_e32 v55, 0x3377d1cf, v53
	v_fmac_f32_e32 v55, 0x3f317217, v53
	v_mov_b32_e32 v53, v55
	v_pk_add_f32 v[10:11], v[10:11], v[52:53] neg_lo:[0,1] neg_hi:[0,1]
	s_nop 0
	v_pk_mul_f32 v[10:11], v[10:11], s[50:51] op_sel_hi:[1,0]
	s_nop 0
	v_add_f32_e32 v52, v10, v54
	v_add_f32_e32 v52, v11, v52
	ds_bpermute_b32 v53, v91, v52
	s_waitcnt lgkmcnt(0)
	v_add_f32_e32 v52, v52, v53
	ds_bpermute_b32 v53, v116, v52
	s_and_saveexec_b64 s[0:1], s[40:41]
	s_cbranch_execz .LBB0_329
	s_waitcnt lgkmcnt(0)
	v_add_f32_e32 v52, v52, v53
	v_mul_f32_e32 v52, 0x3fb8aa3b, v52
	v_exp_f32_e32 v52, v52
	v_lshl_add_u64 v[32:33], v[32:33], 0, v[176:177]
	global_store_dword v[32:33], v52, off offset:144
	s_branch .LBB0_329
